# conv prologue loads de-serialized + epilogue SS row loads hoisted (one wait instead of 8) on top of rcp sigmoid
# speedup vs baseline: 1.0419x; 1.0099x over previous
; DI unsigned pk2(float lo, float hi) { f32x2_t v = {lo, hi}; bf16x2_t b = __builtin_convertvector(v, bf16x2_t); return __builtin_bit_cast(unsigned, b); }
; DI int rot_t(int c, int t) { return (t + 128 * c) & (MTOK - 1); }
;     DI void operator()(AccRef acc, const Unit& u, int wr, int wc, int fr, int fq) const {
;     ...
;                 const int row = row0 + ai * HALF + m * 16;
;                 float rs = rsqrtf(SS0[row] * (1.0f / DM) + EPSN); if (pn < 2) rs *= 0.125f;
; #pragma unroll
;                 for (int bj = 0; bj < 2; ++bj) {
;                     const f32x4 v0 = acc[ai][bj][m][0] * rs, v1 = acc[ai][bj][m][1] * rs;
;                     u32x4 w; w.x = pk2(v0[0], v0[1]); w.y = pk2(v0[2], v0[3]); w.z = pk2(v1[0], v1[1]); w.w = pk2(v1[2], v1[3]);
;                     const int ct = bj * HALF + cb;
;                     if (pn < 2)      *(u32x4*)(Q + (size_t)row * 512 + pn * 256 + ct) = w;
;                     else if (pn < 4) *(u32x4*)(K + (size_t)row * 512 + (pn - 2) * 256 + ct) = w;
;                     else if (pn < 6) { const int vc = (pn - 4) * 256 + ct; const unsigned wv[4] = {w.x, w.y, w.z, w.w};
; _Pragma("unroll")
;                         for (int e = 0; e < 8; ++e) VT[(size_t)(vc + e) * MTOK + rot_t(vc + e, row)] = (bf16)((e & 1) ? (wv[e >> 1] >> 16) : (wv[e >> 1] & 0xffffu)); }
;                     else             *(u32x4*)(HY + (size_t)row * 1536 + (pn - 6) * 256 + ct) = w;
.LBB0_430:
	v_lshl_add_u32 v152, s6, 8, v139
	v_ashrrev_i32_e32 v153, 31, v152
	v_lshl_add_u64 v[154:155], v[152:153], 2, s[82:83]
	global_load_dword v136, v[154:155], off
	global_load_dword v248, v[154:155], off offset:64
	global_load_dword v249, v[154:155], off offset:128
	global_load_dword v250, v[154:155], off offset:192
	global_load_dword v251, v[154:155], off offset:512
	global_load_dword v252, v[154:155], off offset:576
	global_load_dword v253, v[154:155], off offset:640
	global_load_dword v254, v[154:155], off offset:704
	s_cmp_lt_i32 s4, 2
	v_mad_i64_i32 v[158:159], s[8:9], v152, s87, 0
	s_cselect_b64 s[8:9], -1, 0
	s_cmp_gt_i32 s4, 1
	s_cselect_b64 s[42:43], -1, 0
	s_cmp_gt_u32 s4, 3
	s_cselect_b64 s[44:45], -1, 0
	s_cmp_gt_u32 s4, 5
	s_cselect_b64 s[36:37], -1, 0
	s_lshl_b32 s28, s4, 8
	s_mov_b32 s29, s13
	s_mov_b64 s[6:7], -1
	s_add_i32 s12, s28, 0xfffffa00
	s_add_i32 s21, s28, 0xfffffc00
	s_waitcnt vmcnt(0)
	v_fmamk_f32 v136, v136, 0x3a800000, v165
	v_mul_f32_e32 v156, 0x4b800000, v136
	v_cmp_gt_f32_e32 vcc, s85, v136
	s_nop 1
	v_cndmask_b32_e32 v136, v136, v156, vcc
	v_rsq_f32_e32 v136, v136
	v_lshlrev_b64 v[156:157], 10, v[152:153]
	v_mul_f32_e32 v153, 0x45800000, v136
	v_cndmask_b32_e32 v136, v136, v153, vcc
	v_mul_f32_e32 v153, 0x3e000000, v136
	v_cndmask_b32_e64 v160, v136, v153, s[8:9]
	v_pk_mul_f32 v[126:127], v[126:127], v[160:161] op_sel_hi:[1,0]
	v_pk_mul_f32 v[124:125], v[124:125], v[160:161] op_sel_hi:[1,0]
	v_pk_mul_f32 v[166:167], v[122:123], v[160:161] op_sel_hi:[1,0]
	v_pk_mul_f32 v[122:123], v[120:121], v[160:161] op_sel_hi:[1,0]
	v_cvt_pk_bf16_f32 v120, v124, v125
	v_cvt_pk_bf16_f32 v121, v126, v127
	v_cvt_pk_bf16_f32 v122, v122, v123
	v_cvt_pk_bf16_f32 v123, v166, v167
	s_and_b64 vcc, exec, s[42:43]
	s_cbranch_vccz .LBB0_440
	s_mov_b64 s[4:5], -1
	s_and_b64 vcc, exec, s[44:45]
	s_cbranch_vccz .LBB0_437
	s_and_b64 vcc, exec, s[36:37]
	s_cbranch_vccz .LBB0_434
	v_lshl_add_u64 v[124:125], s[80:81], 0, v[158:159]
	v_lshl_add_u64 v[124:125], s[12:13], 1, v[124:125]
	v_lshlrev_b32_e32 v136, 1, v138
	v_lshl_add_u64 v[124:125], v[124:125], 0, v[136:137]
	global_store_dwordx4 v[124:125], v[120:123], off
	s_mov_b64 s[4:5], 0

; DI unsigned pk2(float lo, float hi) { f32x2_t v = {lo, hi}; bf16x2_t b = __builtin_convertvector(v, bf16x2_t); return __builtin_bit_cast(unsigned, b); }
; DI int rot_t(int c, int t) { return (t + 128 * c) & (MTOK - 1); }
;     DI void operator()(AccRef acc, const Unit& u, int wr, int wc, int fr, int fq) const {
;     ...
;                 const int row = row0 + ai * HALF + m * 16;
;                 float rs = rsqrtf(SS0[row] * (1.0f / DM) + EPSN); if (pn < 2) rs *= 0.125f;
; #pragma unroll
;                 for (int bj = 0; bj < 2; ++bj) {
;                     const f32x4 v0 = acc[ai][bj][m][0] * rs, v1 = acc[ai][bj][m][1] * rs;
;                     u32x4 w; w.x = pk2(v0[0], v0[1]); w.y = pk2(v0[2], v0[3]); w.z = pk2(v1[0], v1[1]); w.w = pk2(v1[2], v1[3]);
;                     const int ct = bj * HALF + cb;
;                     if (pn < 2)      *(u32x4*)(Q + (size_t)row * 512 + pn * 256 + ct) = w;
;                     else if (pn < 4) *(u32x4*)(K + (size_t)row * 512 + (pn - 2) * 256 + ct) = w;
;                     else if (pn < 6) { const int vc = (pn - 4) * 256 + ct; const unsigned wv[4] = {w.x, w.y, w.z, w.w};
; _Pragma("unroll")
;                         for (int e = 0; e < 8; ++e) VT[(size_t)(vc + e) * MTOK + rot_t(vc + e, row)] = (bf16)((e & 1) ? (wv[e >> 1] >> 16) : (wv[e >> 1] & 0xffffu)); }
;                     else             *(u32x4*)(HY + (size_t)row * 1536 + (pn - 6) * 256 + ct) = w;
.LBB0_454:
	s_nop 0
	s_nop 0
	v_or_b32_e32 v112, 16, v152
	v_ashrrev_i32_e32 v113, 31, v112
	v_mad_i64_i32 v[116:117], s[42:43], v112, s87, 0
	s_mov_b64 s[42:43], -1
	s_nop 0
	v_fmamk_f32 v114, v248, 0x3a800000, v165
	v_cmp_gt_f32_e32 vcc, s85, v114
	v_mul_f32_e32 v115, 0x4b800000, v114
	s_nop 0
	v_cndmask_b32_e32 v114, v114, v115, vcc
	v_rsq_f32_e32 v114, v114
	s_nop 0
	v_mul_f32_e32 v115, 0x45800000, v114
	v_cndmask_b32_e32 v114, v114, v115, vcc
	v_mul_f32_e32 v115, 0x3e000000, v114
	v_cndmask_b32_e64 v118, v114, v115, s[8:9]
	v_pk_mul_f32 v[110:111], v[110:111], v[118:119] op_sel_hi:[1,0]
	v_pk_mul_f32 v[108:109], v[108:109], v[118:119] op_sel_hi:[1,0]
	v_pk_mul_f32 v[120:121], v[106:107], v[118:119] op_sel_hi:[1,0]
	v_pk_mul_f32 v[106:107], v[104:105], v[118:119] op_sel_hi:[1,0]
	v_lshlrev_b64 v[114:115], 10, v[112:113]
	v_cvt_pk_bf16_f32 v104, v108, v109
	v_cvt_pk_bf16_f32 v105, v110, v111
	v_cvt_pk_bf16_f32 v106, v106, v107
	v_cvt_pk_bf16_f32 v107, v120, v121
	s_and_b64 vcc, exec, s[6:7]
	s_cbranch_vccnz .LBB0_464
	s_and_b64 vcc, exec, s[4:5]
	s_cbranch_vccnz .LBB0_461
	s_andn2_b64 vcc, exec, s[36:37]
	s_cbranch_vccnz .LBB0_458
	v_lshl_add_u64 v[108:109], s[80:81], 0, v[116:117]
	v_lshl_add_u64 v[108:109], s[12:13], 1, v[108:109]
	v_lshl_add_u64 v[108:109], v[108:109], 0, v[136:137]
	s_mov_b64 s[42:43], 0
	global_store_dwordx4 v[108:109], v[104:107], off

; DI unsigned pk2(float lo, float hi) { f32x2_t v = {lo, hi}; bf16x2_t b = __builtin_convertvector(v, bf16x2_t); return __builtin_bit_cast(unsigned, b); }
; DI int rot_t(int c, int t) { return (t + 128 * c) & (MTOK - 1); }
;     DI void operator()(AccRef acc, const Unit& u, int wr, int wc, int fr, int fq) const {
;     ...
;                 const int row = row0 + ai * HALF + m * 16;
;                 float rs = rsqrtf(SS0[row] * (1.0f / DM) + EPSN); if (pn < 2) rs *= 0.125f;
; #pragma unroll
;                 for (int bj = 0; bj < 2; ++bj) {
;                     const f32x4 v0 = acc[ai][bj][m][0] * rs, v1 = acc[ai][bj][m][1] * rs;
;                     u32x4 w; w.x = pk2(v0[0], v0[1]); w.y = pk2(v0[2], v0[3]); w.z = pk2(v1[0], v1[1]); w.w = pk2(v1[2], v1[3]);
;                     const int ct = bj * HALF + cb;
;                     if (pn < 2)      *(u32x4*)(Q + (size_t)row * 512 + pn * 256 + ct) = w;
;                     else if (pn < 4) *(u32x4*)(K + (size_t)row * 512 + (pn - 2) * 256 + ct) = w;
;                     else if (pn < 6) { const int vc = (pn - 4) * 256 + ct; const unsigned wv[4] = {w.x, w.y, w.z, w.w};
; _Pragma("unroll")
;                         for (int e = 0; e < 8; ++e) VT[(size_t)(vc + e) * MTOK + rot_t(vc + e, row)] = (bf16)((e & 1) ? (wv[e >> 1] >> 16) : (wv[e >> 1] & 0xffffu)); }
;                     else             *(u32x4*)(HY + (size_t)row * 1536 + (pn - 6) * 256 + ct) = w;
.LBB0_478:
	s_nop 0
	s_nop 0
	v_or_b32_e32 v96, 32, v152
	v_ashrrev_i32_e32 v97, 31, v96
	v_mad_i64_i32 v[100:101], s[42:43], v96, s87, 0
	s_mov_b64 s[42:43], -1
	s_nop 0
	v_fmamk_f32 v98, v249, 0x3a800000, v165
	v_cmp_gt_f32_e32 vcc, s85, v98
	v_mul_f32_e32 v99, 0x4b800000, v98
	s_nop 0
	v_cndmask_b32_e32 v98, v98, v99, vcc
	v_rsq_f32_e32 v98, v98
	s_nop 0
	v_mul_f32_e32 v99, 0x45800000, v98
	v_cndmask_b32_e32 v98, v98, v99, vcc
	v_mul_f32_e32 v99, 0x3e000000, v98
	v_cndmask_b32_e64 v102, v98, v99, s[8:9]
	v_pk_mul_f32 v[94:95], v[94:95], v[102:103] op_sel_hi:[1,0]
	v_pk_mul_f32 v[92:93], v[92:93], v[102:103] op_sel_hi:[1,0]
	v_pk_mul_f32 v[104:105], v[90:91], v[102:103] op_sel_hi:[1,0]
	v_pk_mul_f32 v[90:91], v[88:89], v[102:103] op_sel_hi:[1,0]
	v_lshlrev_b64 v[98:99], 10, v[96:97]
	v_cvt_pk_bf16_f32 v88, v92, v93
	v_cvt_pk_bf16_f32 v89, v94, v95
	v_cvt_pk_bf16_f32 v90, v90, v91
	v_cvt_pk_bf16_f32 v91, v104, v105
	s_and_b64 vcc, exec, s[6:7]
	s_cbranch_vccnz .LBB0_488
	s_and_b64 vcc, exec, s[4:5]
	s_cbranch_vccnz .LBB0_485
	s_andn2_b64 vcc, exec, s[36:37]
	s_cbranch_vccnz .LBB0_482
	v_lshl_add_u64 v[92:93], s[80:81], 0, v[100:101]
	v_lshl_add_u64 v[92:93], s[12:13], 1, v[92:93]
	v_lshl_add_u64 v[92:93], v[92:93], 0, v[136:137]
	s_mov_b64 s[42:43], 0
	global_store_dwordx4 v[92:93], v[88:91], off

; DI unsigned pk2(float lo, float hi) { f32x2_t v = {lo, hi}; bf16x2_t b = __builtin_convertvector(v, bf16x2_t); return __builtin_bit_cast(unsigned, b); }
; DI int rot_t(int c, int t) { return (t + 128 * c) & (MTOK - 1); }
;     DI void operator()(AccRef acc, const Unit& u, int wr, int wc, int fr, int fq) const {
;     ...
;                 const int row = row0 + ai * HALF + m * 16;
;                 float rs = rsqrtf(SS0[row] * (1.0f / DM) + EPSN); if (pn < 2) rs *= 0.125f;
; #pragma unroll
;                 for (int bj = 0; bj < 2; ++bj) {
;                     const f32x4 v0 = acc[ai][bj][m][0] * rs, v1 = acc[ai][bj][m][1] * rs;
;                     u32x4 w; w.x = pk2(v0[0], v0[1]); w.y = pk2(v0[2], v0[3]); w.z = pk2(v1[0], v1[1]); w.w = pk2(v1[2], v1[3]);
;                     const int ct = bj * HALF + cb;
;                     if (pn < 2)      *(u32x4*)(Q + (size_t)row * 512 + pn * 256 + ct) = w;
;                     else if (pn < 4) *(u32x4*)(K + (size_t)row * 512 + (pn - 2) * 256 + ct) = w;
;                     else if (pn < 6) { const int vc = (pn - 4) * 256 + ct; const unsigned wv[4] = {w.x, w.y, w.z, w.w};
; _Pragma("unroll")
;                         for (int e = 0; e < 8; ++e) VT[(size_t)(vc + e) * MTOK + rot_t(vc + e, row)] = (bf16)((e & 1) ? (wv[e >> 1] >> 16) : (wv[e >> 1] & 0xffffu)); }
;                     else             *(u32x4*)(HY + (size_t)row * 1536 + (pn - 6) * 256 + ct) = w;
.LBB0_502:
	s_nop 0
	s_nop 0
	v_or_b32_e32 v80, 48, v152
	v_ashrrev_i32_e32 v81, 31, v80
	v_mad_i64_i32 v[84:85], s[42:43], v80, s87, 0
	s_mov_b64 s[42:43], -1
	s_nop 0
	v_fmamk_f32 v82, v250, 0x3a800000, v165
	v_cmp_gt_f32_e32 vcc, s85, v82
	v_mul_f32_e32 v83, 0x4b800000, v82
	s_nop 0
	v_cndmask_b32_e32 v82, v82, v83, vcc
	v_rsq_f32_e32 v82, v82
	s_nop 0
	v_mul_f32_e32 v83, 0x45800000, v82
	v_cndmask_b32_e32 v82, v82, v83, vcc
	v_mul_f32_e32 v83, 0x3e000000, v82
	v_cndmask_b32_e64 v86, v82, v83, s[8:9]
	v_pk_mul_f32 v[78:79], v[78:79], v[86:87] op_sel_hi:[1,0]
	v_pk_mul_f32 v[76:77], v[76:77], v[86:87] op_sel_hi:[1,0]
	v_pk_mul_f32 v[88:89], v[74:75], v[86:87] op_sel_hi:[1,0]
	v_pk_mul_f32 v[74:75], v[72:73], v[86:87] op_sel_hi:[1,0]
	v_lshlrev_b64 v[82:83], 10, v[80:81]
	v_cvt_pk_bf16_f32 v72, v76, v77
	v_cvt_pk_bf16_f32 v73, v78, v79
	v_cvt_pk_bf16_f32 v74, v74, v75
	v_cvt_pk_bf16_f32 v75, v88, v89
	s_and_b64 vcc, exec, s[6:7]
	s_cbranch_vccnz .LBB0_512
	s_and_b64 vcc, exec, s[4:5]
	s_cbranch_vccnz .LBB0_509
	s_andn2_b64 vcc, exec, s[36:37]
	s_cbranch_vccnz .LBB0_506
	v_lshl_add_u64 v[76:77], s[80:81], 0, v[84:85]
	v_lshl_add_u64 v[76:77], s[12:13], 1, v[76:77]
	v_lshl_add_u64 v[76:77], v[76:77], 0, v[136:137]
	s_mov_b64 s[42:43], 0
	global_store_dwordx4 v[76:77], v[72:75], off

; DI unsigned pk2(float lo, float hi) { f32x2_t v = {lo, hi}; bf16x2_t b = __builtin_convertvector(v, bf16x2_t); return __builtin_bit_cast(unsigned, b); }
; DI int rot_t(int c, int t) { return (t + 128 * c) & (MTOK - 1); }
;     DI void operator()(AccRef acc, const Unit& u, int wr, int wc, int fr, int fq) const {
;     ...
;                 const int row = row0 + ai * HALF + m * 16;
;                 float rs = rsqrtf(SS0[row] * (1.0f / DM) + EPSN); if (pn < 2) rs *= 0.125f;
; #pragma unroll
;                 for (int bj = 0; bj < 2; ++bj) {
;                     const f32x4 v0 = acc[ai][bj][m][0] * rs, v1 = acc[ai][bj][m][1] * rs;
;                     u32x4 w; w.x = pk2(v0[0], v0[1]); w.y = pk2(v0[2], v0[3]); w.z = pk2(v1[0], v1[1]); w.w = pk2(v1[2], v1[3]);
;                     const int ct = bj * HALF + cb;
;                     if (pn < 2)      *(u32x4*)(Q + (size_t)row * 512 + pn * 256 + ct) = w;
;                     else if (pn < 4) *(u32x4*)(K + (size_t)row * 512 + (pn - 2) * 256 + ct) = w;
;                     else if (pn < 6) { const int vc = (pn - 4) * 256 + ct; const unsigned wv[4] = {w.x, w.y, w.z, w.w};
; _Pragma("unroll")
;                         for (int e = 0; e < 8; ++e) VT[(size_t)(vc + e) * MTOK + rot_t(vc + e, row)] = (bf16)((e & 1) ? (wv[e >> 1] >> 16) : (wv[e >> 1] & 0xffffu)); }
;                     else             *(u32x4*)(HY + (size_t)row * 1536 + (pn - 6) * 256 + ct) = w;
.LBB0_526:
	s_nop 0
	s_nop 0
	v_add_u32_e32 v64, 0x80, v152
	v_ashrrev_i32_e32 v65, 31, v64
	v_mad_i64_i32 v[68:69], s[42:43], v64, s87, 0
	s_mov_b64 s[42:43], -1
	s_nop 0
	v_fmamk_f32 v66, v251, 0x3a800000, v165
	v_cmp_gt_f32_e32 vcc, s85, v66
	v_mul_f32_e32 v67, 0x4b800000, v66
	s_nop 0
	v_cndmask_b32_e32 v66, v66, v67, vcc
	v_rsq_f32_e32 v66, v66
	s_nop 0
	v_mul_f32_e32 v67, 0x45800000, v66
	v_cndmask_b32_e32 v66, v66, v67, vcc
	v_mul_f32_e32 v67, 0x3e000000, v66
	v_cndmask_b32_e64 v70, v66, v67, s[8:9]
	v_pk_mul_f32 v[62:63], v[62:63], v[70:71] op_sel_hi:[1,0]
	v_pk_mul_f32 v[60:61], v[60:61], v[70:71] op_sel_hi:[1,0]
	v_pk_mul_f32 v[72:73], v[58:59], v[70:71] op_sel_hi:[1,0]
	v_pk_mul_f32 v[58:59], v[56:57], v[70:71] op_sel_hi:[1,0]
	v_lshlrev_b64 v[66:67], 10, v[64:65]
	v_cvt_pk_bf16_f32 v56, v60, v61
	v_cvt_pk_bf16_f32 v57, v62, v63
	v_cvt_pk_bf16_f32 v58, v58, v59
	v_cvt_pk_bf16_f32 v59, v72, v73
	s_and_b64 vcc, exec, s[6:7]
	s_cbranch_vccnz .LBB0_536
	s_and_b64 vcc, exec, s[4:5]
	s_cbranch_vccnz .LBB0_533
	s_andn2_b64 vcc, exec, s[36:37]
	s_cbranch_vccnz .LBB0_530
	v_lshl_add_u64 v[60:61], s[80:81], 0, v[68:69]
	v_lshl_add_u64 v[60:61], s[12:13], 1, v[60:61]
	v_lshl_add_u64 v[60:61], v[60:61], 0, v[136:137]
	s_mov_b64 s[42:43], 0
	global_store_dwordx4 v[60:61], v[56:59], off

; DI unsigned pk2(float lo, float hi) { f32x2_t v = {lo, hi}; bf16x2_t b = __builtin_convertvector(v, bf16x2_t); return __builtin_bit_cast(unsigned, b); }
; DI int rot_t(int c, int t) { return (t + 128 * c) & (MTOK - 1); }
;     DI void operator()(AccRef acc, const Unit& u, int wr, int wc, int fr, int fq) const {
;     ...
;                 const int row = row0 + ai * HALF + m * 16;
;                 float rs = rsqrtf(SS0[row] * (1.0f / DM) + EPSN); if (pn < 2) rs *= 0.125f;
; #pragma unroll
;                 for (int bj = 0; bj < 2; ++bj) {
;                     const f32x4 v0 = acc[ai][bj][m][0] * rs, v1 = acc[ai][bj][m][1] * rs;
;                     u32x4 w; w.x = pk2(v0[0], v0[1]); w.y = pk2(v0[2], v0[3]); w.z = pk2(v1[0], v1[1]); w.w = pk2(v1[2], v1[3]);
;                     const int ct = bj * HALF + cb;
;                     if (pn < 2)      *(u32x4*)(Q + (size_t)row * 512 + pn * 256 + ct) = w;
;                     else if (pn < 4) *(u32x4*)(K + (size_t)row * 512 + (pn - 2) * 256 + ct) = w;
;                     else if (pn < 6) { const int vc = (pn - 4) * 256 + ct; const unsigned wv[4] = {w.x, w.y, w.z, w.w};
; _Pragma("unroll")
;                         for (int e = 0; e < 8; ++e) VT[(size_t)(vc + e) * MTOK + rot_t(vc + e, row)] = (bf16)((e & 1) ? (wv[e >> 1] >> 16) : (wv[e >> 1] & 0xffffu)); }
;                     else             *(u32x4*)(HY + (size_t)row * 1536 + (pn - 6) * 256 + ct) = w;
.LBB0_550:
	s_nop 0
	s_nop 0
	v_add_u32_e32 v48, 0x90, v152
	v_ashrrev_i32_e32 v49, 31, v48
	v_mad_i64_i32 v[52:53], s[42:43], v48, s87, 0
	s_mov_b64 s[42:43], -1
	s_nop 0
	v_fmamk_f32 v50, v252, 0x3a800000, v165
	v_cmp_gt_f32_e32 vcc, s85, v50
	v_mul_f32_e32 v51, 0x4b800000, v50
	s_nop 0
	v_cndmask_b32_e32 v50, v50, v51, vcc
	v_rsq_f32_e32 v50, v50
	s_nop 0
	v_mul_f32_e32 v51, 0x45800000, v50
	v_cndmask_b32_e32 v50, v50, v51, vcc
	v_mul_f32_e32 v51, 0x3e000000, v50
	v_cndmask_b32_e64 v54, v50, v51, s[8:9]
	v_pk_mul_f32 v[46:47], v[46:47], v[54:55] op_sel_hi:[1,0]
	v_pk_mul_f32 v[44:45], v[44:45], v[54:55] op_sel_hi:[1,0]
	v_pk_mul_f32 v[56:57], v[42:43], v[54:55] op_sel_hi:[1,0]
	v_pk_mul_f32 v[42:43], v[40:41], v[54:55] op_sel_hi:[1,0]
	v_lshlrev_b64 v[50:51], 10, v[48:49]
	v_cvt_pk_bf16_f32 v40, v44, v45
	v_cvt_pk_bf16_f32 v41, v46, v47
	v_cvt_pk_bf16_f32 v42, v42, v43
	v_cvt_pk_bf16_f32 v43, v56, v57
	s_and_b64 vcc, exec, s[6:7]
	s_cbranch_vccnz .LBB0_560
	s_and_b64 vcc, exec, s[4:5]
	s_cbranch_vccnz .LBB0_557
	s_andn2_b64 vcc, exec, s[36:37]
	s_cbranch_vccnz .LBB0_554
	v_lshl_add_u64 v[44:45], s[80:81], 0, v[52:53]
	v_lshl_add_u64 v[44:45], s[12:13], 1, v[44:45]
	v_lshl_add_u64 v[44:45], v[44:45], 0, v[136:137]
	s_mov_b64 s[42:43], 0
	global_store_dwordx4 v[44:45], v[40:43], off

; DI unsigned pk2(float lo, float hi) { f32x2_t v = {lo, hi}; bf16x2_t b = __builtin_convertvector(v, bf16x2_t); return __builtin_bit_cast(unsigned, b); }
; DI int rot_t(int c, int t) { return (t + 128 * c) & (MTOK - 1); }
;     DI void operator()(AccRef acc, const Unit& u, int wr, int wc, int fr, int fq) const {
;     ...
;                 const int row = row0 + ai * HALF + m * 16;
;                 float rs = rsqrtf(SS0[row] * (1.0f / DM) + EPSN); if (pn < 2) rs *= 0.125f;
; #pragma unroll
;                 for (int bj = 0; bj < 2; ++bj) {
;                     const f32x4 v0 = acc[ai][bj][m][0] * rs, v1 = acc[ai][bj][m][1] * rs;
;                     u32x4 w; w.x = pk2(v0[0], v0[1]); w.y = pk2(v0[2], v0[3]); w.z = pk2(v1[0], v1[1]); w.w = pk2(v1[2], v1[3]);
;                     const int ct = bj * HALF + cb;
;                     if (pn < 2)      *(u32x4*)(Q + (size_t)row * 512 + pn * 256 + ct) = w;
;                     else if (pn < 4) *(u32x4*)(K + (size_t)row * 512 + (pn - 2) * 256 + ct) = w;
;                     else if (pn < 6) { const int vc = (pn - 4) * 256 + ct; const unsigned wv[4] = {w.x, w.y, w.z, w.w};
; _Pragma("unroll")
;                         for (int e = 0; e < 8; ++e) VT[(size_t)(vc + e) * MTOK + rot_t(vc + e, row)] = (bf16)((e & 1) ? (wv[e >> 1] >> 16) : (wv[e >> 1] & 0xffffu)); }
;                     else             *(u32x4*)(HY + (size_t)row * 1536 + (pn - 6) * 256 + ct) = w;
.LBB0_574:
	s_nop 0
	s_nop 0
	v_add_u32_e32 v32, 0xa0, v152
	v_ashrrev_i32_e32 v33, 31, v32
	v_mad_i64_i32 v[36:37], s[42:43], v32, s87, 0
	s_mov_b64 s[42:43], -1
	s_nop 0
	v_fmamk_f32 v34, v253, 0x3a800000, v165
	v_cmp_gt_f32_e32 vcc, s85, v34
	v_mul_f32_e32 v35, 0x4b800000, v34
	s_nop 0
	v_cndmask_b32_e32 v34, v34, v35, vcc
	v_rsq_f32_e32 v34, v34
	s_nop 0
	v_mul_f32_e32 v35, 0x45800000, v34
	v_cndmask_b32_e32 v34, v34, v35, vcc
	v_mul_f32_e32 v35, 0x3e000000, v34
	v_cndmask_b32_e64 v38, v34, v35, s[8:9]
	v_pk_mul_f32 v[30:31], v[30:31], v[38:39] op_sel_hi:[1,0]
	v_pk_mul_f32 v[28:29], v[28:29], v[38:39] op_sel_hi:[1,0]
	v_pk_mul_f32 v[40:41], v[26:27], v[38:39] op_sel_hi:[1,0]
	v_pk_mul_f32 v[26:27], v[24:25], v[38:39] op_sel_hi:[1,0]
	v_lshlrev_b64 v[34:35], 10, v[32:33]
	v_cvt_pk_bf16_f32 v24, v28, v29
	v_cvt_pk_bf16_f32 v25, v30, v31
	v_cvt_pk_bf16_f32 v26, v26, v27
	v_cvt_pk_bf16_f32 v27, v40, v41
	s_and_b64 vcc, exec, s[6:7]
	s_cbranch_vccnz .LBB0_584
	s_and_b64 vcc, exec, s[4:5]
	s_cbranch_vccnz .LBB0_581
	s_andn2_b64 vcc, exec, s[36:37]
	s_cbranch_vccnz .LBB0_578
	v_lshl_add_u64 v[28:29], s[80:81], 0, v[36:37]
	v_lshl_add_u64 v[28:29], s[12:13], 1, v[28:29]
	v_lshl_add_u64 v[28:29], v[28:29], 0, v[136:137]
	s_mov_b64 s[42:43], 0
	global_store_dwordx4 v[28:29], v[24:27], off

; DI unsigned pk2(float lo, float hi) { f32x2_t v = {lo, hi}; bf16x2_t b = __builtin_convertvector(v, bf16x2_t); return __builtin_bit_cast(unsigned, b); }
; DI int rot_t(int c, int t) { return (t + 128 * c) & (MTOK - 1); }
;     DI void operator()(AccRef acc, const Unit& u, int wr, int wc, int fr, int fq) const {
;     ...
;                 const int row = row0 + ai * HALF + m * 16;
;                 float rs = rsqrtf(SS0[row] * (1.0f / DM) + EPSN); if (pn < 2) rs *= 0.125f;
; #pragma unroll
;                 for (int bj = 0; bj < 2; ++bj) {
;                     const f32x4 v0 = acc[ai][bj][m][0] * rs, v1 = acc[ai][bj][m][1] * rs;
;                     u32x4 w; w.x = pk2(v0[0], v0[1]); w.y = pk2(v0[2], v0[3]); w.z = pk2(v1[0], v1[1]); w.w = pk2(v1[2], v1[3]);
;                     const int ct = bj * HALF + cb;
;                     if (pn < 2)      *(u32x4*)(Q + (size_t)row * 512 + pn * 256 + ct) = w;
;                     else if (pn < 4) *(u32x4*)(K + (size_t)row * 512 + (pn - 2) * 256 + ct) = w;
;                     else if (pn < 6) { const int vc = (pn - 4) * 256 + ct; const unsigned wv[4] = {w.x, w.y, w.z, w.w};
; _Pragma("unroll")
;                         for (int e = 0; e < 8; ++e) VT[(size_t)(vc + e) * MTOK + rot_t(vc + e, row)] = (bf16)((e & 1) ? (wv[e >> 1] >> 16) : (wv[e >> 1] & 0xffffu)); }
;                     else             *(u32x4*)(HY + (size_t)row * 1536 + (pn - 6) * 256 + ct) = w;
.LBB0_598:
	s_nop 0
	s_nop 0
	v_add_u32_e32 v16, 0xb0, v152
	v_ashrrev_i32_e32 v17, 31, v16
	s_nop 0
	v_fmamk_f32 v18, v254, 0x3a800000, v165
	v_cmp_gt_f32_e32 vcc, s85, v18
	v_mul_f32_e32 v19, 0x4b800000, v18
	s_nop 0
	v_cndmask_b32_e32 v18, v18, v19, vcc
	v_rsq_f32_e32 v18, v18
	s_nop 0
	v_mul_f32_e32 v19, 0x45800000, v18
	v_cndmask_b32_e32 v18, v18, v19, vcc
	v_mul_f32_e32 v19, 0x3e000000, v18
	v_cndmask_b32_e64 v22, v18, v19, s[8:9]
	v_mad_i64_i32 v[20:21], s[8:9], v16, s87, 0
	v_pk_mul_f32 v[14:15], v[14:15], v[22:23] op_sel_hi:[1,0]
	v_pk_mul_f32 v[12:13], v[12:13], v[22:23] op_sel_hi:[1,0]
	v_pk_mul_f32 v[24:25], v[10:11], v[22:23] op_sel_hi:[1,0]
	v_pk_mul_f32 v[10:11], v[8:9], v[22:23] op_sel_hi:[1,0]
	v_lshlrev_b64 v[18:19], 10, v[16:17]
	v_cvt_pk_bf16_f32 v8, v12, v13
	v_cvt_pk_bf16_f32 v9, v14, v15
	v_cvt_pk_bf16_f32 v10, v10, v11
	v_cvt_pk_bf16_f32 v11, v24, v25
	s_mov_b64 s[8:9], -1
	s_and_b64 vcc, exec, s[6:7]
	s_cbranch_vccnz .LBB0_608
	s_and_b64 vcc, exec, s[4:5]
	s_cbranch_vccnz .LBB0_605
	s_andn2_b64 vcc, exec, s[36:37]
	s_cbranch_vccnz .LBB0_602
	v_lshl_add_u64 v[12:13], s[80:81], 0, v[20:21]
	v_lshl_add_u64 v[12:13], s[12:13], 1, v[12:13]
	v_lshl_add_u64 v[12:13], v[12:13], 0, v[136:137]
	s_mov_b64 s[8:9], 0
	global_store_dwordx4 v[12:13], v[8:11], off

; #define LAS __attribute__((address_space(3)))
; DI bf16 f2bf(float f) { return (bf16)(pk2(f, 0.f) & 0xffffu); }
; template <int L, int NB>
; DI void conv_unit(const Frame& F, int c, const bf16* FRg, const float* F0, const float* hyD, const bf16* UT, bf16* YT, int tok0, bool dry) {
;     ...
;         const bf16* frow = FRg + (size_t)c * 2 * L;
;         for (int ch = F.tid; ch < 2 * L / 8; ch += 512) { const u32x4 v = *(const u32x4*)(frow + 8 * ch); const int x0 = 8 * ch; *(LAS u32x4*)(fr + 2 * x0 + ((x0 >> LOGRS) << 4)) = v; }
;         __syncthreads();
;         if (F.tid == 0) *(LAS bf16*)(fr + 2 * L + ((L >> LOGRS) << 4)) = f2bf(F0[c] + F0[512 + c] + hyD[c]);
;         __syncthreads();
.LBB0_778:
	s_or_b64 exec, exec, s[28:29]
	s_mov_b32 s1, s36
	s_lshl_b64 s[28:29], s[0:1], 14
	v_lshl_add_u64 v[2:3], v[154:155], 0, s[28:29]
	s_mov_b64 s[38:39], 0x2000
	v_lshl_add_u64 v[4:5], v[2:3], 0, s[38:39]
	global_load_dwordx4 v[6:9], v[2:3], off
	global_load_dwordx4 v[10:13], v[4:5], off
	s_lshl_b64 s[98:99], s[26:27], 2
	s_add_u32 s100, s34, s98
	s_addc_u32 s101, s35, s99
	global_load_dword v74, v0, s[100:101]
	global_load_dword v75, v0, s[100:101] offset:2048
	s_add_u32 s98, s30, s98
	s_addc_u32 s99, s31, s99
	global_load_dword v76, v0, s[98:99]
	v_add_u32_e32 v1, 0x2200, v170
	s_waitcnt vmcnt(4)
	ds_write_b128 v170, v[6:9]
	s_waitcnt vmcnt(3)
	ds_write_b128 v1, v[10:13]
	s_waitcnt lgkmcnt(0)
	s_barrier
	s_mov_b64 s[28:29], exec
	v_readlane_b32 s38, v246, 0
	v_readlane_b32 s39, v246, 1
	s_and_b64 s[38:39], s[28:29], s[38:39]
	s_mov_b64 exec, s[38:39]
	s_cbranch_execz .LBB0_782
	s_waitcnt vmcnt(0)
	v_add_f32_e32 v1, v74, v75
	v_add_f32_e32 v1, v1, v76
	v_cvt_pk_bf16_f32 v1, v1, s0
	ds_write_b16 v0, v1 offset:8704

; #define LAS __attribute__((address_space(3)))
; DI bf16 f2bf(float f) { return (bf16)(pk2(f, 0.f) & 0xffffu); }
; template <int L, int NB>
; DI void conv_unit(const Frame& F, int c, const bf16* FRg, const float* F0, const float* hyD, const bf16* UT, bf16* YT, int tok0, bool dry) {
;     ...
;     CONV_ISSUE(0);
;     {
;         const bf16* frow = FRg + (size_t)c * 2 * L;
;         for (int ch = F.tid; ch < 2 * L / 8; ch += 512) { const u32x4 v = *(const u32x4*)(frow + 8 * ch); const int x0 = 8 * ch; *(LAS u32x4*)(fr + 2 * x0 + ((x0 >> LOGRS) << 4)) = v; }
;         __syncthreads();
;         if (F.tid == 0) *(LAS bf16*)(fr + 2 * L + ((L >> LOGRS) << 4)) = f2bf(F0[c] + F0[512 + c] + hyD[c]);
;         __syncthreads();
.LBB0_896:
	s_or_b64 exec, exec, s[28:29]
	s_add_i32 s28, s1, 0x3e00
	s_add_i32 s29, s1, 0x3e08
	s_add_u32 s26, s40, s26
	s_addc_u32 s27, s41, s27
	global_load_dwordx4 v[2:5], v208, s[26:27]
	v_add_u32_e32 v1, s28, v161
	v_and_b32_e32 v1, 0x7ff8, v1
	v_lshlrev_b32_e32 v1, 1, v1
	global_load_dwordx4 v[40:43], v1, s[38:39]
	v_add_u32_e32 v1, s29, v161
	v_and_b32_e32 v1, 0x7ff8, v1
	v_lshlrev_b32_e32 v1, 1, v1
	global_load_dwordx4 v[44:47], v1, s[38:39]
	v_add_u32_e32 v1, s28, v162
	v_and_b32_e32 v1, 0x7ff8, v1
	v_lshlrev_b32_e32 v1, 1, v1
	global_load_dwordx4 v[48:51], v1, s[38:39]
	v_add_u32_e32 v1, s29, v162
	v_and_b32_e32 v1, 0x7ff8, v1
	v_lshlrev_b32_e32 v1, 1, v1
	global_load_dwordx4 v[52:55], v1, s[38:39]
	v_add_u32_e32 v1, s28, v163
	v_and_b32_e32 v1, 0x7ff8, v1
	v_lshlrev_b32_e32 v1, 1, v1
	global_load_dwordx4 v[56:59], v1, s[38:39]
	v_add_u32_e32 v1, s29, v163
	v_and_b32_e32 v1, 0x7ff8, v1
	v_lshlrev_b32_e32 v1, 1, v1
	global_load_dwordx4 v[64:67], v1, s[38:39]
	v_add_u32_e32 v1, s28, v164
	v_and_b32_e32 v1, 0x7ff8, v1
	v_lshlrev_b32_e32 v1, 1, v1
	global_load_dwordx4 v[68:71], v1, s[38:39]
	v_add_u32_e32 v1, s29, v164
	v_and_b32_e32 v1, 0x7ff8, v1
	v_lshlrev_b32_e32 v1, 1, v1
	global_load_dwordx4 v[72:75], v1, s[38:39]
	global_load_dwordx4 v[6:9], v210, s[26:27]
	global_load_dwordx4 v[10:13], v212, s[26:27]
	global_load_dwordx4 v[14:17], v214, s[26:27]
	global_load_dwordx4 v[18:21], v216, s[26:27]
	global_load_dwordx4 v[22:25], v218, s[26:27]
	global_load_dwordx4 v[26:29], v220, s[26:27]
	s_lshl_b64 s[98:99], s[78:79], 2
	s_add_u32 s100, s94, s98
	s_addc_u32 s101, s95, s99
	global_load_dword v76, v0, s[100:101]
	global_load_dword v77, v0, s[100:101] offset:2048
	s_add_u32 s98, s30, s98
	s_addc_u32 s99, s31, s99
	global_load_dword v78, v0, s[98:99]
	s_waitcnt vmcnt(17)
	ds_write_b128 v209, v[2:5]
	s_waitcnt vmcnt(8)
	ds_write_b128 v211, v[6:9]
	s_waitcnt vmcnt(7)
	ds_write_b128 v213, v[10:13]
	s_waitcnt vmcnt(6)
	ds_write_b128 v215, v[14:17]
	s_waitcnt vmcnt(5)
	ds_write_b128 v217, v[18:21]
	s_waitcnt vmcnt(4)
	ds_write_b128 v219, v[22:25]
	s_waitcnt vmcnt(3)
	ds_write_b128 v221, v[26:29]
	s_and_saveexec_b64 s[28:29], s[24:25]
	s_cbranch_execz .LBB0_898
	global_load_dwordx4 v[2:5], v222, s[26:27]
	s_waitcnt vmcnt(0)
	ds_write_b128 v223, v[2:5]
.LBB0_898:
	s_or_b64 exec, exec, s[28:29]
	s_waitcnt lgkmcnt(0)
	s_barrier
	s_mov_b64 s[26:27], exec
	v_readlane_b32 s28, v246, 0
	v_readlane_b32 s29, v246, 1
	s_and_b64 s[28:29], s[26:27], s[28:29]
	s_mov_b64 exec, s[28:29]
	s_cbranch_execz .LBB0_900
	s_waitcnt vmcnt(0)
	v_add_f32_e32 v1, v76, v77
	v_add_f32_e32 v1, v1, v78
	v_cvt_pk_bf16_f32 v1, v1, s0
	ds_write_b16 v0, v1 offset:33280

; DI unsigned pk2(float lo, float hi) { f32x2_t v = {lo, hi}; bf16x2_t b = __builtin_convertvector(v, bf16x2_t); return __builtin_bit_cast(unsigned, b); }
; DI float sigmoidf_(float x) { return 1.0f / (1.0f + __expf(-x)); }
;     DI void operator()(AccRef acc, const Unit& u, int wr, int wc, int fr, int fq) const {
;     ...
;             for (int m = 0; m < 4; ++m) {
;                 const int row = row0 + ai * HALF + m * 16; const float rs = rsqrtf(SS0[row] * (1.0f / DM) + EPSN);
; #pragma unroll
;                 for (int bj = 0; bj < 2; ++bj) {
;                     const f32x4 v0 = acc[ai][bj][m][0] * rs, v1 = acc[ai][bj][m][1] * rs;
;                     u32x4 w; w.x = pk2(sigmoidf_(v0[0]), sigmoidf_(v0[1])); w.y = pk2(sigmoidf_(v0[2]), sigmoidf_(v0[3])); w.z = pk2(sigmoidf_(v1[0]), sigmoidf_(v1[1])); w.w = pk2(sigmoidf_(v1[2]), sigmoidf_(v1[3]));
;                     *(u32x4*)(D + (size_t)row * DM + col0 + bj * HALF) = w;
;                 }
.LBB0_1250:
	v_lshl_add_u32 v146, s0, 8, v160
	v_ashrrev_i32_e32 v147, 31, v146
	v_lshl_add_u64 v[144:145], v[146:147], 2, s[82:83]
	global_load_dword v152, v[144:145], off
	global_load_dword v248, v[144:145], off offset:64
	global_load_dword v249, v[144:145], off offset:128
	global_load_dword v250, v[144:145], off offset:192
	global_load_dword v251, v[144:145], off offset:512
	global_load_dword v252, v[144:145], off offset:576
	global_load_dword v253, v[144:145], off offset:640
	global_load_dword v254, v[144:145], off offset:704
	v_lshlrev_b64 v[174:175], 11, v[146:147]
	s_waitcnt vmcnt(0)
	v_fmamk_f32 v152, v152, 0x3a800000, v172
	v_mul_f32_e32 v154, 0x4b800000, v152
	v_cmp_gt_f32_e32 vcc, s62, v152
	s_nop 1
	v_cndmask_b32_e32 v152, v152, v154, vcc
	v_rsq_f32_e32 v152, v152
	v_lshl_or_b32 v154, s1, 8, v162
	v_ashrrev_i32_e32 v155, 31, v154
	v_mul_f32_e32 v147, 0x45800000, v152
	v_cndmask_b32_e32 v152, v152, v147, vcc
	v_pk_mul_f32 v[124:125], v[124:125], v[152:153] op_sel_hi:[1,0]
	v_pk_mul_f32 v[126:127], v[126:127], v[152:153] op_sel_hi:[1,0]
	v_pk_mul_f32 v[120:121], v[120:121], v[152:153] op_sel_hi:[1,0]
	v_mul_f32_e32 v124, 0xbfb8aa3b, v124
	v_mul_f32_e32 v125, 0xbfb8aa3b, v125
	v_pk_mul_f32 v[122:123], v[122:123], v[152:153] op_sel_hi:[1,0]
	v_mul_f32_e32 v126, 0xbfb8aa3b, v126
	v_mul_f32_e32 v127, 0xbfb8aa3b, v127
	v_mul_f32_e32 v147, 0xbfb8aa3b, v120
	v_mul_f32_e32 v173, 0xbfb8aa3b, v121
	v_exp_f32_e32 v120, v124
	v_exp_f32_e32 v121, v125
	v_mul_f32_e32 v176, 0xbfb8aa3b, v122
	v_mul_f32_e32 v178, 0xbfb8aa3b, v123
	v_exp_f32_e32 v122, v126
	v_exp_f32_e32 v123, v127
	v_exp_f32_e32 v124, v147
	v_exp_f32_e32 v125, v173
	v_pk_add_f32 v[120:121], v[120:121], 1.0 op_sel_hi:[1,0]
	v_exp_f32_e32 v126, v176
	v_pk_add_f32 v[176:177], v[122:123], 1.0 op_sel_hi:[1,0]
	v_pk_add_f32 v[124:125], v[124:125], 1.0 op_sel_hi:[1,0]
	v_rcp_f32_e32 v121, v121
	v_rcp_f32_e32 v120, v120
	s_nop 0
	v_cvt_pk_bf16_f32 v122, v120, v121
	v_rcp_f32_e32 v125, v125
	v_exp_f32_e32 v127, v178
	v_rcp_f32_e32 v120, v177
	v_rcp_f32_e32 v121, v176
	s_nop 0
	v_cvt_pk_bf16_f32 v123, v121, v120
	v_pk_add_f32 v[120:121], v[126:127], 1.0 op_sel_hi:[1,0]
	v_rcp_f32_e32 v124, v124
	s_nop 0
	v_cvt_pk_bf16_f32 v124, v124, v125
	v_rcp_f32_e32 v121, v121
	v_pk_mul_f32 v[116:117], v[116:117], v[152:153] op_sel_hi:[1,0]
	v_mul_f32_e32 v116, 0xbfb8aa3b, v116
	v_lshl_add_u64 v[126:127], s[54:55], 0, v[174:175]
	v_exp_f32_e32 v174, v116
	v_mul_f32_e32 v116, 0xbfb8aa3b, v117
	v_exp_f32_e32 v175, v116
	v_rcp_f32_e32 v120, v120
	s_nop 0
	v_cvt_pk_bf16_f32 v125, v120, v121
	v_lshlrev_b64 v[120:121], 1, v[154:155]
	v_lshl_add_u64 v[116:117], v[126:127], 0, v[120:121]
	global_store_dwordx4 v[116:117], v[122:125], off
	v_pk_mul_f32 v[118:119], v[118:119], v[152:153] op_sel_hi:[1,0]
	v_pk_mul_f32 v[114:115], v[114:115], v[152:153] op_sel_hi:[1,0]
	v_pk_add_f32 v[122:123], v[174:175], 1.0 op_sel_hi:[1,0]
	v_pk_mul_f32 v[124:125], v[112:113], v[152:153] op_sel_hi:[1,0]
	v_mul_f32_e32 v114, 0xbfb8aa3b, v114
	v_mul_f32_e32 v115, 0xbfb8aa3b, v115
	v_exp_f32_e32 v114, v114
	v_rcp_f32_e32 v123, v123
	v_mul_f32_e32 v113, 0xbfb8aa3b, v119
	v_mul_f32_e32 v112, 0xbfb8aa3b, v118
	v_exp_f32_e32 v112, v112
	v_exp_f32_e32 v113, v113
	s_nop 0
	v_pk_add_f32 v[118:119], v[112:113], 1.0 op_sel_hi:[1,0]
	v_rcp_f32_e32 v112, v122
	s_nop 0
	v_cvt_pk_bf16_f32 v112, v112, v123
	v_mul_f32_e32 v122, 0xbfb8aa3b, v124
	v_mul_f32_e32 v123, 0xbfb8aa3b, v125
	v_exp_f32_e32 v122, v122
	v_exp_f32_e32 v123, v123
	v_rcp_f32_e32 v113, v119
	v_pk_add_f32 v[122:123], v[122:123], 1.0 op_sel_hi:[1,0]
	v_rcp_f32_e32 v118, v118
	s_nop 0
	v_cvt_pk_bf16_f32 v113, v118, v113
	v_rcp_f32_e32 v123, v123
	v_exp_f32_e32 v115, v115
	s_nop 0
	v_pk_add_f32 v[118:119], v[114:115], 1.0 op_sel_hi:[1,0]
	v_rcp_f32_e32 v114, v122
	s_nop 0
	v_cvt_pk_bf16_f32 v114, v114, v123
	v_rcp_f32_e32 v115, v119
	v_rcp_f32_e32 v118, v118
	s_nop 0
	v_cvt_pk_bf16_f32 v115, v118, v115
	global_store_dwordx4 v[116:117], v[112:115], off offset:256
	s_nop 0
	s_nop 0
	v_or_b32_e32 v114, 16, v146
	v_ashrrev_i32_e32 v115, 31, v114
	v_lshlrev_b64 v[114:115], 11, v[114:115]
	s_nop 0
	v_fmamk_f32 v112, v248, 0x3a800000, v172
	v_mul_f32_e32 v113, 0x4b800000, v112
	v_cmp_gt_f32_e32 vcc, s62, v112
	s_nop 1
	v_cndmask_b32_e32 v112, v112, v113, vcc
	v_rsq_f32_e32 v112, v112
	s_nop 0
	v_mul_f32_e32 v113, 0x45800000, v112
	v_cndmask_b32_e32 v112, v112, v113, vcc
	v_pk_mul_f32 v[108:109], v[108:109], v[112:113] op_sel_hi:[1,0]
	s_nop 0
	v_mul_f32_e32 v108, 0xbfb8aa3b, v108
	v_mul_f32_e32 v109, 0xbfb8aa3b, v109
	v_exp_f32_e32 v108, v108
	v_exp_f32_e32 v109, v109
	s_nop 0
	v_pk_add_f32 v[108:109], v[108:109], 1.0 op_sel_hi:[1,0]
	s_nop 0
	v_pk_mul_f32 v[118:119], v[104:105], v[112:113] op_sel_hi:[1,0]
	v_pk_mul_f32 v[110:111], v[110:111], v[112:113] op_sel_hi:[1,0]
	v_pk_mul_f32 v[106:107], v[106:107], v[112:113] op_sel_hi:[1,0]
	v_rcp_f32_e32 v109, v109
	v_mul_f32_e32 v105, 0xbfb8aa3b, v111
	v_mul_f32_e32 v104, 0xbfb8aa3b, v110
	v_exp_f32_e32 v104, v104
	v_exp_f32_e32 v105, v105
	s_nop 0
	v_pk_add_f32 v[110:111], v[104:105], 1.0 op_sel_hi:[1,0]
	v_rcp_f32_e32 v104, v108
	s_nop 0
	v_cvt_pk_bf16_f32 v104, v104, v109
	v_mul_f32_e32 v109, 0xbfb8aa3b, v119
	v_mul_f32_e32 v108, 0xbfb8aa3b, v118
	v_exp_f32_e32 v108, v108
	v_exp_f32_e32 v109, v109
	v_rcp_f32_e32 v105, v111
	v_pk_add_f32 v[108:109], v[108:109], 1.0 op_sel_hi:[1,0]
	v_rcp_f32_e32 v110, v110
	s_nop 0
	v_cvt_pk_bf16_f32 v105, v110, v105
	v_rcp_f32_e32 v109, v109
	v_mul_f32_e32 v106, 0xbfb8aa3b, v106
	v_mul_f32_e32 v107, 0xbfb8aa3b, v107
	v_exp_f32_e32 v106, v106
	v_exp_f32_e32 v107, v107
	s_nop 0
; DI unsigned pk2(float lo, float hi) { f32x2_t v = {lo, hi}; bf16x2_t b = __builtin_convertvector(v, bf16x2_t); return __builtin_bit_cast(unsigned, b); }
; DI float sigmoidf_(float x) { return 1.0f / (1.0f + __expf(-x)); }
;     DI void operator()(AccRef acc, const Unit& u, int wr, int wc, int fr, int fq) const {
;     ...
;             for (int m = 0; m < 4; ++m) {
;                 const int row = row0 + ai * HALF + m * 16; const float rs = rsqrtf(SS0[row] * (1.0f / DM) + EPSN);
; #pragma unroll
;                 for (int bj = 0; bj < 2; ++bj) {
;                     const f32x4 v0 = acc[ai][bj][m][0] * rs, v1 = acc[ai][bj][m][1] * rs;
;                     u32x4 w; w.x = pk2(sigmoidf_(v0[0]), sigmoidf_(v0[1])); w.y = pk2(sigmoidf_(v0[2]), sigmoidf_(v0[3])); w.z = pk2(sigmoidf_(v1[0]), sigmoidf_(v1[1])); w.w = pk2(sigmoidf_(v1[2]), sigmoidf_(v1[3]));
;                     *(u32x4*)(D + (size_t)row * DM + col0 + bj * HALF) = w;
;                 }
	v_pk_add_f32 v[110:111], v[106:107], 1.0 op_sel_hi:[1,0]
	v_rcp_f32_e32 v106, v108
	s_nop 0
	v_cvt_pk_bf16_f32 v106, v106, v109
	v_rcp_f32_e32 v107, v111
	v_pk_mul_f32 v[100:101], v[100:101], v[112:113] op_sel_hi:[1,0]
	v_mul_f32_e32 v100, 0xbfb8aa3b, v100
	v_mul_f32_e32 v101, 0xbfb8aa3b, v101
	v_exp_f32_e32 v100, v100
	v_exp_f32_e32 v101, v101
	v_rcp_f32_e32 v108, v110
	s_nop 0
	v_cvt_pk_bf16_f32 v107, v108, v107
	v_lshl_add_u64 v[108:109], s[54:55], 0, v[114:115]
	v_lshl_add_u64 v[108:109], v[108:109], 0, v[120:121]
	v_pk_add_f32 v[100:101], v[100:101], 1.0 op_sel_hi:[1,0]
	global_store_dwordx4 v[108:109], v[104:107], off
	v_pk_mul_f32 v[102:103], v[102:103], v[112:113] op_sel_hi:[1,0]
	v_pk_mul_f32 v[98:99], v[98:99], v[112:113] op_sel_hi:[1,0]
	v_pk_mul_f32 v[104:105], v[96:97], v[112:113] op_sel_hi:[1,0]
	v_mul_f32_e32 v98, 0xbfb8aa3b, v98
	v_mul_f32_e32 v99, 0xbfb8aa3b, v99
	v_rcp_f32_e32 v101, v101
	v_mul_f32_e32 v97, 0xbfb8aa3b, v103
	v_mul_f32_e32 v96, 0xbfb8aa3b, v102
	v_exp_f32_e32 v96, v96
	v_exp_f32_e32 v97, v97
	s_nop 0
	v_pk_add_f32 v[102:103], v[96:97], 1.0 op_sel_hi:[1,0]
	v_rcp_f32_e32 v96, v100
	s_nop 0
	v_cvt_pk_bf16_f32 v96, v96, v101
	v_mul_f32_e32 v101, 0xbfb8aa3b, v105
	v_mul_f32_e32 v100, 0xbfb8aa3b, v104
	v_exp_f32_e32 v100, v100
	v_exp_f32_e32 v101, v101
	v_rcp_f32_e32 v97, v103
	v_pk_add_f32 v[100:101], v[100:101], 1.0 op_sel_hi:[1,0]
	v_rcp_f32_e32 v102, v102
	s_nop 0
	v_cvt_pk_bf16_f32 v97, v102, v97
	v_rcp_f32_e32 v101, v101
	v_exp_f32_e32 v98, v98
	v_exp_f32_e32 v99, v99
	s_nop 0
	v_pk_add_f32 v[102:103], v[98:99], 1.0 op_sel_hi:[1,0]
	v_rcp_f32_e32 v98, v100
	s_nop 0
	v_cvt_pk_bf16_f32 v98, v98, v101
	v_rcp_f32_e32 v99, v103
	v_rcp_f32_e32 v100, v102
	s_nop 0
	v_cvt_pk_bf16_f32 v99, v100, v99
	global_store_dwordx4 v[108:109], v[96:99], off offset:256
	s_nop 0
	s_nop 0
	v_or_b32_e32 v98, 32, v146
	v_ashrrev_i32_e32 v99, 31, v98
	v_lshlrev_b64 v[98:99], 11, v[98:99]
	s_nop 0
	v_fmamk_f32 v96, v249, 0x3a800000, v172
	v_mul_f32_e32 v97, 0x4b800000, v96
	v_cmp_gt_f32_e32 vcc, s62, v96
	s_nop 1
	v_cndmask_b32_e32 v96, v96, v97, vcc
	v_rsq_f32_e32 v96, v96
	s_nop 0
	v_mul_f32_e32 v97, 0x45800000, v96
	v_cndmask_b32_e32 v96, v96, v97, vcc
	v_pk_mul_f32 v[92:93], v[92:93], v[96:97] op_sel_hi:[1,0]
	s_nop 0
	v_mul_f32_e32 v92, 0xbfb8aa3b, v92
	v_mul_f32_e32 v93, 0xbfb8aa3b, v93
	v_exp_f32_e32 v92, v92
	v_exp_f32_e32 v93, v93
	s_nop 0
	v_pk_add_f32 v[92:93], v[92:93], 1.0 op_sel_hi:[1,0]
	s_nop 0
	v_pk_mul_f32 v[100:101], v[88:89], v[96:97] op_sel_hi:[1,0]
	v_pk_mul_f32 v[94:95], v[94:95], v[96:97] op_sel_hi:[1,0]
	v_pk_mul_f32 v[90:91], v[90:91], v[96:97] op_sel_hi:[1,0]
	v_rcp_f32_e32 v93, v93
	v_mul_f32_e32 v89, 0xbfb8aa3b, v95
	v_mul_f32_e32 v88, 0xbfb8aa3b, v94
	v_exp_f32_e32 v88, v88
	v_exp_f32_e32 v89, v89
	s_nop 0
	v_pk_add_f32 v[94:95], v[88:89], 1.0 op_sel_hi:[1,0]
	v_rcp_f32_e32 v88, v92
	s_nop 0
	v_cvt_pk_bf16_f32 v88, v88, v93
	v_mul_f32_e32 v93, 0xbfb8aa3b, v101
	v_mul_f32_e32 v92, 0xbfb8aa3b, v100
	v_exp_f32_e32 v92, v92
	v_exp_f32_e32 v93, v93
	v_rcp_f32_e32 v89, v95
	v_pk_add_f32 v[92:93], v[92:93], 1.0 op_sel_hi:[1,0]
	v_rcp_f32_e32 v94, v94
	s_nop 0
	v_cvt_pk_bf16_f32 v89, v94, v89
	v_rcp_f32_e32 v93, v93
	v_mul_f32_e32 v90, 0xbfb8aa3b, v90
	v_mul_f32_e32 v91, 0xbfb8aa3b, v91
	v_exp_f32_e32 v90, v90
	v_exp_f32_e32 v91, v91
	s_nop 0
	v_pk_add_f32 v[94:95], v[90:91], 1.0 op_sel_hi:[1,0]
	v_rcp_f32_e32 v90, v92
	s_nop 0
	v_cvt_pk_bf16_f32 v90, v90, v93
	v_rcp_f32_e32 v91, v95
	v_pk_mul_f32 v[84:85], v[84:85], v[96:97] op_sel_hi:[1,0]
	v_mul_f32_e32 v84, 0xbfb8aa3b, v84
	v_mul_f32_e32 v85, 0xbfb8aa3b, v85
	v_exp_f32_e32 v84, v84
	v_exp_f32_e32 v85, v85
	v_rcp_f32_e32 v92, v94
	s_nop 0
	v_cvt_pk_bf16_f32 v91, v92, v91
	v_lshl_add_u64 v[92:93], s[54:55], 0, v[98:99]
	v_lshl_add_u64 v[92:93], v[92:93], 0, v[120:121]
	v_pk_add_f32 v[84:85], v[84:85], 1.0 op_sel_hi:[1,0]
	global_store_dwordx4 v[92:93], v[88:91], off
	v_pk_mul_f32 v[86:87], v[86:87], v[96:97] op_sel_hi:[1,0]
	v_pk_mul_f32 v[82:83], v[82:83], v[96:97] op_sel_hi:[1,0]
	v_pk_mul_f32 v[88:89], v[80:81], v[96:97] op_sel_hi:[1,0]
	v_mul_f32_e32 v82, 0xbfb8aa3b, v82
	v_mul_f32_e32 v83, 0xbfb8aa3b, v83
	v_rcp_f32_e32 v85, v85
	v_mul_f32_e32 v81, 0xbfb8aa3b, v87
	v_mul_f32_e32 v80, 0xbfb8aa3b, v86
	v_exp_f32_e32 v80, v80
	v_exp_f32_e32 v81, v81
	s_nop 0
	v_pk_add_f32 v[86:87], v[80:81], 1.0 op_sel_hi:[1,0]
	v_rcp_f32_e32 v80, v84
	s_nop 0
	v_cvt_pk_bf16_f32 v80, v80, v85
	v_mul_f32_e32 v85, 0xbfb8aa3b, v89
	v_mul_f32_e32 v84, 0xbfb8aa3b, v88
	v_exp_f32_e32 v84, v84
	v_exp_f32_e32 v85, v85
	v_rcp_f32_e32 v81, v87
	v_pk_add_f32 v[84:85], v[84:85], 1.0 op_sel_hi:[1,0]
	v_rcp_f32_e32 v86, v86
	s_nop 0
	v_cvt_pk_bf16_f32 v81, v86, v81
	v_rcp_f32_e32 v85, v85
	v_exp_f32_e32 v82, v82
	v_exp_f32_e32 v83, v83
	s_nop 0
	v_pk_add_f32 v[86:87], v[82:83], 1.0 op_sel_hi:[1,0]
	v_rcp_f32_e32 v82, v84
	s_nop 0
	v_cvt_pk_bf16_f32 v82, v82, v85
	v_rcp_f32_e32 v83, v87
	v_rcp_f32_e32 v84, v86
	s_nop 0
	v_cvt_pk_bf16_f32 v83, v84, v83
	global_store_dwordx4 v[92:93], v[80:83], off offset:256
	s_nop 0
	s_nop 0
	v_or_b32_e32 v82, 48, v146
	v_ashrrev_i32_e32 v83, 31, v82
	v_lshlrev_b64 v[82:83], 11, v[82:83]
	s_nop 0
	v_fmamk_f32 v80, v250, 0x3a800000, v172
	v_mul_f32_e32 v81, 0x4b800000, v80
	v_cmp_gt_f32_e32 vcc, s62, v80
	s_nop 1
	v_cndmask_b32_e32 v80, v80, v81, vcc
	v_rsq_f32_e32 v80, v80
	s_nop 0
	v_mul_f32_e32 v81, 0x45800000, v80
	v_cndmask_b32_e32 v80, v80, v81, vcc
	v_pk_mul_f32 v[76:77], v[76:77], v[80:81] op_sel_hi:[1,0]
	s_nop 0
	v_mul_f32_e32 v76, 0xbfb8aa3b, v76
	v_mul_f32_e32 v77, 0xbfb8aa3b, v77
	v_exp_f32_e32 v76, v76
	v_exp_f32_e32 v77, v77
	s_nop 0
; DI unsigned pk2(float lo, float hi) { f32x2_t v = {lo, hi}; bf16x2_t b = __builtin_convertvector(v, bf16x2_t); return __builtin_bit_cast(unsigned, b); }
; DI float sigmoidf_(float x) { return 1.0f / (1.0f + __expf(-x)); }
;     DI void operator()(AccRef acc, const Unit& u, int wr, int wc, int fr, int fq) const {
;     ...
;             for (int m = 0; m < 4; ++m) {
;                 const int row = row0 + ai * HALF + m * 16; const float rs = rsqrtf(SS0[row] * (1.0f / DM) + EPSN);
; #pragma unroll
;                 for (int bj = 0; bj < 2; ++bj) {
;                     const f32x4 v0 = acc[ai][bj][m][0] * rs, v1 = acc[ai][bj][m][1] * rs;
;                     u32x4 w; w.x = pk2(sigmoidf_(v0[0]), sigmoidf_(v0[1])); w.y = pk2(sigmoidf_(v0[2]), sigmoidf_(v0[3])); w.z = pk2(sigmoidf_(v1[0]), sigmoidf_(v1[1])); w.w = pk2(sigmoidf_(v1[2]), sigmoidf_(v1[3]));
;                     *(u32x4*)(D + (size_t)row * DM + col0 + bj * HALF) = w;
;                 }
	v_pk_add_f32 v[76:77], v[76:77], 1.0 op_sel_hi:[1,0]
	s_nop 0
	v_pk_mul_f32 v[84:85], v[72:73], v[80:81] op_sel_hi:[1,0]
	v_pk_mul_f32 v[78:79], v[78:79], v[80:81] op_sel_hi:[1,0]
	v_pk_mul_f32 v[74:75], v[74:75], v[80:81] op_sel_hi:[1,0]
	v_rcp_f32_e32 v77, v77
	v_mul_f32_e32 v73, 0xbfb8aa3b, v79
	v_mul_f32_e32 v72, 0xbfb8aa3b, v78
	v_exp_f32_e32 v72, v72
	v_exp_f32_e32 v73, v73
	s_nop 0
	v_pk_add_f32 v[78:79], v[72:73], 1.0 op_sel_hi:[1,0]
	v_rcp_f32_e32 v72, v76
	s_nop 0
	v_cvt_pk_bf16_f32 v72, v72, v77
	v_mul_f32_e32 v77, 0xbfb8aa3b, v85
	v_mul_f32_e32 v76, 0xbfb8aa3b, v84
	v_exp_f32_e32 v76, v76
	v_exp_f32_e32 v77, v77
	v_rcp_f32_e32 v73, v79
	v_pk_add_f32 v[76:77], v[76:77], 1.0 op_sel_hi:[1,0]
	v_rcp_f32_e32 v78, v78
	s_nop 0
	v_cvt_pk_bf16_f32 v73, v78, v73
	v_rcp_f32_e32 v77, v77
	v_mul_f32_e32 v74, 0xbfb8aa3b, v74
	v_mul_f32_e32 v75, 0xbfb8aa3b, v75
	v_exp_f32_e32 v74, v74
	v_exp_f32_e32 v75, v75
	s_nop 0
	v_pk_add_f32 v[78:79], v[74:75], 1.0 op_sel_hi:[1,0]
	v_rcp_f32_e32 v74, v76
	s_nop 0
	v_cvt_pk_bf16_f32 v74, v74, v77
	v_rcp_f32_e32 v75, v79
	v_pk_mul_f32 v[68:69], v[68:69], v[80:81] op_sel_hi:[1,0]
	v_mul_f32_e32 v68, 0xbfb8aa3b, v68
	v_mul_f32_e32 v69, 0xbfb8aa3b, v69
	v_exp_f32_e32 v68, v68
	v_exp_f32_e32 v69, v69
	v_rcp_f32_e32 v76, v78
	s_nop 0
	v_cvt_pk_bf16_f32 v75, v76, v75
	v_lshl_add_u64 v[76:77], s[54:55], 0, v[82:83]
	v_lshl_add_u64 v[76:77], v[76:77], 0, v[120:121]
	v_pk_add_f32 v[68:69], v[68:69], 1.0 op_sel_hi:[1,0]
	global_store_dwordx4 v[76:77], v[72:75], off
	v_pk_mul_f32 v[70:71], v[70:71], v[80:81] op_sel_hi:[1,0]
	v_pk_mul_f32 v[66:67], v[66:67], v[80:81] op_sel_hi:[1,0]
	v_pk_mul_f32 v[72:73], v[64:65], v[80:81] op_sel_hi:[1,0]
	v_mul_f32_e32 v66, 0xbfb8aa3b, v66
	v_mul_f32_e32 v67, 0xbfb8aa3b, v67
	v_rcp_f32_e32 v69, v69
	v_mul_f32_e32 v65, 0xbfb8aa3b, v71
	v_mul_f32_e32 v64, 0xbfb8aa3b, v70
	v_exp_f32_e32 v64, v64
	v_exp_f32_e32 v65, v65
	s_nop 0
	v_pk_add_f32 v[70:71], v[64:65], 1.0 op_sel_hi:[1,0]
	v_rcp_f32_e32 v64, v68
	s_nop 0
	v_cvt_pk_bf16_f32 v64, v64, v69
	v_mul_f32_e32 v69, 0xbfb8aa3b, v73
	v_mul_f32_e32 v68, 0xbfb8aa3b, v72
	v_exp_f32_e32 v68, v68
	v_exp_f32_e32 v69, v69
	v_rcp_f32_e32 v65, v71
	v_pk_add_f32 v[68:69], v[68:69], 1.0 op_sel_hi:[1,0]
	v_rcp_f32_e32 v70, v70
	s_nop 0
	v_cvt_pk_bf16_f32 v65, v70, v65
	v_rcp_f32_e32 v69, v69
	v_exp_f32_e32 v66, v66
	v_exp_f32_e32 v67, v67
	s_nop 0
	v_pk_add_f32 v[70:71], v[66:67], 1.0 op_sel_hi:[1,0]
	v_rcp_f32_e32 v66, v68
	s_nop 0
	v_cvt_pk_bf16_f32 v66, v66, v69
	v_rcp_f32_e32 v67, v71
	v_rcp_f32_e32 v68, v70
	s_nop 0
	v_cvt_pk_bf16_f32 v67, v68, v67
	global_store_dwordx4 v[76:77], v[64:67], off offset:256
	s_nop 0
	s_nop 0
	v_fmamk_f32 v64, v251, 0x3a800000, v172
	v_mul_f32_e32 v65, 0x4b800000, v64
	v_cmp_gt_f32_e32 vcc, s62, v64
	s_nop 1
	v_cndmask_b32_e32 v64, v64, v65, vcc
	v_rsq_f32_e32 v64, v64
	s_nop 0
	v_mul_f32_e32 v65, 0x45800000, v64
	v_cndmask_b32_e32 v64, v64, v65, vcc
	v_pk_mul_f32 v[60:61], v[60:61], v[64:65] op_sel_hi:[1,0]
	s_nop 0
	v_mul_f32_e32 v60, 0xbfb8aa3b, v60
	v_mul_f32_e32 v61, 0xbfb8aa3b, v61
	v_exp_f32_e32 v60, v60
	v_exp_f32_e32 v61, v61
	s_nop 0
	v_pk_add_f32 v[60:61], v[60:61], 1.0 op_sel_hi:[1,0]
	s_nop 0
	v_pk_mul_f32 v[66:67], v[56:57], v[64:65] op_sel_hi:[1,0]
	v_pk_mul_f32 v[62:63], v[62:63], v[64:65] op_sel_hi:[1,0]
	v_pk_mul_f32 v[58:59], v[58:59], v[64:65] op_sel_hi:[1,0]
	v_rcp_f32_e32 v61, v61
	v_mul_f32_e32 v57, 0xbfb8aa3b, v63
	v_mul_f32_e32 v56, 0xbfb8aa3b, v62
	v_exp_f32_e32 v56, v56
	v_exp_f32_e32 v57, v57
	s_nop 0
	v_pk_add_f32 v[62:63], v[56:57], 1.0 op_sel_hi:[1,0]
	v_rcp_f32_e32 v56, v60
	s_nop 0
	v_cvt_pk_bf16_f32 v56, v56, v61
	v_mul_f32_e32 v61, 0xbfb8aa3b, v67
	v_mul_f32_e32 v60, 0xbfb8aa3b, v66
	v_exp_f32_e32 v60, v60
	v_exp_f32_e32 v61, v61
	v_rcp_f32_e32 v57, v63
	v_pk_add_f32 v[60:61], v[60:61], 1.0 op_sel_hi:[1,0]
	v_rcp_f32_e32 v62, v62
	s_nop 0
	v_cvt_pk_bf16_f32 v57, v62, v57
	v_rcp_f32_e32 v61, v61
	v_mul_f32_e32 v58, 0xbfb8aa3b, v58
	v_mul_f32_e32 v59, 0xbfb8aa3b, v59
	v_exp_f32_e32 v58, v58
	v_exp_f32_e32 v59, v59
	s_nop 0
	v_pk_add_f32 v[62:63], v[58:59], 1.0 op_sel_hi:[1,0]
	v_rcp_f32_e32 v58, v60
	s_nop 0
	v_cvt_pk_bf16_f32 v58, v58, v61
	v_rcp_f32_e32 v59, v63
	s_mov_b64 s[0:1], 0x40000
	v_pk_mul_f32 v[52:53], v[52:53], v[64:65] op_sel_hi:[1,0]
	v_mul_f32_e32 v52, 0xbfb8aa3b, v52
	v_mul_f32_e32 v53, 0xbfb8aa3b, v53
	v_exp_f32_e32 v52, v52
	v_exp_f32_e32 v53, v53
	v_rcp_f32_e32 v60, v62
	s_nop 0
	v_cvt_pk_bf16_f32 v59, v60, v59
	v_lshl_add_u64 v[60:61], v[116:117], 0, s[0:1]
	s_mov_b32 s0, 0x40000
	v_add_co_u32_e32 v62, vcc, s0, v116
	v_pk_add_f32 v[52:53], v[52:53], 1.0 op_sel_hi:[1,0]
	s_nop 0
	v_addc_co_u32_e32 v63, vcc, 0, v117, vcc
	global_store_dwordx4 v[62:63], v[56:59], off
	v_pk_mul_f32 v[54:55], v[54:55], v[64:65] op_sel_hi:[1,0]
	v_pk_mul_f32 v[50:51], v[50:51], v[64:65] op_sel_hi:[1,0]
	v_pk_mul_f32 v[56:57], v[48:49], v[64:65] op_sel_hi:[1,0]
	v_mul_f32_e32 v50, 0xbfb8aa3b, v50
	v_mul_f32_e32 v51, 0xbfb8aa3b, v51
	v_rcp_f32_e32 v53, v53
	v_mul_f32_e32 v49, 0xbfb8aa3b, v55
	v_mul_f32_e32 v48, 0xbfb8aa3b, v54
	v_exp_f32_e32 v48, v48
	v_exp_f32_e32 v49, v49
	s_nop 0
	v_pk_add_f32 v[54:55], v[48:49], 1.0 op_sel_hi:[1,0]
	v_rcp_f32_e32 v48, v52
	s_nop 0
	v_cvt_pk_bf16_f32 v48, v48, v53
	v_mul_f32_e32 v53, 0xbfb8aa3b, v57
	v_mul_f32_e32 v52, 0xbfb8aa3b, v56
	v_exp_f32_e32 v52, v52
	v_exp_f32_e32 v53, v53
	v_rcp_f32_e32 v49, v55
	v_pk_add_f32 v[52:53], v[52:53], 1.0 op_sel_hi:[1,0]
	v_rcp_f32_e32 v54, v54
	s_nop 0
	v_cvt_pk_bf16_f32 v49, v54, v49
	v_rcp_f32_e32 v53, v53
	v_exp_f32_e32 v50, v50
	v_exp_f32_e32 v51, v51
	s_nop 0
	v_pk_add_f32 v[54:55], v[50:51], 1.0 op_sel_hi:[1,0]
; DI unsigned pk2(float lo, float hi) { f32x2_t v = {lo, hi}; bf16x2_t b = __builtin_convertvector(v, bf16x2_t); return __builtin_bit_cast(unsigned, b); }
; DI float sigmoidf_(float x) { return 1.0f / (1.0f + __expf(-x)); }
;     DI void operator()(AccRef acc, const Unit& u, int wr, int wc, int fr, int fq) const {
;     ...
;             for (int m = 0; m < 4; ++m) {
;                 const int row = row0 + ai * HALF + m * 16; const float rs = rsqrtf(SS0[row] * (1.0f / DM) + EPSN);
; #pragma unroll
;                 for (int bj = 0; bj < 2; ++bj) {
;                     const f32x4 v0 = acc[ai][bj][m][0] * rs, v1 = acc[ai][bj][m][1] * rs;
;                     u32x4 w; w.x = pk2(sigmoidf_(v0[0]), sigmoidf_(v0[1])); w.y = pk2(sigmoidf_(v0[2]), sigmoidf_(v0[3])); w.z = pk2(sigmoidf_(v1[0]), sigmoidf_(v1[1])); w.w = pk2(sigmoidf_(v1[2]), sigmoidf_(v1[3]));
;                     *(u32x4*)(D + (size_t)row * DM + col0 + bj * HALF) = w;
;                 }
	v_rcp_f32_e32 v50, v52
	s_nop 0
	v_cvt_pk_bf16_f32 v50, v50, v53
	v_rcp_f32_e32 v51, v55
	v_rcp_f32_e32 v52, v54
	s_nop 0
	v_cvt_pk_bf16_f32 v51, v52, v51
	global_store_dwordx4 v[60:61], v[48:51], off offset:256
	s_nop 0
	s_nop 0
	v_fmamk_f32 v48, v252, 0x3a800000, v172
	v_mul_f32_e32 v49, 0x4b800000, v48
	v_cmp_gt_f32_e32 vcc, s62, v48
	s_nop 1
	v_cndmask_b32_e32 v48, v48, v49, vcc
	v_rsq_f32_e32 v48, v48
	s_nop 0
	v_mul_f32_e32 v49, 0x45800000, v48
	v_cndmask_b32_e32 v48, v48, v49, vcc
	v_pk_mul_f32 v[44:45], v[44:45], v[48:49] op_sel_hi:[1,0]
	s_nop 0
	v_mul_f32_e32 v44, 0xbfb8aa3b, v44
	v_mul_f32_e32 v45, 0xbfb8aa3b, v45
	v_exp_f32_e32 v44, v44
	v_exp_f32_e32 v45, v45
	s_nop 0
	v_pk_add_f32 v[44:45], v[44:45], 1.0 op_sel_hi:[1,0]
	s_nop 0
	v_pk_mul_f32 v[50:51], v[40:41], v[48:49] op_sel_hi:[1,0]
	v_pk_mul_f32 v[46:47], v[46:47], v[48:49] op_sel_hi:[1,0]
	v_pk_mul_f32 v[42:43], v[42:43], v[48:49] op_sel_hi:[1,0]
	v_rcp_f32_e32 v45, v45
	v_mul_f32_e32 v41, 0xbfb8aa3b, v47
	v_mul_f32_e32 v40, 0xbfb8aa3b, v46
	v_exp_f32_e32 v40, v40
	v_exp_f32_e32 v41, v41
	s_nop 0
	v_pk_add_f32 v[46:47], v[40:41], 1.0 op_sel_hi:[1,0]
	v_rcp_f32_e32 v40, v44
	s_nop 0
	v_cvt_pk_bf16_f32 v40, v40, v45
	v_mul_f32_e32 v45, 0xbfb8aa3b, v51
	v_mul_f32_e32 v44, 0xbfb8aa3b, v50
	v_exp_f32_e32 v44, v44
	v_exp_f32_e32 v45, v45
	v_rcp_f32_e32 v41, v47
	v_pk_add_f32 v[44:45], v[44:45], 1.0 op_sel_hi:[1,0]
	v_rcp_f32_e32 v46, v46
	s_nop 0
	v_cvt_pk_bf16_f32 v41, v46, v41
	v_rcp_f32_e32 v45, v45
	v_mul_f32_e32 v42, 0xbfb8aa3b, v42
	v_mul_f32_e32 v43, 0xbfb8aa3b, v43
	v_exp_f32_e32 v42, v42
	v_exp_f32_e32 v43, v43
	s_nop 0
	v_pk_add_f32 v[46:47], v[42:43], 1.0 op_sel_hi:[1,0]
	v_rcp_f32_e32 v42, v44
	s_nop 0
	v_cvt_pk_bf16_f32 v42, v42, v45
	v_rcp_f32_e32 v43, v47
	s_mov_b64 s[0:1], 0x48000
	v_pk_mul_f32 v[36:37], v[36:37], v[48:49] op_sel_hi:[1,0]
	v_mul_f32_e32 v36, 0xbfb8aa3b, v36
	v_mul_f32_e32 v37, 0xbfb8aa3b, v37
	v_exp_f32_e32 v36, v36
	v_exp_f32_e32 v37, v37
	v_rcp_f32_e32 v44, v46
	s_nop 0
	v_cvt_pk_bf16_f32 v43, v44, v43
	v_lshl_add_u64 v[44:45], v[116:117], 0, s[0:1]
	s_mov_b32 s0, 0x48000
	v_add_co_u32_e32 v46, vcc, s0, v116
	v_pk_add_f32 v[36:37], v[36:37], 1.0 op_sel_hi:[1,0]
	s_nop 0
	v_addc_co_u32_e32 v47, vcc, 0, v117, vcc
	global_store_dwordx4 v[46:47], v[40:43], off
	v_pk_mul_f32 v[38:39], v[38:39], v[48:49] op_sel_hi:[1,0]
	v_pk_mul_f32 v[34:35], v[34:35], v[48:49] op_sel_hi:[1,0]
	v_pk_mul_f32 v[40:41], v[32:33], v[48:49] op_sel_hi:[1,0]
	v_mul_f32_e32 v34, 0xbfb8aa3b, v34
	v_mul_f32_e32 v35, 0xbfb8aa3b, v35
	v_rcp_f32_e32 v37, v37
	v_mul_f32_e32 v33, 0xbfb8aa3b, v39
	v_mul_f32_e32 v32, 0xbfb8aa3b, v38
	v_exp_f32_e32 v32, v32
	v_exp_f32_e32 v33, v33
	s_nop 0
	v_pk_add_f32 v[38:39], v[32:33], 1.0 op_sel_hi:[1,0]
	v_rcp_f32_e32 v32, v36
	s_nop 0
	v_cvt_pk_bf16_f32 v32, v32, v37
	v_mul_f32_e32 v37, 0xbfb8aa3b, v41
	v_mul_f32_e32 v36, 0xbfb8aa3b, v40
	v_exp_f32_e32 v36, v36
	v_exp_f32_e32 v37, v37
	v_rcp_f32_e32 v33, v39
	v_pk_add_f32 v[36:37], v[36:37], 1.0 op_sel_hi:[1,0]
	v_rcp_f32_e32 v38, v38
	s_nop 0
	v_cvt_pk_bf16_f32 v33, v38, v33
	v_rcp_f32_e32 v37, v37
	v_exp_f32_e32 v34, v34
	v_exp_f32_e32 v35, v35
	s_nop 0
	v_pk_add_f32 v[38:39], v[34:35], 1.0 op_sel_hi:[1,0]
	v_rcp_f32_e32 v34, v36
	s_nop 0
	v_cvt_pk_bf16_f32 v34, v34, v37
	v_rcp_f32_e32 v35, v39
	v_rcp_f32_e32 v36, v38
	s_nop 0
	v_cvt_pk_bf16_f32 v35, v36, v35
	global_store_dwordx4 v[44:45], v[32:35], off offset:256
	s_nop 0
	s_nop 0
	v_fmamk_f32 v32, v253, 0x3a800000, v172
	v_mul_f32_e32 v33, 0x4b800000, v32
	v_cmp_gt_f32_e32 vcc, s62, v32
	s_nop 1
	v_cndmask_b32_e32 v32, v32, v33, vcc
	v_rsq_f32_e32 v32, v32
	s_nop 0
	v_mul_f32_e32 v33, 0x45800000, v32
	v_cndmask_b32_e32 v32, v32, v33, vcc
	v_pk_mul_f32 v[28:29], v[28:29], v[32:33] op_sel_hi:[1,0]
	s_nop 0
	v_mul_f32_e32 v28, 0xbfb8aa3b, v28
	v_mul_f32_e32 v29, 0xbfb8aa3b, v29
	v_exp_f32_e32 v28, v28
	v_exp_f32_e32 v29, v29
	s_nop 0
	v_pk_add_f32 v[28:29], v[28:29], 1.0 op_sel_hi:[1,0]
	s_nop 0
	v_pk_mul_f32 v[34:35], v[24:25], v[32:33] op_sel_hi:[1,0]
	v_pk_mul_f32 v[30:31], v[30:31], v[32:33] op_sel_hi:[1,0]
	v_pk_mul_f32 v[26:27], v[26:27], v[32:33] op_sel_hi:[1,0]
	v_rcp_f32_e32 v29, v29
	v_mul_f32_e32 v25, 0xbfb8aa3b, v31
	v_mul_f32_e32 v24, 0xbfb8aa3b, v30
	v_exp_f32_e32 v24, v24
	v_exp_f32_e32 v25, v25
	s_nop 0
	v_pk_add_f32 v[30:31], v[24:25], 1.0 op_sel_hi:[1,0]
	v_rcp_f32_e32 v24, v28
	s_nop 0
	v_cvt_pk_bf16_f32 v24, v24, v29
	v_mul_f32_e32 v29, 0xbfb8aa3b, v35
	v_mul_f32_e32 v28, 0xbfb8aa3b, v34
	v_exp_f32_e32 v28, v28
	v_exp_f32_e32 v29, v29
	v_rcp_f32_e32 v25, v31
	v_pk_add_f32 v[28:29], v[28:29], 1.0 op_sel_hi:[1,0]
	v_rcp_f32_e32 v30, v30
	s_nop 0
	v_cvt_pk_bf16_f32 v25, v30, v25
	v_rcp_f32_e32 v29, v29
	v_mul_f32_e32 v26, 0xbfb8aa3b, v26
	v_mul_f32_e32 v27, 0xbfb8aa3b, v27
	v_exp_f32_e32 v26, v26
	v_exp_f32_e32 v27, v27
	s_nop 0
	v_pk_add_f32 v[30:31], v[26:27], 1.0 op_sel_hi:[1,0]
	v_rcp_f32_e32 v26, v28
; DI unsigned pk2(float lo, float hi) { f32x2_t v = {lo, hi}; bf16x2_t b = __builtin_convertvector(v, bf16x2_t); return __builtin_bit_cast(unsigned, b); }
; DI float sigmoidf_(float x) { return 1.0f / (1.0f + __expf(-x)); }
;     DI void operator()(AccRef acc, const Unit& u, int wr, int wc, int fr, int fq) const {
;     ...
;             for (int m = 0; m < 4; ++m) {
;                 const int row = row0 + ai * HALF + m * 16; const float rs = rsqrtf(SS0[row] * (1.0f / DM) + EPSN);
; #pragma unroll
;                 for (int bj = 0; bj < 2; ++bj) {
;                     const f32x4 v0 = acc[ai][bj][m][0] * rs, v1 = acc[ai][bj][m][1] * rs;
;                     u32x4 w; w.x = pk2(sigmoidf_(v0[0]), sigmoidf_(v0[1])); w.y = pk2(sigmoidf_(v0[2]), sigmoidf_(v0[3])); w.z = pk2(sigmoidf_(v1[0]), sigmoidf_(v1[1])); w.w = pk2(sigmoidf_(v1[2]), sigmoidf_(v1[3]));
;                     *(u32x4*)(D + (size_t)row * DM + col0 + bj * HALF) = w;
;                 }
	s_nop 0
	v_cvt_pk_bf16_f32 v26, v26, v29
	v_rcp_f32_e32 v27, v31
	v_pk_mul_f32 v[20:21], v[20:21], v[32:33] op_sel_hi:[1,0]
	v_mul_f32_e32 v20, 0xbfb8aa3b, v20
	v_mul_f32_e32 v21, 0xbfb8aa3b, v21
	v_exp_f32_e32 v20, v20
	v_exp_f32_e32 v21, v21
	v_rcp_f32_e32 v28, v30
	v_add_co_u32_e32 v30, vcc, s63, v116
	v_cvt_pk_bf16_f32 v27, v28, v27
	s_nop 0
	v_addc_co_u32_e32 v31, vcc, 0, v117, vcc
	v_pk_add_f32 v[20:21], v[20:21], 1.0 op_sel_hi:[1,0]
	global_store_dwordx4 v[30:31], v[24:27], off
	v_pk_mul_f32 v[22:23], v[22:23], v[32:33] op_sel_hi:[1,0]
	v_pk_mul_f32 v[18:19], v[18:19], v[32:33] op_sel_hi:[1,0]
	v_pk_mul_f32 v[24:25], v[16:17], v[32:33] op_sel_hi:[1,0]
	v_mul_f32_e32 v18, 0xbfb8aa3b, v18
	v_mul_f32_e32 v19, 0xbfb8aa3b, v19
	v_rcp_f32_e32 v21, v21
	v_mul_f32_e32 v17, 0xbfb8aa3b, v23
	v_mul_f32_e32 v16, 0xbfb8aa3b, v22
	v_exp_f32_e32 v16, v16
	v_exp_f32_e32 v17, v17
	s_nop 0
	v_pk_add_f32 v[22:23], v[16:17], 1.0 op_sel_hi:[1,0]
	v_rcp_f32_e32 v16, v20
	s_nop 0
	v_cvt_pk_bf16_f32 v16, v16, v21
	v_mul_f32_e32 v21, 0xbfb8aa3b, v25
	v_mul_f32_e32 v20, 0xbfb8aa3b, v24
	v_exp_f32_e32 v20, v20
	v_exp_f32_e32 v21, v21
	v_rcp_f32_e32 v17, v23
	v_pk_add_f32 v[20:21], v[20:21], 1.0 op_sel_hi:[1,0]
	v_rcp_f32_e32 v22, v22
	s_nop 0
	v_cvt_pk_bf16_f32 v17, v22, v17
	v_rcp_f32_e32 v21, v21
	v_exp_f32_e32 v18, v18
	v_exp_f32_e32 v19, v19
	s_nop 0
	v_pk_add_f32 v[22:23], v[18:19], 1.0 op_sel_hi:[1,0]
	v_rcp_f32_e32 v18, v20
	s_nop 0
	v_cvt_pk_bf16_f32 v18, v18, v21
	v_lshl_add_u64 v[28:29], v[116:117], 0, s[22:23]
	v_rcp_f32_e32 v19, v23
	v_rcp_f32_e32 v20, v22
	s_nop 0
	v_cvt_pk_bf16_f32 v19, v20, v19
	global_store_dwordx4 v[28:29], v[16:19], off offset:256
	s_nop 0
	s_nop 0
	v_fmamk_f32 v16, v254, 0x3a800000, v172
	v_mul_f32_e32 v17, 0x4b800000, v16
	v_cmp_gt_f32_e32 vcc, s62, v16
	s_nop 1
	v_cndmask_b32_e32 v16, v16, v17, vcc
	v_rsq_f32_e32 v16, v16
	s_nop 0
	v_mul_f32_e32 v17, 0x45800000, v16
	v_cndmask_b32_e32 v16, v16, v17, vcc
	v_pk_mul_f32 v[12:13], v[12:13], v[16:17] op_sel_hi:[1,0]
	s_nop 0
	v_mul_f32_e32 v12, 0xbfb8aa3b, v12
	v_mul_f32_e32 v13, 0xbfb8aa3b, v13
	v_exp_f32_e32 v12, v12
	v_exp_f32_e32 v13, v13
	s_nop 0
	v_pk_add_f32 v[12:13], v[12:13], 1.0 op_sel_hi:[1,0]
	s_nop 0
	v_pk_mul_f32 v[18:19], v[8:9], v[16:17] op_sel_hi:[1,0]
	v_pk_mul_f32 v[14:15], v[14:15], v[16:17] op_sel_hi:[1,0]
	v_pk_mul_f32 v[10:11], v[10:11], v[16:17] op_sel_hi:[1,0]
	v_rcp_f32_e32 v13, v13
	v_mul_f32_e32 v9, 0xbfb8aa3b, v15
	v_mul_f32_e32 v8, 0xbfb8aa3b, v14
	v_exp_f32_e32 v8, v8
	v_exp_f32_e32 v9, v9
	s_nop 0
	v_pk_add_f32 v[14:15], v[8:9], 1.0 op_sel_hi:[1,0]
	v_rcp_f32_e32 v8, v12
	s_nop 0
	v_cvt_pk_bf16_f32 v8, v8, v13
	v_mul_f32_e32 v13, 0xbfb8aa3b, v19
	v_mul_f32_e32 v12, 0xbfb8aa3b, v18
	v_exp_f32_e32 v12, v12
	v_exp_f32_e32 v13, v13
	v_rcp_f32_e32 v9, v15
	v_pk_add_f32 v[12:13], v[12:13], 1.0 op_sel_hi:[1,0]
	v_rcp_f32_e32 v14, v14
	s_nop 0
	v_cvt_pk_bf16_f32 v9, v14, v9
	v_rcp_f32_e32 v13, v13
	v_mul_f32_e32 v10, 0xbfb8aa3b, v10
	v_mul_f32_e32 v11, 0xbfb8aa3b, v11
	v_exp_f32_e32 v10, v10
	v_exp_f32_e32 v11, v11
	s_nop 0
	v_pk_add_f32 v[14:15], v[10:11], 1.0 op_sel_hi:[1,0]
	v_rcp_f32_e32 v10, v12
	s_nop 0
	v_cvt_pk_bf16_f32 v10, v10, v13
	v_rcp_f32_e32 v11, v15
	v_pk_mul_f32 v[4:5], v[4:5], v[16:17] op_sel_hi:[1,0]
	v_mul_f32_e32 v4, 0xbfb8aa3b, v4
	v_mul_f32_e32 v5, 0xbfb8aa3b, v5
	v_exp_f32_e32 v4, v4
	v_exp_f32_e32 v5, v5
	v_rcp_f32_e32 v12, v14
	v_add_co_u32_e32 v14, vcc, s68, v116
	v_cvt_pk_bf16_f32 v11, v12, v11
	s_nop 0
	v_addc_co_u32_e32 v15, vcc, 0, v117, vcc
	v_pk_add_f32 v[4:5], v[4:5], 1.0 op_sel_hi:[1,0]
	global_store_dwordx4 v[14:15], v[8:11], off
	v_pk_mul_f32 v[6:7], v[6:7], v[16:17] op_sel_hi:[1,0]
	v_pk_mul_f32 v[2:3], v[2:3], v[16:17] op_sel_hi:[1,0]
	v_pk_mul_f32 v[8:9], v[0:1], v[16:17] op_sel_hi:[1,0]
	v_mul_f32_e32 v2, 0xbfb8aa3b, v2
	v_mul_f32_e32 v3, 0xbfb8aa3b, v3
	v_rcp_f32_e32 v5, v5
	v_mul_f32_e32 v1, 0xbfb8aa3b, v7
	v_mul_f32_e32 v0, 0xbfb8aa3b, v6
	v_exp_f32_e32 v0, v0
	v_exp_f32_e32 v1, v1
	s_nop 0
	v_pk_add_f32 v[6:7], v[0:1], 1.0 op_sel_hi:[1,0]
	v_rcp_f32_e32 v0, v4
	s_nop 0
	v_cvt_pk_bf16_f32 v0, v0, v5
	v_mul_f32_e32 v5, 0xbfb8aa3b, v9
	v_mul_f32_e32 v4, 0xbfb8aa3b, v8
	v_exp_f32_e32 v4, v4
	v_exp_f32_e32 v5, v5
	v_rcp_f32_e32 v1, v7
	v_pk_add_f32 v[4:5], v[4:5], 1.0 op_sel_hi:[1,0]
	v_rcp_f32_e32 v6, v6
	s_nop 0
	v_cvt_pk_bf16_f32 v1, v6, v1
	v_rcp_f32_e32 v5, v5
	v_exp_f32_e32 v2, v2
	v_exp_f32_e32 v3, v3
	s_nop 0
	v_pk_add_f32 v[6:7], v[2:3], 1.0 op_sel_hi:[1,0]
	v_rcp_f32_e32 v2, v4
	s_nop 0
	v_cvt_pk_bf16_f32 v2, v2, v5
	v_lshl_add_u64 v[12:13], v[116:117], 0, s[24:25]
	v_rcp_f32_e32 v3, v7
	s_mov_b64 s[0:1], -1
	v_rcp_f32_e32 v4, v6
	s_nop 0
	v_cvt_pk_bf16_f32 v3, v4, v3
	s_andn2_b64 vcc, exec, s[2:3]
	global_store_dwordx4 v[12:13], v[0:3], off offset:256
	s_cbranch_vccnz .LBB0_1239
	s_andn2_b64 vcc, exec, s[16:17]
	s_cbranch_vccnz .LBB0_1238
	s_barrier
	s_branch .LBB0_1238

; DI unsigned pk2(float lo, float hi) { f32x2_t v = {lo, hi}; bf16x2_t b = __builtin_convertvector(v, bf16x2_t); return __builtin_bit_cast(unsigned, b); }
; DI float sigmoidf_(float x) { return 1.0f / (1.0f + __expf(-x)); }
;     DI void operator()(AccRef acc, const Unit& u, int wr, int wc, int fr, int fq) const {
;     ...
;             for (int m = 0; m < 4; ++m) {
;                 const int row = row0 + ai * HALF + m * 16; const float rs = rsqrtf(SS0[row] * (1.0f / DM) + EPSN);
; #pragma unroll
;                 for (int bj = 0; bj < 2; ++bj) {
;                     const f32x4 v0 = acc[ai][bj][m][0] * rs, v1 = acc[ai][bj][m][1] * rs;
;                     u32x4 w; w.x = pk2(sigmoidf_(v0[0]), sigmoidf_(v0[1])); w.y = pk2(sigmoidf_(v0[2]), sigmoidf_(v0[3])); w.z = pk2(sigmoidf_(v1[0]), sigmoidf_(v1[1])); w.w = pk2(sigmoidf_(v1[2]), sigmoidf_(v1[3]));
;                     *(u32x4*)(D + (size_t)row * DM + col0 + bj * HALF) = w;
;                 }
.LBB0_1298:
	v_lshl_add_u32 v158, s0, 8, v137
	v_ashrrev_i32_e32 v159, 31, v158
	v_lshl_add_u64 v[156:157], v[158:159], 2, s[82:83]
	global_load_dword v160, v[156:157], off
	global_load_dword v248, v[156:157], off offset:64
	global_load_dword v249, v[156:157], off offset:128
	global_load_dword v250, v[156:157], off offset:192
	global_load_dword v251, v[156:157], off offset:512
	global_load_dword v252, v[156:157], off offset:576
	global_load_dword v253, v[156:157], off offset:640
	global_load_dword v254, v[156:157], off offset:704
	v_lshlrev_b64 v[172:173], 11, v[158:159]
	s_waitcnt vmcnt(0)
	v_fmamk_f32 v160, v160, 0x3a800000, v171
	v_mul_f32_e32 v162, 0x4b800000, v160
	v_cmp_gt_f32_e32 vcc, s60, v160
	s_nop 1
	v_cndmask_b32_e32 v160, v160, v162, vcc
	v_rsq_f32_e32 v160, v160
	v_lshl_or_b32 v162, s1, 8, v141
	v_ashrrev_i32_e32 v163, 31, v162
	v_mul_f32_e32 v159, 0x45800000, v160
	v_cndmask_b32_e32 v160, v160, v159, vcc
	v_pk_mul_f32 v[124:125], v[124:125], v[160:161] op_sel_hi:[1,0]
	v_pk_mul_f32 v[126:127], v[126:127], v[160:161] op_sel_hi:[1,0]
	v_pk_mul_f32 v[120:121], v[120:121], v[160:161] op_sel_hi:[1,0]
	v_mul_f32_e32 v124, 0xbfb8aa3b, v124
	v_mul_f32_e32 v125, 0xbfb8aa3b, v125
	v_pk_mul_f32 v[122:123], v[122:123], v[160:161] op_sel_hi:[1,0]
	v_mul_f32_e32 v126, 0xbfb8aa3b, v126
	v_mul_f32_e32 v127, 0xbfb8aa3b, v127
	v_mul_f32_e32 v159, 0xbfb8aa3b, v120
	v_mul_f32_e32 v174, 0xbfb8aa3b, v121
	v_exp_f32_e32 v120, v124
	v_exp_f32_e32 v121, v125
	v_mul_f32_e32 v175, 0xbfb8aa3b, v122
	v_mul_f32_e32 v176, 0xbfb8aa3b, v123
	v_exp_f32_e32 v122, v126
	v_exp_f32_e32 v123, v127
	v_exp_f32_e32 v124, v159
	v_exp_f32_e32 v125, v174
	v_pk_add_f32 v[120:121], v[120:121], 1.0 op_sel_hi:[1,0]
	v_exp_f32_e32 v126, v175
	v_pk_add_f32 v[174:175], v[122:123], 1.0 op_sel_hi:[1,0]
	v_pk_add_f32 v[124:125], v[124:125], 1.0 op_sel_hi:[1,0]
	v_rcp_f32_e32 v121, v121
	v_rcp_f32_e32 v120, v120
	s_nop 0
	v_cvt_pk_bf16_f32 v122, v120, v121
	v_rcp_f32_e32 v125, v125
	v_exp_f32_e32 v127, v176
	v_rcp_f32_e32 v120, v175
	v_rcp_f32_e32 v121, v174
	s_nop 0
	v_cvt_pk_bf16_f32 v123, v121, v120
	v_pk_add_f32 v[120:121], v[126:127], 1.0 op_sel_hi:[1,0]
	v_rcp_f32_e32 v124, v124
	s_nop 0
	v_cvt_pk_bf16_f32 v124, v124, v125
	v_rcp_f32_e32 v121, v121
	v_pk_mul_f32 v[116:117], v[116:117], v[160:161] op_sel_hi:[1,0]
	v_mul_f32_e32 v116, 0xbfb8aa3b, v116
	v_lshl_add_u64 v[126:127], s[80:81], 0, v[172:173]
	v_exp_f32_e32 v172, v116
	v_mul_f32_e32 v116, 0xbfb8aa3b, v117
	v_exp_f32_e32 v173, v116
	v_rcp_f32_e32 v120, v120
	s_nop 0
	v_cvt_pk_bf16_f32 v125, v120, v121
	v_lshlrev_b64 v[120:121], 1, v[162:163]
	v_lshl_add_u64 v[116:117], v[126:127], 0, v[120:121]
	global_store_dwordx4 v[116:117], v[122:125], off
	v_pk_mul_f32 v[118:119], v[118:119], v[160:161] op_sel_hi:[1,0]
	v_pk_mul_f32 v[114:115], v[114:115], v[160:161] op_sel_hi:[1,0]
	v_pk_add_f32 v[122:123], v[172:173], 1.0 op_sel_hi:[1,0]
	v_pk_mul_f32 v[124:125], v[112:113], v[160:161] op_sel_hi:[1,0]
	v_mul_f32_e32 v114, 0xbfb8aa3b, v114
	v_mul_f32_e32 v115, 0xbfb8aa3b, v115
	v_exp_f32_e32 v114, v114
	v_rcp_f32_e32 v123, v123
	v_mul_f32_e32 v113, 0xbfb8aa3b, v119
	v_mul_f32_e32 v112, 0xbfb8aa3b, v118
	v_exp_f32_e32 v112, v112
	v_exp_f32_e32 v113, v113
	s_nop 0
	v_pk_add_f32 v[118:119], v[112:113], 1.0 op_sel_hi:[1,0]
	v_rcp_f32_e32 v112, v122
	s_nop 0
	v_cvt_pk_bf16_f32 v112, v112, v123
	v_mul_f32_e32 v122, 0xbfb8aa3b, v124
	v_mul_f32_e32 v123, 0xbfb8aa3b, v125
	v_exp_f32_e32 v122, v122
	v_exp_f32_e32 v123, v123
	v_rcp_f32_e32 v113, v119
	v_pk_add_f32 v[122:123], v[122:123], 1.0 op_sel_hi:[1,0]
	v_rcp_f32_e32 v118, v118
	s_nop 0
	v_cvt_pk_bf16_f32 v113, v118, v113
	v_rcp_f32_e32 v123, v123
	v_exp_f32_e32 v115, v115
	s_nop 0
	v_pk_add_f32 v[118:119], v[114:115], 1.0 op_sel_hi:[1,0]
	v_rcp_f32_e32 v114, v122
	s_nop 0
	v_cvt_pk_bf16_f32 v114, v114, v123
	v_rcp_f32_e32 v115, v119
	v_rcp_f32_e32 v118, v118
	s_nop 0
	v_cvt_pk_bf16_f32 v115, v118, v115
	global_store_dwordx4 v[116:117], v[112:115], off offset:256
	s_nop 0
	s_nop 0
	v_or_b32_e32 v114, 16, v158
	v_ashrrev_i32_e32 v115, 31, v114
	v_lshlrev_b64 v[114:115], 11, v[114:115]
	s_nop 0
	v_fmamk_f32 v112, v248, 0x3a800000, v171
	v_mul_f32_e32 v113, 0x4b800000, v112
	v_cmp_gt_f32_e32 vcc, s60, v112
	s_nop 1
	v_cndmask_b32_e32 v112, v112, v113, vcc
	v_rsq_f32_e32 v112, v112
	s_nop 0
	v_mul_f32_e32 v113, 0x45800000, v112
	v_cndmask_b32_e32 v112, v112, v113, vcc
	v_pk_mul_f32 v[108:109], v[108:109], v[112:113] op_sel_hi:[1,0]
	s_nop 0
	v_mul_f32_e32 v108, 0xbfb8aa3b, v108
	v_mul_f32_e32 v109, 0xbfb8aa3b, v109
	v_exp_f32_e32 v108, v108
	v_exp_f32_e32 v109, v109
	s_nop 0
	v_pk_add_f32 v[108:109], v[108:109], 1.0 op_sel_hi:[1,0]
	s_nop 0
	v_pk_mul_f32 v[118:119], v[104:105], v[112:113] op_sel_hi:[1,0]
	v_pk_mul_f32 v[110:111], v[110:111], v[112:113] op_sel_hi:[1,0]
	v_pk_mul_f32 v[106:107], v[106:107], v[112:113] op_sel_hi:[1,0]
	v_rcp_f32_e32 v109, v109
	v_mul_f32_e32 v105, 0xbfb8aa3b, v111
	v_mul_f32_e32 v104, 0xbfb8aa3b, v110
	v_exp_f32_e32 v104, v104
	v_exp_f32_e32 v105, v105
	s_nop 0
	v_pk_add_f32 v[110:111], v[104:105], 1.0 op_sel_hi:[1,0]
	v_rcp_f32_e32 v104, v108
	s_nop 0
	v_cvt_pk_bf16_f32 v104, v104, v109
	v_mul_f32_e32 v109, 0xbfb8aa3b, v119
	v_mul_f32_e32 v108, 0xbfb8aa3b, v118
	v_exp_f32_e32 v108, v108
	v_exp_f32_e32 v109, v109
	v_rcp_f32_e32 v105, v111
	v_pk_add_f32 v[108:109], v[108:109], 1.0 op_sel_hi:[1,0]
	v_rcp_f32_e32 v110, v110
	s_nop 0
	v_cvt_pk_bf16_f32 v105, v110, v105
	v_rcp_f32_e32 v109, v109
	v_mul_f32_e32 v106, 0xbfb8aa3b, v106
	v_mul_f32_e32 v107, 0xbfb8aa3b, v107
	v_exp_f32_e32 v106, v106
	v_exp_f32_e32 v107, v107
	s_nop 0
; DI unsigned pk2(float lo, float hi) { f32x2_t v = {lo, hi}; bf16x2_t b = __builtin_convertvector(v, bf16x2_t); return __builtin_bit_cast(unsigned, b); }
; DI float sigmoidf_(float x) { return 1.0f / (1.0f + __expf(-x)); }
;     DI void operator()(AccRef acc, const Unit& u, int wr, int wc, int fr, int fq) const {
;     ...
;             for (int m = 0; m < 4; ++m) {
;                 const int row = row0 + ai * HALF + m * 16; const float rs = rsqrtf(SS0[row] * (1.0f / DM) + EPSN);
; #pragma unroll
;                 for (int bj = 0; bj < 2; ++bj) {
;                     const f32x4 v0 = acc[ai][bj][m][0] * rs, v1 = acc[ai][bj][m][1] * rs;
;                     u32x4 w; w.x = pk2(sigmoidf_(v0[0]), sigmoidf_(v0[1])); w.y = pk2(sigmoidf_(v0[2]), sigmoidf_(v0[3])); w.z = pk2(sigmoidf_(v1[0]), sigmoidf_(v1[1])); w.w = pk2(sigmoidf_(v1[2]), sigmoidf_(v1[3]));
;                     *(u32x4*)(D + (size_t)row * DM + col0 + bj * HALF) = w;
;                 }
	v_pk_add_f32 v[110:111], v[106:107], 1.0 op_sel_hi:[1,0]
	v_rcp_f32_e32 v106, v108
	s_nop 0
	v_cvt_pk_bf16_f32 v106, v106, v109
	v_rcp_f32_e32 v107, v111
	v_pk_mul_f32 v[100:101], v[100:101], v[112:113] op_sel_hi:[1,0]
	v_mul_f32_e32 v100, 0xbfb8aa3b, v100
	v_mul_f32_e32 v101, 0xbfb8aa3b, v101
	v_exp_f32_e32 v100, v100
	v_exp_f32_e32 v101, v101
	v_rcp_f32_e32 v108, v110
	s_nop 0
	v_cvt_pk_bf16_f32 v107, v108, v107
	v_lshl_add_u64 v[108:109], s[80:81], 0, v[114:115]
	v_lshl_add_u64 v[108:109], v[108:109], 0, v[120:121]
	v_pk_add_f32 v[100:101], v[100:101], 1.0 op_sel_hi:[1,0]
	global_store_dwordx4 v[108:109], v[104:107], off
	v_pk_mul_f32 v[102:103], v[102:103], v[112:113] op_sel_hi:[1,0]
	v_pk_mul_f32 v[98:99], v[98:99], v[112:113] op_sel_hi:[1,0]
	v_pk_mul_f32 v[104:105], v[96:97], v[112:113] op_sel_hi:[1,0]
	v_mul_f32_e32 v98, 0xbfb8aa3b, v98
	v_mul_f32_e32 v99, 0xbfb8aa3b, v99
	v_rcp_f32_e32 v101, v101
	v_mul_f32_e32 v97, 0xbfb8aa3b, v103
	v_mul_f32_e32 v96, 0xbfb8aa3b, v102
	v_exp_f32_e32 v96, v96
	v_exp_f32_e32 v97, v97
	s_nop 0
	v_pk_add_f32 v[102:103], v[96:97], 1.0 op_sel_hi:[1,0]
	v_rcp_f32_e32 v96, v100
	s_nop 0
	v_cvt_pk_bf16_f32 v96, v96, v101
	v_mul_f32_e32 v101, 0xbfb8aa3b, v105
	v_mul_f32_e32 v100, 0xbfb8aa3b, v104
	v_exp_f32_e32 v100, v100
	v_exp_f32_e32 v101, v101
	v_rcp_f32_e32 v97, v103
	v_pk_add_f32 v[100:101], v[100:101], 1.0 op_sel_hi:[1,0]
	v_rcp_f32_e32 v102, v102
	s_nop 0
	v_cvt_pk_bf16_f32 v97, v102, v97
	v_rcp_f32_e32 v101, v101
	v_exp_f32_e32 v98, v98
	v_exp_f32_e32 v99, v99
	s_nop 0
	v_pk_add_f32 v[102:103], v[98:99], 1.0 op_sel_hi:[1,0]
	v_rcp_f32_e32 v98, v100
	s_nop 0
	v_cvt_pk_bf16_f32 v98, v98, v101
	v_rcp_f32_e32 v99, v103
	v_rcp_f32_e32 v100, v102
	s_nop 0
	v_cvt_pk_bf16_f32 v99, v100, v99
	global_store_dwordx4 v[108:109], v[96:99], off offset:256
	s_nop 0
	s_nop 0
	v_or_b32_e32 v98, 32, v158
	v_ashrrev_i32_e32 v99, 31, v98
	v_lshlrev_b64 v[98:99], 11, v[98:99]
	s_nop 0
	v_fmamk_f32 v96, v249, 0x3a800000, v171
	v_mul_f32_e32 v97, 0x4b800000, v96
	v_cmp_gt_f32_e32 vcc, s60, v96
	s_nop 1
	v_cndmask_b32_e32 v96, v96, v97, vcc
	v_rsq_f32_e32 v96, v96
	s_nop 0
	v_mul_f32_e32 v97, 0x45800000, v96
	v_cndmask_b32_e32 v96, v96, v97, vcc
	v_pk_mul_f32 v[92:93], v[92:93], v[96:97] op_sel_hi:[1,0]
	s_nop 0
	v_mul_f32_e32 v92, 0xbfb8aa3b, v92
	v_mul_f32_e32 v93, 0xbfb8aa3b, v93
	v_exp_f32_e32 v92, v92
	v_exp_f32_e32 v93, v93
	s_nop 0
	v_pk_add_f32 v[92:93], v[92:93], 1.0 op_sel_hi:[1,0]
	s_nop 0
	v_pk_mul_f32 v[100:101], v[88:89], v[96:97] op_sel_hi:[1,0]
	v_pk_mul_f32 v[94:95], v[94:95], v[96:97] op_sel_hi:[1,0]
	v_pk_mul_f32 v[90:91], v[90:91], v[96:97] op_sel_hi:[1,0]
	v_rcp_f32_e32 v93, v93
	v_mul_f32_e32 v89, 0xbfb8aa3b, v95
	v_mul_f32_e32 v88, 0xbfb8aa3b, v94
	v_exp_f32_e32 v88, v88
	v_exp_f32_e32 v89, v89
	s_nop 0
	v_pk_add_f32 v[94:95], v[88:89], 1.0 op_sel_hi:[1,0]
	v_rcp_f32_e32 v88, v92
	s_nop 0
	v_cvt_pk_bf16_f32 v88, v88, v93
	v_mul_f32_e32 v93, 0xbfb8aa3b, v101
	v_mul_f32_e32 v92, 0xbfb8aa3b, v100
	v_exp_f32_e32 v92, v92
	v_exp_f32_e32 v93, v93
	v_rcp_f32_e32 v89, v95
	v_pk_add_f32 v[92:93], v[92:93], 1.0 op_sel_hi:[1,0]
	v_rcp_f32_e32 v94, v94
	s_nop 0
	v_cvt_pk_bf16_f32 v89, v94, v89
	v_rcp_f32_e32 v93, v93
	v_mul_f32_e32 v90, 0xbfb8aa3b, v90
	v_mul_f32_e32 v91, 0xbfb8aa3b, v91
	v_exp_f32_e32 v90, v90
	v_exp_f32_e32 v91, v91
	s_nop 0
	v_pk_add_f32 v[94:95], v[90:91], 1.0 op_sel_hi:[1,0]
	v_rcp_f32_e32 v90, v92
	s_nop 0
	v_cvt_pk_bf16_f32 v90, v90, v93
	v_rcp_f32_e32 v91, v95
	v_pk_mul_f32 v[84:85], v[84:85], v[96:97] op_sel_hi:[1,0]
	v_mul_f32_e32 v84, 0xbfb8aa3b, v84
	v_mul_f32_e32 v85, 0xbfb8aa3b, v85
	v_exp_f32_e32 v84, v84
	v_exp_f32_e32 v85, v85
	v_rcp_f32_e32 v92, v94
	s_nop 0
	v_cvt_pk_bf16_f32 v91, v92, v91
	v_lshl_add_u64 v[92:93], s[80:81], 0, v[98:99]
	v_lshl_add_u64 v[92:93], v[92:93], 0, v[120:121]
	v_pk_add_f32 v[84:85], v[84:85], 1.0 op_sel_hi:[1,0]
	global_store_dwordx4 v[92:93], v[88:91], off
	v_pk_mul_f32 v[86:87], v[86:87], v[96:97] op_sel_hi:[1,0]
	v_pk_mul_f32 v[82:83], v[82:83], v[96:97] op_sel_hi:[1,0]
	v_pk_mul_f32 v[88:89], v[80:81], v[96:97] op_sel_hi:[1,0]
	v_mul_f32_e32 v82, 0xbfb8aa3b, v82
	v_mul_f32_e32 v83, 0xbfb8aa3b, v83
	v_rcp_f32_e32 v85, v85
	v_mul_f32_e32 v81, 0xbfb8aa3b, v87
	v_mul_f32_e32 v80, 0xbfb8aa3b, v86
	v_exp_f32_e32 v80, v80
	v_exp_f32_e32 v81, v81
	s_nop 0
	v_pk_add_f32 v[86:87], v[80:81], 1.0 op_sel_hi:[1,0]
	v_rcp_f32_e32 v80, v84
	s_nop 0
	v_cvt_pk_bf16_f32 v80, v80, v85
	v_mul_f32_e32 v85, 0xbfb8aa3b, v89
	v_mul_f32_e32 v84, 0xbfb8aa3b, v88
	v_exp_f32_e32 v84, v84
	v_exp_f32_e32 v85, v85
	v_rcp_f32_e32 v81, v87
	v_pk_add_f32 v[84:85], v[84:85], 1.0 op_sel_hi:[1,0]
	v_rcp_f32_e32 v86, v86
	s_nop 0
	v_cvt_pk_bf16_f32 v81, v86, v81
	v_rcp_f32_e32 v85, v85
	v_exp_f32_e32 v82, v82
	v_exp_f32_e32 v83, v83
	s_nop 0
	v_pk_add_f32 v[86:87], v[82:83], 1.0 op_sel_hi:[1,0]
	v_rcp_f32_e32 v82, v84
	s_nop 0
	v_cvt_pk_bf16_f32 v82, v82, v85
	v_rcp_f32_e32 v83, v87
	v_rcp_f32_e32 v84, v86
	s_nop 0
	v_cvt_pk_bf16_f32 v83, v84, v83
	global_store_dwordx4 v[92:93], v[80:83], off offset:256
	s_nop 0
	s_nop 0
	v_or_b32_e32 v82, 48, v158
	v_ashrrev_i32_e32 v83, 31, v82
	v_lshlrev_b64 v[82:83], 11, v[82:83]
	s_nop 0
	v_fmamk_f32 v80, v250, 0x3a800000, v171
	v_mul_f32_e32 v81, 0x4b800000, v80
	v_cmp_gt_f32_e32 vcc, s60, v80
	s_nop 1
	v_cndmask_b32_e32 v80, v80, v81, vcc
	v_rsq_f32_e32 v80, v80
	s_nop 0
	v_mul_f32_e32 v81, 0x45800000, v80
	v_cndmask_b32_e32 v80, v80, v81, vcc
	v_pk_mul_f32 v[76:77], v[76:77], v[80:81] op_sel_hi:[1,0]
	s_nop 0
	v_mul_f32_e32 v76, 0xbfb8aa3b, v76
	v_mul_f32_e32 v77, 0xbfb8aa3b, v77
	v_exp_f32_e32 v76, v76
	v_exp_f32_e32 v77, v77
	s_nop 0
; DI unsigned pk2(float lo, float hi) { f32x2_t v = {lo, hi}; bf16x2_t b = __builtin_convertvector(v, bf16x2_t); return __builtin_bit_cast(unsigned, b); }
; DI float sigmoidf_(float x) { return 1.0f / (1.0f + __expf(-x)); }
;     DI void operator()(AccRef acc, const Unit& u, int wr, int wc, int fr, int fq) const {
;     ...
;             for (int m = 0; m < 4; ++m) {
;                 const int row = row0 + ai * HALF + m * 16; const float rs = rsqrtf(SS0[row] * (1.0f / DM) + EPSN);
; #pragma unroll
;                 for (int bj = 0; bj < 2; ++bj) {
;                     const f32x4 v0 = acc[ai][bj][m][0] * rs, v1 = acc[ai][bj][m][1] * rs;
;                     u32x4 w; w.x = pk2(sigmoidf_(v0[0]), sigmoidf_(v0[1])); w.y = pk2(sigmoidf_(v0[2]), sigmoidf_(v0[3])); w.z = pk2(sigmoidf_(v1[0]), sigmoidf_(v1[1])); w.w = pk2(sigmoidf_(v1[2]), sigmoidf_(v1[3]));
;                     *(u32x4*)(D + (size_t)row * DM + col0 + bj * HALF) = w;
;                 }
	v_pk_add_f32 v[76:77], v[76:77], 1.0 op_sel_hi:[1,0]
	s_nop 0
	v_pk_mul_f32 v[84:85], v[72:73], v[80:81] op_sel_hi:[1,0]
	v_pk_mul_f32 v[78:79], v[78:79], v[80:81] op_sel_hi:[1,0]
	v_pk_mul_f32 v[74:75], v[74:75], v[80:81] op_sel_hi:[1,0]
	v_rcp_f32_e32 v77, v77
	v_mul_f32_e32 v73, 0xbfb8aa3b, v79
	v_mul_f32_e32 v72, 0xbfb8aa3b, v78
	v_exp_f32_e32 v72, v72
	v_exp_f32_e32 v73, v73
	s_nop 0
	v_pk_add_f32 v[78:79], v[72:73], 1.0 op_sel_hi:[1,0]
	v_rcp_f32_e32 v72, v76
	s_nop 0
	v_cvt_pk_bf16_f32 v72, v72, v77
	v_mul_f32_e32 v77, 0xbfb8aa3b, v85
	v_mul_f32_e32 v76, 0xbfb8aa3b, v84
	v_exp_f32_e32 v76, v76
	v_exp_f32_e32 v77, v77
	v_rcp_f32_e32 v73, v79
	v_pk_add_f32 v[76:77], v[76:77], 1.0 op_sel_hi:[1,0]
	v_rcp_f32_e32 v78, v78
	s_nop 0
	v_cvt_pk_bf16_f32 v73, v78, v73
	v_rcp_f32_e32 v77, v77
	v_mul_f32_e32 v74, 0xbfb8aa3b, v74
	v_mul_f32_e32 v75, 0xbfb8aa3b, v75
	v_exp_f32_e32 v74, v74
	v_exp_f32_e32 v75, v75
	s_nop 0
	v_pk_add_f32 v[78:79], v[74:75], 1.0 op_sel_hi:[1,0]
	v_rcp_f32_e32 v74, v76
	s_nop 0
	v_cvt_pk_bf16_f32 v74, v74, v77
	v_rcp_f32_e32 v75, v79
	v_pk_mul_f32 v[68:69], v[68:69], v[80:81] op_sel_hi:[1,0]
	v_mul_f32_e32 v68, 0xbfb8aa3b, v68
	v_mul_f32_e32 v69, 0xbfb8aa3b, v69
	v_exp_f32_e32 v68, v68
	v_exp_f32_e32 v69, v69
	v_rcp_f32_e32 v76, v78
	s_nop 0
	v_cvt_pk_bf16_f32 v75, v76, v75
	v_lshl_add_u64 v[76:77], s[80:81], 0, v[82:83]
	v_lshl_add_u64 v[76:77], v[76:77], 0, v[120:121]
	v_pk_add_f32 v[68:69], v[68:69], 1.0 op_sel_hi:[1,0]
	global_store_dwordx4 v[76:77], v[72:75], off
	v_pk_mul_f32 v[70:71], v[70:71], v[80:81] op_sel_hi:[1,0]
	v_pk_mul_f32 v[66:67], v[66:67], v[80:81] op_sel_hi:[1,0]
	v_pk_mul_f32 v[72:73], v[64:65], v[80:81] op_sel_hi:[1,0]
	v_mul_f32_e32 v66, 0xbfb8aa3b, v66
	v_mul_f32_e32 v67, 0xbfb8aa3b, v67
	v_rcp_f32_e32 v69, v69
	v_mul_f32_e32 v65, 0xbfb8aa3b, v71
	v_mul_f32_e32 v64, 0xbfb8aa3b, v70
	v_exp_f32_e32 v64, v64
	v_exp_f32_e32 v65, v65
	s_nop 0
	v_pk_add_f32 v[70:71], v[64:65], 1.0 op_sel_hi:[1,0]
	v_rcp_f32_e32 v64, v68
	s_nop 0
	v_cvt_pk_bf16_f32 v64, v64, v69
	v_mul_f32_e32 v69, 0xbfb8aa3b, v73
	v_mul_f32_e32 v68, 0xbfb8aa3b, v72
	v_exp_f32_e32 v68, v68
	v_exp_f32_e32 v69, v69
	v_rcp_f32_e32 v65, v71
	v_pk_add_f32 v[68:69], v[68:69], 1.0 op_sel_hi:[1,0]
	v_rcp_f32_e32 v70, v70
	s_nop 0
	v_cvt_pk_bf16_f32 v65, v70, v65
	v_rcp_f32_e32 v69, v69
	v_exp_f32_e32 v66, v66
	v_exp_f32_e32 v67, v67
	s_nop 0
	v_pk_add_f32 v[70:71], v[66:67], 1.0 op_sel_hi:[1,0]
	v_rcp_f32_e32 v66, v68
	s_nop 0
	v_cvt_pk_bf16_f32 v66, v66, v69
	v_rcp_f32_e32 v67, v71
	v_rcp_f32_e32 v68, v70
	s_nop 0
	v_cvt_pk_bf16_f32 v67, v68, v67
	global_store_dwordx4 v[76:77], v[64:67], off offset:256
	s_nop 0
	s_nop 0
	v_fmamk_f32 v64, v251, 0x3a800000, v171
	v_mul_f32_e32 v65, 0x4b800000, v64
	v_cmp_gt_f32_e32 vcc, s60, v64
	s_nop 1
	v_cndmask_b32_e32 v64, v64, v65, vcc
	v_rsq_f32_e32 v64, v64
	s_nop 0
	v_mul_f32_e32 v65, 0x45800000, v64
	v_cndmask_b32_e32 v64, v64, v65, vcc
	v_pk_mul_f32 v[60:61], v[60:61], v[64:65] op_sel_hi:[1,0]
	s_nop 0
	v_mul_f32_e32 v60, 0xbfb8aa3b, v60
	v_mul_f32_e32 v61, 0xbfb8aa3b, v61
	v_exp_f32_e32 v60, v60
	v_exp_f32_e32 v61, v61
	s_nop 0
	v_pk_add_f32 v[60:61], v[60:61], 1.0 op_sel_hi:[1,0]
	s_nop 0
	v_pk_mul_f32 v[66:67], v[56:57], v[64:65] op_sel_hi:[1,0]
	v_pk_mul_f32 v[62:63], v[62:63], v[64:65] op_sel_hi:[1,0]
	v_pk_mul_f32 v[58:59], v[58:59], v[64:65] op_sel_hi:[1,0]
	v_rcp_f32_e32 v61, v61
	v_mul_f32_e32 v57, 0xbfb8aa3b, v63
	v_mul_f32_e32 v56, 0xbfb8aa3b, v62
	v_exp_f32_e32 v56, v56
	v_exp_f32_e32 v57, v57
	s_nop 0
	v_pk_add_f32 v[62:63], v[56:57], 1.0 op_sel_hi:[1,0]
	v_rcp_f32_e32 v56, v60
	s_nop 0
	v_cvt_pk_bf16_f32 v56, v56, v61
	v_mul_f32_e32 v61, 0xbfb8aa3b, v67
	v_mul_f32_e32 v60, 0xbfb8aa3b, v66
	v_exp_f32_e32 v60, v60
	v_exp_f32_e32 v61, v61
	v_rcp_f32_e32 v57, v63
	v_pk_add_f32 v[60:61], v[60:61], 1.0 op_sel_hi:[1,0]
	v_rcp_f32_e32 v62, v62
	s_nop 0
	v_cvt_pk_bf16_f32 v57, v62, v57
	v_rcp_f32_e32 v61, v61
	v_mul_f32_e32 v58, 0xbfb8aa3b, v58
	v_mul_f32_e32 v59, 0xbfb8aa3b, v59
	v_exp_f32_e32 v58, v58
	v_exp_f32_e32 v59, v59
	s_nop 0
	v_pk_add_f32 v[62:63], v[58:59], 1.0 op_sel_hi:[1,0]
	v_rcp_f32_e32 v58, v60
	s_nop 0
	v_cvt_pk_bf16_f32 v58, v58, v61
	v_rcp_f32_e32 v59, v63
	s_mov_b64 s[0:1], 0x40000
	v_pk_mul_f32 v[52:53], v[52:53], v[64:65] op_sel_hi:[1,0]
	v_mul_f32_e32 v52, 0xbfb8aa3b, v52
	v_mul_f32_e32 v53, 0xbfb8aa3b, v53
	v_exp_f32_e32 v52, v52
	v_exp_f32_e32 v53, v53
	v_rcp_f32_e32 v60, v62
	s_nop 0
	v_cvt_pk_bf16_f32 v59, v60, v59
	v_lshl_add_u64 v[60:61], v[116:117], 0, s[0:1]
	s_mov_b32 s0, 0x40000
	v_add_co_u32_e32 v62, vcc, s0, v116
	v_pk_add_f32 v[52:53], v[52:53], 1.0 op_sel_hi:[1,0]
	s_nop 0
	v_addc_co_u32_e32 v63, vcc, 0, v117, vcc
	global_store_dwordx4 v[62:63], v[56:59], off
	v_pk_mul_f32 v[54:55], v[54:55], v[64:65] op_sel_hi:[1,0]
	v_pk_mul_f32 v[50:51], v[50:51], v[64:65] op_sel_hi:[1,0]
	v_pk_mul_f32 v[56:57], v[48:49], v[64:65] op_sel_hi:[1,0]
	v_mul_f32_e32 v50, 0xbfb8aa3b, v50
	v_mul_f32_e32 v51, 0xbfb8aa3b, v51
	v_rcp_f32_e32 v53, v53
	v_mul_f32_e32 v49, 0xbfb8aa3b, v55
	v_mul_f32_e32 v48, 0xbfb8aa3b, v54
	v_exp_f32_e32 v48, v48
	v_exp_f32_e32 v49, v49
	s_nop 0
	v_pk_add_f32 v[54:55], v[48:49], 1.0 op_sel_hi:[1,0]
	v_rcp_f32_e32 v48, v52
	s_nop 0
	v_cvt_pk_bf16_f32 v48, v48, v53
	v_mul_f32_e32 v53, 0xbfb8aa3b, v57
	v_mul_f32_e32 v52, 0xbfb8aa3b, v56
	v_exp_f32_e32 v52, v52
	v_exp_f32_e32 v53, v53
	v_rcp_f32_e32 v49, v55
	v_pk_add_f32 v[52:53], v[52:53], 1.0 op_sel_hi:[1,0]
	v_rcp_f32_e32 v54, v54
	s_nop 0
	v_cvt_pk_bf16_f32 v49, v54, v49
	v_rcp_f32_e32 v53, v53
	v_exp_f32_e32 v50, v50
	v_exp_f32_e32 v51, v51
	s_nop 0
	v_pk_add_f32 v[54:55], v[50:51], 1.0 op_sel_hi:[1,0]
; DI unsigned pk2(float lo, float hi) { f32x2_t v = {lo, hi}; bf16x2_t b = __builtin_convertvector(v, bf16x2_t); return __builtin_bit_cast(unsigned, b); }
; DI float sigmoidf_(float x) { return 1.0f / (1.0f + __expf(-x)); }
;     DI void operator()(AccRef acc, const Unit& u, int wr, int wc, int fr, int fq) const {
;     ...
;             for (int m = 0; m < 4; ++m) {
;                 const int row = row0 + ai * HALF + m * 16; const float rs = rsqrtf(SS0[row] * (1.0f / DM) + EPSN);
; #pragma unroll
;                 for (int bj = 0; bj < 2; ++bj) {
;                     const f32x4 v0 = acc[ai][bj][m][0] * rs, v1 = acc[ai][bj][m][1] * rs;
;                     u32x4 w; w.x = pk2(sigmoidf_(v0[0]), sigmoidf_(v0[1])); w.y = pk2(sigmoidf_(v0[2]), sigmoidf_(v0[3])); w.z = pk2(sigmoidf_(v1[0]), sigmoidf_(v1[1])); w.w = pk2(sigmoidf_(v1[2]), sigmoidf_(v1[3]));
;                     *(u32x4*)(D + (size_t)row * DM + col0 + bj * HALF) = w;
;                 }
	v_rcp_f32_e32 v50, v52
	s_nop 0
	v_cvt_pk_bf16_f32 v50, v50, v53
	v_rcp_f32_e32 v51, v55
	v_rcp_f32_e32 v52, v54
	s_nop 0
	v_cvt_pk_bf16_f32 v51, v52, v51
	global_store_dwordx4 v[60:61], v[48:51], off offset:256
	s_nop 0
	s_nop 0
	v_fmamk_f32 v48, v252, 0x3a800000, v171
	v_mul_f32_e32 v49, 0x4b800000, v48
	v_cmp_gt_f32_e32 vcc, s60, v48
	s_nop 1
	v_cndmask_b32_e32 v48, v48, v49, vcc
	v_rsq_f32_e32 v48, v48
	s_nop 0
	v_mul_f32_e32 v49, 0x45800000, v48
	v_cndmask_b32_e32 v48, v48, v49, vcc
	v_pk_mul_f32 v[44:45], v[44:45], v[48:49] op_sel_hi:[1,0]
	s_nop 0
	v_mul_f32_e32 v44, 0xbfb8aa3b, v44
	v_mul_f32_e32 v45, 0xbfb8aa3b, v45
	v_exp_f32_e32 v44, v44
	v_exp_f32_e32 v45, v45
	s_nop 0
	v_pk_add_f32 v[44:45], v[44:45], 1.0 op_sel_hi:[1,0]
	s_nop 0
	v_pk_mul_f32 v[50:51], v[40:41], v[48:49] op_sel_hi:[1,0]
	v_pk_mul_f32 v[46:47], v[46:47], v[48:49] op_sel_hi:[1,0]
	v_pk_mul_f32 v[42:43], v[42:43], v[48:49] op_sel_hi:[1,0]
	v_rcp_f32_e32 v45, v45
	v_mul_f32_e32 v41, 0xbfb8aa3b, v47
	v_mul_f32_e32 v40, 0xbfb8aa3b, v46
	v_exp_f32_e32 v40, v40
	v_exp_f32_e32 v41, v41
	s_nop 0
	v_pk_add_f32 v[46:47], v[40:41], 1.0 op_sel_hi:[1,0]
	v_rcp_f32_e32 v40, v44
	s_nop 0
	v_cvt_pk_bf16_f32 v40, v40, v45
	v_mul_f32_e32 v45, 0xbfb8aa3b, v51
	v_mul_f32_e32 v44, 0xbfb8aa3b, v50
	v_exp_f32_e32 v44, v44
	v_exp_f32_e32 v45, v45
	v_rcp_f32_e32 v41, v47
	v_pk_add_f32 v[44:45], v[44:45], 1.0 op_sel_hi:[1,0]
	v_rcp_f32_e32 v46, v46
	s_nop 0
	v_cvt_pk_bf16_f32 v41, v46, v41
	v_rcp_f32_e32 v45, v45
	v_mul_f32_e32 v42, 0xbfb8aa3b, v42
	v_mul_f32_e32 v43, 0xbfb8aa3b, v43
	v_exp_f32_e32 v42, v42
	v_exp_f32_e32 v43, v43
	s_nop 0
	v_pk_add_f32 v[46:47], v[42:43], 1.0 op_sel_hi:[1,0]
	v_rcp_f32_e32 v42, v44
	s_nop 0
	v_cvt_pk_bf16_f32 v42, v42, v45
	v_rcp_f32_e32 v43, v47
	s_mov_b64 s[0:1], 0x48000
	v_pk_mul_f32 v[36:37], v[36:37], v[48:49] op_sel_hi:[1,0]
	v_mul_f32_e32 v36, 0xbfb8aa3b, v36
	v_mul_f32_e32 v37, 0xbfb8aa3b, v37
	v_exp_f32_e32 v36, v36
	v_exp_f32_e32 v37, v37
	v_rcp_f32_e32 v44, v46
	v_add_co_u32_e32 v46, vcc, s61, v116
	v_cvt_pk_bf16_f32 v43, v44, v43
	s_nop 0
	v_addc_co_u32_e32 v47, vcc, 0, v117, vcc
	v_pk_add_f32 v[36:37], v[36:37], 1.0 op_sel_hi:[1,0]
	v_lshl_add_u64 v[44:45], v[116:117], 0, s[0:1]
	global_store_dwordx4 v[46:47], v[40:43], off
	v_pk_mul_f32 v[38:39], v[38:39], v[48:49] op_sel_hi:[1,0]
	v_pk_mul_f32 v[34:35], v[34:35], v[48:49] op_sel_hi:[1,0]
	v_pk_mul_f32 v[40:41], v[32:33], v[48:49] op_sel_hi:[1,0]
	v_mul_f32_e32 v34, 0xbfb8aa3b, v34
	v_mul_f32_e32 v35, 0xbfb8aa3b, v35
	v_rcp_f32_e32 v37, v37
	v_mul_f32_e32 v33, 0xbfb8aa3b, v39
	v_mul_f32_e32 v32, 0xbfb8aa3b, v38
	v_exp_f32_e32 v32, v32
	v_exp_f32_e32 v33, v33
	s_nop 0
	v_pk_add_f32 v[38:39], v[32:33], 1.0 op_sel_hi:[1,0]
	v_rcp_f32_e32 v32, v36
	s_nop 0
	v_cvt_pk_bf16_f32 v32, v32, v37
	v_mul_f32_e32 v37, 0xbfb8aa3b, v41
	v_mul_f32_e32 v36, 0xbfb8aa3b, v40
	v_exp_f32_e32 v36, v36
	v_exp_f32_e32 v37, v37
	v_rcp_f32_e32 v33, v39
	v_pk_add_f32 v[36:37], v[36:37], 1.0 op_sel_hi:[1,0]
	v_rcp_f32_e32 v38, v38
	s_nop 0
	v_cvt_pk_bf16_f32 v33, v38, v33
	v_rcp_f32_e32 v37, v37
	v_exp_f32_e32 v34, v34
	v_exp_f32_e32 v35, v35
	s_nop 0
	v_pk_add_f32 v[38:39], v[34:35], 1.0 op_sel_hi:[1,0]
	v_rcp_f32_e32 v34, v36
	s_nop 0
	v_cvt_pk_bf16_f32 v34, v34, v37
	v_rcp_f32_e32 v35, v39
	v_rcp_f32_e32 v36, v38
	s_nop 0
	v_cvt_pk_bf16_f32 v35, v36, v35
	global_store_dwordx4 v[44:45], v[32:35], off offset:256
	s_nop 0
	s_nop 0
	v_fmamk_f32 v32, v253, 0x3a800000, v171
	v_mul_f32_e32 v33, 0x4b800000, v32
	v_cmp_gt_f32_e32 vcc, s60, v32
	s_nop 1
	v_cndmask_b32_e32 v32, v32, v33, vcc
	v_rsq_f32_e32 v32, v32
	s_nop 0
	v_mul_f32_e32 v33, 0x45800000, v32
	v_cndmask_b32_e32 v32, v32, v33, vcc
	v_pk_mul_f32 v[28:29], v[28:29], v[32:33] op_sel_hi:[1,0]
	s_nop 0
	v_mul_f32_e32 v28, 0xbfb8aa3b, v28
	v_mul_f32_e32 v29, 0xbfb8aa3b, v29
	v_exp_f32_e32 v28, v28
	v_exp_f32_e32 v29, v29
	s_nop 0
	v_pk_add_f32 v[28:29], v[28:29], 1.0 op_sel_hi:[1,0]
	s_nop 0
	v_pk_mul_f32 v[34:35], v[24:25], v[32:33] op_sel_hi:[1,0]
	v_pk_mul_f32 v[30:31], v[30:31], v[32:33] op_sel_hi:[1,0]
	v_pk_mul_f32 v[26:27], v[26:27], v[32:33] op_sel_hi:[1,0]
	v_rcp_f32_e32 v29, v29
	v_mul_f32_e32 v25, 0xbfb8aa3b, v31
	v_mul_f32_e32 v24, 0xbfb8aa3b, v30
	v_exp_f32_e32 v24, v24
	v_exp_f32_e32 v25, v25
	s_nop 0
	v_pk_add_f32 v[30:31], v[24:25], 1.0 op_sel_hi:[1,0]
	v_rcp_f32_e32 v24, v28
	s_nop 0
	v_cvt_pk_bf16_f32 v24, v24, v29
	v_mul_f32_e32 v29, 0xbfb8aa3b, v35
	v_mul_f32_e32 v28, 0xbfb8aa3b, v34
	v_exp_f32_e32 v28, v28
	v_exp_f32_e32 v29, v29
	v_rcp_f32_e32 v25, v31
	v_pk_add_f32 v[28:29], v[28:29], 1.0 op_sel_hi:[1,0]
	v_rcp_f32_e32 v30, v30
	s_nop 0
	v_cvt_pk_bf16_f32 v25, v30, v25
	v_rcp_f32_e32 v29, v29
	v_mul_f32_e32 v26, 0xbfb8aa3b, v26
	v_mul_f32_e32 v27, 0xbfb8aa3b, v27
	v_exp_f32_e32 v26, v26
	v_exp_f32_e32 v27, v27
	s_nop 0
	v_pk_add_f32 v[30:31], v[26:27], 1.0 op_sel_hi:[1,0]
	v_rcp_f32_e32 v26, v28
	s_nop 0
; DI unsigned pk2(float lo, float hi) { f32x2_t v = {lo, hi}; bf16x2_t b = __builtin_convertvector(v, bf16x2_t); return __builtin_bit_cast(unsigned, b); }
; DI float sigmoidf_(float x) { return 1.0f / (1.0f + __expf(-x)); }
;     DI void operator()(AccRef acc, const Unit& u, int wr, int wc, int fr, int fq) const {
;     ...
;             for (int m = 0; m < 4; ++m) {
;                 const int row = row0 + ai * HALF + m * 16; const float rs = rsqrtf(SS0[row] * (1.0f / DM) + EPSN);
; #pragma unroll
;                 for (int bj = 0; bj < 2; ++bj) {
;                     const f32x4 v0 = acc[ai][bj][m][0] * rs, v1 = acc[ai][bj][m][1] * rs;
;                     u32x4 w; w.x = pk2(sigmoidf_(v0[0]), sigmoidf_(v0[1])); w.y = pk2(sigmoidf_(v0[2]), sigmoidf_(v0[3])); w.z = pk2(sigmoidf_(v1[0]), sigmoidf_(v1[1])); w.w = pk2(sigmoidf_(v1[2]), sigmoidf_(v1[3]));
;                     *(u32x4*)(D + (size_t)row * DM + col0 + bj * HALF) = w;
;                 }
	v_cvt_pk_bf16_f32 v26, v26, v29
	v_rcp_f32_e32 v27, v31
	v_pk_mul_f32 v[20:21], v[20:21], v[32:33] op_sel_hi:[1,0]
	v_mul_f32_e32 v20, 0xbfb8aa3b, v20
	v_mul_f32_e32 v21, 0xbfb8aa3b, v21
	v_exp_f32_e32 v20, v20
	v_exp_f32_e32 v21, v21
	v_rcp_f32_e32 v28, v30
	v_add_co_u32_e32 v30, vcc, s62, v116
	v_cvt_pk_bf16_f32 v27, v28, v27
	s_nop 0
	v_addc_co_u32_e32 v31, vcc, 0, v117, vcc
	v_pk_add_f32 v[20:21], v[20:21], 1.0 op_sel_hi:[1,0]
	global_store_dwordx4 v[30:31], v[24:27], off
	v_pk_mul_f32 v[22:23], v[22:23], v[32:33] op_sel_hi:[1,0]
	v_pk_mul_f32 v[18:19], v[18:19], v[32:33] op_sel_hi:[1,0]
	v_pk_mul_f32 v[24:25], v[16:17], v[32:33] op_sel_hi:[1,0]
	v_mul_f32_e32 v18, 0xbfb8aa3b, v18
	v_mul_f32_e32 v19, 0xbfb8aa3b, v19
	v_rcp_f32_e32 v21, v21
	v_mul_f32_e32 v17, 0xbfb8aa3b, v23
	v_mul_f32_e32 v16, 0xbfb8aa3b, v22
	v_exp_f32_e32 v16, v16
	v_exp_f32_e32 v17, v17
	s_nop 0
	v_pk_add_f32 v[22:23], v[16:17], 1.0 op_sel_hi:[1,0]
	v_rcp_f32_e32 v16, v20
	s_nop 0
	v_cvt_pk_bf16_f32 v16, v16, v21
	v_mul_f32_e32 v21, 0xbfb8aa3b, v25
	v_mul_f32_e32 v20, 0xbfb8aa3b, v24
	v_exp_f32_e32 v20, v20
	v_exp_f32_e32 v21, v21
	v_rcp_f32_e32 v17, v23
	v_pk_add_f32 v[20:21], v[20:21], 1.0 op_sel_hi:[1,0]
	v_rcp_f32_e32 v22, v22
	s_nop 0
	v_cvt_pk_bf16_f32 v17, v22, v17
	v_rcp_f32_e32 v21, v21
	v_exp_f32_e32 v18, v18
	v_exp_f32_e32 v19, v19
	s_nop 0
	v_pk_add_f32 v[22:23], v[18:19], 1.0 op_sel_hi:[1,0]
	v_rcp_f32_e32 v18, v20
	s_nop 0
	v_cvt_pk_bf16_f32 v18, v18, v21
	v_lshl_add_u64 v[28:29], v[116:117], 0, s[22:23]
	v_rcp_f32_e32 v19, v23
	v_rcp_f32_e32 v20, v22
	s_nop 0
	v_cvt_pk_bf16_f32 v19, v20, v19
	global_store_dwordx4 v[28:29], v[16:19], off offset:256
	s_nop 0
	s_nop 0
	v_fmamk_f32 v16, v254, 0x3a800000, v171
	v_mul_f32_e32 v17, 0x4b800000, v16
	v_cmp_gt_f32_e32 vcc, s60, v16
	s_nop 1
	v_cndmask_b32_e32 v16, v16, v17, vcc
	v_rsq_f32_e32 v16, v16
	s_nop 0
	v_mul_f32_e32 v17, 0x45800000, v16
	v_cndmask_b32_e32 v16, v16, v17, vcc
	v_pk_mul_f32 v[12:13], v[12:13], v[16:17] op_sel_hi:[1,0]
	s_nop 0
	v_mul_f32_e32 v12, 0xbfb8aa3b, v12
	v_mul_f32_e32 v13, 0xbfb8aa3b, v13
	v_exp_f32_e32 v12, v12
	v_exp_f32_e32 v13, v13
	s_nop 0
	v_pk_add_f32 v[12:13], v[12:13], 1.0 op_sel_hi:[1,0]
	s_nop 0
	v_pk_mul_f32 v[18:19], v[8:9], v[16:17] op_sel_hi:[1,0]
	v_pk_mul_f32 v[14:15], v[14:15], v[16:17] op_sel_hi:[1,0]
	v_pk_mul_f32 v[10:11], v[10:11], v[16:17] op_sel_hi:[1,0]
	v_rcp_f32_e32 v13, v13
	v_mul_f32_e32 v9, 0xbfb8aa3b, v15
	v_mul_f32_e32 v8, 0xbfb8aa3b, v14
	v_exp_f32_e32 v8, v8
	v_exp_f32_e32 v9, v9
	s_nop 0
	v_pk_add_f32 v[14:15], v[8:9], 1.0 op_sel_hi:[1,0]
	v_rcp_f32_e32 v8, v12
	s_nop 0
	v_cvt_pk_bf16_f32 v8, v8, v13
	v_mul_f32_e32 v13, 0xbfb8aa3b, v19
	v_mul_f32_e32 v12, 0xbfb8aa3b, v18
	v_exp_f32_e32 v12, v12
	v_exp_f32_e32 v13, v13
	v_rcp_f32_e32 v9, v15
	v_pk_add_f32 v[12:13], v[12:13], 1.0 op_sel_hi:[1,0]
	v_rcp_f32_e32 v14, v14
	s_nop 0
	v_cvt_pk_bf16_f32 v9, v14, v9
	v_rcp_f32_e32 v13, v13
	v_mul_f32_e32 v10, 0xbfb8aa3b, v10
	v_mul_f32_e32 v11, 0xbfb8aa3b, v11
	v_exp_f32_e32 v10, v10
	v_exp_f32_e32 v11, v11
	s_nop 0
	v_pk_add_f32 v[14:15], v[10:11], 1.0 op_sel_hi:[1,0]
	v_rcp_f32_e32 v10, v12
	s_nop 0
	v_cvt_pk_bf16_f32 v10, v10, v13
	v_rcp_f32_e32 v11, v15
	v_pk_mul_f32 v[4:5], v[4:5], v[16:17] op_sel_hi:[1,0]
	v_mul_f32_e32 v4, 0xbfb8aa3b, v4
	v_mul_f32_e32 v5, 0xbfb8aa3b, v5
	v_exp_f32_e32 v4, v4
	v_exp_f32_e32 v5, v5
	v_rcp_f32_e32 v12, v14
	v_add_co_u32_e32 v14, vcc, s63, v116
	v_cvt_pk_bf16_f32 v11, v12, v11
	s_nop 0
	v_addc_co_u32_e32 v15, vcc, 0, v117, vcc
	v_pk_add_f32 v[4:5], v[4:5], 1.0 op_sel_hi:[1,0]
	global_store_dwordx4 v[14:15], v[8:11], off
	v_pk_mul_f32 v[6:7], v[6:7], v[16:17] op_sel_hi:[1,0]
	v_pk_mul_f32 v[2:3], v[2:3], v[16:17] op_sel_hi:[1,0]
	v_pk_mul_f32 v[8:9], v[0:1], v[16:17] op_sel_hi:[1,0]
	v_mul_f32_e32 v2, 0xbfb8aa3b, v2
	v_mul_f32_e32 v3, 0xbfb8aa3b, v3
	v_rcp_f32_e32 v5, v5
	v_mul_f32_e32 v1, 0xbfb8aa3b, v7
	v_mul_f32_e32 v0, 0xbfb8aa3b, v6
	v_exp_f32_e32 v0, v0
	v_exp_f32_e32 v1, v1
	s_nop 0
	v_pk_add_f32 v[6:7], v[0:1], 1.0 op_sel_hi:[1,0]
	v_rcp_f32_e32 v0, v4
	s_nop 0
	v_cvt_pk_bf16_f32 v0, v0, v5
	v_mul_f32_e32 v5, 0xbfb8aa3b, v9
	v_mul_f32_e32 v4, 0xbfb8aa3b, v8
	v_exp_f32_e32 v4, v4
	v_exp_f32_e32 v5, v5
	v_rcp_f32_e32 v1, v7
	v_pk_add_f32 v[4:5], v[4:5], 1.0 op_sel_hi:[1,0]
	v_rcp_f32_e32 v6, v6
	s_nop 0
	v_cvt_pk_bf16_f32 v1, v6, v1
	v_rcp_f32_e32 v5, v5
	v_exp_f32_e32 v2, v2
	v_exp_f32_e32 v3, v3
	s_nop 0
	v_pk_add_f32 v[6:7], v[2:3], 1.0 op_sel_hi:[1,0]
	v_rcp_f32_e32 v2, v4
	s_nop 0
	v_cvt_pk_bf16_f32 v2, v2, v5
	v_lshl_add_u64 v[12:13], v[116:117], 0, s[24:25]
	v_rcp_f32_e32 v3, v7
	s_mov_b64 s[0:1], -1
	v_rcp_f32_e32 v4, v6
	s_nop 0
	v_cvt_pk_bf16_f32 v3, v4, v3
	s_andn2_b64 vcc, exec, s[4:5]
	global_store_dwordx4 v[12:13], v[0:3], off offset:256
	s_cbranch_vccnz .LBB0_1287
	s_andn2_b64 vcc, exec, s[16:17]
	s_cbranch_vccnz .LBB0_1286
	s_barrier
	s_branch .LBB0_1286

; DI unsigned pk2(float lo, float hi) { f32x2_t v = {lo, hi}; bf16x2_t b = __builtin_convertvector(v, bf16x2_t); return __builtin_bit_cast(unsigned, b); }
; DI float sigmoidf_(float x) { return 1.0f / (1.0f + __expf(-x)); }
;     DI void operator()(AccRef acc, const Unit& u, int wr, int wc, int fr, int fq) const {
;     ...
;             for (int m = 0; m < 4; ++m) {
;                 const int row = row0 + ai * HALF + m * 16; const float rs = rsqrtf(SS1[row] * (1.0f / DM) + EPSN);
;                 float h[8];
; #pragma unroll
;                 for (int n = 0; n < 2; ++n)
; #pragma unroll
;                     for (int e = 0; e < 4; ++e) { const float g = acc[ai][0][m][n][e] * rs, up = acc[ai][1][m][n][e] * rs; h[4 * n + e] = g * sigmoidf_(g) * up; }
;                 u32x4 w; w.x = pk2(h[0], h[1]); w.y = pk2(h[2], h[3]); w.z = pk2(h[4], h[5]); w.w = pk2(h[6], h[7]);
;                 *(u32x4*)(H + (size_t)row * DFF + col0) = w;
.LBB0_1490:
	v_lshl_add_u32 v144, s0, 8, v149
	v_ashrrev_i32_e32 v145, 31, v144
	v_lshl_add_u64 v[146:147], v[144:145], 2, s[46:47]
	global_load_dword v145, v[146:147], off
	global_load_dword v248, v[146:147], off offset:64
	global_load_dword v249, v[146:147], off offset:128
	global_load_dword v250, v[146:147], off offset:192
	global_load_dword v251, v[146:147], off offset:512
	global_load_dword v252, v[146:147], off offset:576
	global_load_dword v253, v[146:147], off offset:640
	global_load_dword v254, v[146:147], off offset:704
	s_waitcnt vmcnt(0)
	v_fmamk_f32 v145, v145, 0x3a800000, v158
	v_mul_f32_e32 v152, 0x4b800000, v145
	v_cmp_gt_f32_e32 vcc, s43, v145
	s_nop 1
	v_cndmask_b32_e32 v145, v145, v152, vcc
	v_rsq_f32_e32 v145, v145
	v_lshl_or_b32 v152, s1, 7, v154
	v_ashrrev_i32_e32 v153, 31, v152
	v_mul_f32_e32 v159, 0x45800000, v145
	v_cndmask_b32_e32 v160, v145, v159, vcc
	v_pk_mul_f32 v[124:125], v[124:125], v[160:161] op_sel_hi:[1,0]
	v_pk_mul_f32 v[126:127], v[126:127], v[160:161] op_sel_hi:[1,0]
	v_mul_f32_e32 v145, 0xbfb8aa3b, v124
	v_mul_f32_e32 v159, 0xbfb8aa3b, v125
	v_exp_f32_e32 v162, v145
	v_exp_f32_e32 v163, v159
	v_pk_mul_f32 v[120:121], v[120:121], v[160:161] op_sel_hi:[1,0]
	v_pk_mul_f32 v[122:123], v[122:123], v[160:161] op_sel_hi:[1,0]
	v_pk_mul_f32 v[116:117], v[116:117], v[160:161] op_sel_hi:[1,0]
	v_mul_f32_e32 v161, 0xbfb8aa3b, v126
	v_mul_f32_e32 v165, 0xbfb8aa3b, v127
	v_exp_f32_e32 v164, v161
	v_exp_f32_e32 v165, v165
	v_pk_add_f32 v[162:163], v[162:163], 1.0 op_sel_hi:[1,0]
	v_pk_mul_f32 v[112:113], v[112:113], v[160:161] op_sel_hi:[1,0]
	v_pk_add_f32 v[164:165], v[164:165], 1.0 op_sel_hi:[1,0]
	v_mul_f32_e32 v166, 0xbfb8aa3b, v116
	v_mul_f32_e32 v167, 0xbfb8aa3b, v117
	v_exp_f32_e32 v166, v166
	v_exp_f32_e32 v167, v167
	s_nop 0
	v_pk_add_f32 v[166:167], v[166:167], 1.0 op_sel_hi:[1,0]
	v_rcp_f32_e32 v163, v163
	v_rcp_f32_e32 v162, v162
	s_nop 0
	v_pk_mul_f32 v[124:125], v[124:125], v[162:163]
	v_rcp_f32_e32 v163, v165
	v_rcp_f32_e32 v162, v164
	v_pk_mul_f32 v[120:121], v[120:121], v[124:125]
	v_pk_mul_f32 v[124:125], v[126:127], v[162:163]
	v_pk_mul_f32 v[118:119], v[118:119], v[160:161] op_sel_hi:[1,0]
	v_pk_mul_f32 v[122:123], v[122:123], v[124:125]
	v_mul_f32_e32 v124, 0xbfb8aa3b, v118
	v_mul_f32_e32 v125, 0xbfb8aa3b, v119
	v_exp_f32_e32 v124, v124
	v_exp_f32_e32 v125, v125
	s_nop 0
	v_pk_add_f32 v[124:125], v[124:125], 1.0 op_sel_hi:[1,0]
	v_rcp_f32_e32 v127, v167
	v_rcp_f32_e32 v126, v166
	s_nop 0
	v_pk_mul_f32 v[116:117], v[116:117], v[126:127]
	v_pk_mul_f32 v[114:115], v[114:115], v[160:161] op_sel_hi:[1,0]
	v_pk_mul_f32 v[112:113], v[112:113], v[116:117]
	v_rcp_f32_e32 v117, v125
	v_rcp_f32_e32 v116, v124
	s_nop 0
	v_pk_mul_f32 v[116:117], v[118:119], v[116:117]
	v_cvt_pk_bf16_f32 v118, v112, v113
	v_pk_mul_f32 v[114:115], v[114:115], v[116:117]
	v_mov_b64_e32 v[112:113], s[48:49]
	v_cvt_pk_bf16_f32 v116, v120, v121
	v_cvt_pk_bf16_f32 v119, v114, v115
	v_mad_i64_i32 v[120:121], s[0:1], v144, s44, v[112:113]
	v_lshlrev_b64 v[114:115], 1, v[152:153]
	v_cvt_pk_bf16_f32 v117, v122, v123
	v_lshl_add_u64 v[120:121], v[120:121], 0, v[114:115]
	global_store_dwordx4 v[120:121], v[116:119], off
	s_nop 1
	v_or_b32_e32 v116, 16, v144
	v_ashrrev_i32_e32 v117, 31, v116
	v_lshl_add_u64 v[118:119], v[116:117], 2, s[46:47]
	s_nop 0
	s_nop 0
	v_fmamk_f32 v117, v248, 0x3a800000, v158
	v_mul_f32_e32 v118, 0x4b800000, v117
	v_cmp_gt_f32_e32 vcc, s43, v117
	s_nop 1
	v_cndmask_b32_e32 v117, v117, v118, vcc
	v_rsq_f32_e32 v117, v117
	s_nop 0
	v_mul_f32_e32 v118, 0x45800000, v117
	v_cndmask_b32_e32 v118, v117, v118, vcc
	v_pk_mul_f32 v[108:109], v[108:109], v[118:119] op_sel_hi:[1,0]
	v_pk_mul_f32 v[110:111], v[110:111], v[118:119] op_sel_hi:[1,0]
	v_mul_f32_e32 v117, 0xbfb8aa3b, v108
	v_mul_f32_e32 v119, 0xbfb8aa3b, v109
	v_exp_f32_e32 v120, v117
	v_exp_f32_e32 v121, v119
	v_mul_f32_e32 v122, 0xbfb8aa3b, v110
	v_mul_f32_e32 v123, 0xbfb8aa3b, v111
	v_exp_f32_e32 v122, v122
	v_pk_add_f32 v[120:121], v[120:121], 1.0 op_sel_hi:[1,0]
	v_exp_f32_e32 v123, v123
	s_nop 0
	v_pk_add_f32 v[122:123], v[122:123], 1.0 op_sel_hi:[1,0]
	v_pk_mul_f32 v[104:105], v[104:105], v[118:119] op_sel_hi:[1,0]
	v_pk_mul_f32 v[106:107], v[106:107], v[118:119] op_sel_hi:[1,0]
	v_rcp_f32_e32 v121, v121
	v_rcp_f32_e32 v120, v120
	s_nop 0
	v_pk_mul_f32 v[108:109], v[108:109], v[120:121]
	v_pk_mul_f32 v[104:105], v[104:105], v[108:109]
	v_rcp_f32_e32 v109, v123
	v_pk_mul_f32 v[100:101], v[100:101], v[118:119] op_sel_hi:[1,0]
	v_mul_f32_e32 v117, 0xbfb8aa3b, v100
	v_exp_f32_e32 v120, v117
	v_mul_f32_e32 v117, 0xbfb8aa3b, v101
	v_exp_f32_e32 v121, v117
	v_rcp_f32_e32 v108, v122
	s_nop 0
	v_pk_mul_f32 v[108:109], v[110:111], v[108:109]
	v_pk_add_f32 v[120:121], v[120:121], 1.0 op_sel_hi:[1,0]
	v_pk_mul_f32 v[106:107], v[106:107], v[108:109]
	s_nop 0
	v_pk_mul_f32 v[96:97], v[96:97], v[118:119] op_sel_hi:[1,0]
	v_rcp_f32_e32 v109, v121
	v_pk_mul_f32 v[102:103], v[102:103], v[118:119] op_sel_hi:[1,0]
	v_mul_f32_e32 v110, 0xbfb8aa3b, v102
	v_mul_f32_e32 v111, 0xbfb8aa3b, v103
	v_exp_f32_e32 v110, v110
	v_exp_f32_e32 v111, v111
	v_rcp_f32_e32 v108, v120
	s_nop 0
	v_pk_mul_f32 v[100:101], v[100:101], v[108:109]
	v_pk_add_f32 v[110:111], v[110:111], 1.0 op_sel_hi:[1,0]
	v_pk_mul_f32 v[100:101], v[96:97], v[100:101]
	s_nop 0
	v_pk_mul_f32 v[96:97], v[98:99], v[118:119] op_sel_hi:[1,0]
	v_rcp_f32_e32 v99, v111
	v_rcp_f32_e32 v98, v110
	s_nop 0
	v_pk_mul_f32 v[98:99], v[102:103], v[98:99]
	s_nop 0
	v_pk_mul_f32 v[102:103], v[96:97], v[98:99]
	v_cvt_pk_bf16_f32 v98, v100, v101
	v_mad_i64_i32 v[100:101], s[0:1], v116, s44, v[112:113]
	v_cvt_pk_bf16_f32 v96, v104, v105
; DI unsigned pk2(float lo, float hi) { f32x2_t v = {lo, hi}; bf16x2_t b = __builtin_convertvector(v, bf16x2_t); return __builtin_bit_cast(unsigned, b); }
; DI float sigmoidf_(float x) { return 1.0f / (1.0f + __expf(-x)); }
;     DI void operator()(AccRef acc, const Unit& u, int wr, int wc, int fr, int fq) const {
;     ...
;             for (int m = 0; m < 4; ++m) {
;                 const int row = row0 + ai * HALF + m * 16; const float rs = rsqrtf(SS1[row] * (1.0f / DM) + EPSN);
;                 float h[8];
; #pragma unroll
;                 for (int n = 0; n < 2; ++n)
; #pragma unroll
;                     for (int e = 0; e < 4; ++e) { const float g = acc[ai][0][m][n][e] * rs, up = acc[ai][1][m][n][e] * rs; h[4 * n + e] = g * sigmoidf_(g) * up; }
;                 u32x4 w; w.x = pk2(h[0], h[1]); w.y = pk2(h[2], h[3]); w.z = pk2(h[4], h[5]); w.w = pk2(h[6], h[7]);
;                 *(u32x4*)(H + (size_t)row * DFF + col0) = w;
	v_cvt_pk_bf16_f32 v97, v106, v107
	v_cvt_pk_bf16_f32 v99, v102, v103
	v_lshl_add_u64 v[100:101], v[100:101], 0, v[114:115]
	global_store_dwordx4 v[100:101], v[96:99], off
	s_nop 1
	v_or_b32_e32 v96, 32, v144
	v_ashrrev_i32_e32 v97, 31, v96
	v_lshl_add_u64 v[98:99], v[96:97], 2, s[46:47]
	s_nop 0
	s_nop 0
	v_fmamk_f32 v97, v249, 0x3a800000, v158
	v_mul_f32_e32 v98, 0x4b800000, v97
	v_cmp_gt_f32_e32 vcc, s43, v97
	s_nop 1
	v_cndmask_b32_e32 v97, v97, v98, vcc
	v_rsq_f32_e32 v97, v97
	s_nop 0
	v_mul_f32_e32 v98, 0x45800000, v97
	v_cndmask_b32_e32 v98, v97, v98, vcc
	v_pk_mul_f32 v[92:93], v[92:93], v[98:99] op_sel_hi:[1,0]
	s_nop 0
	v_mul_f32_e32 v97, 0xbfb8aa3b, v92
	v_exp_f32_e32 v100, v97
	v_mul_f32_e32 v97, 0xbfb8aa3b, v93
	v_exp_f32_e32 v101, v97
	s_nop 0
	v_pk_add_f32 v[100:101], v[100:101], 1.0 op_sel_hi:[1,0]
	s_nop 0
	s_nop 0
	v_pk_mul_f32 v[88:89], v[88:89], v[98:99] op_sel_hi:[1,0]
	v_rcp_f32_e32 v101, v101
	v_pk_mul_f32 v[94:95], v[94:95], v[98:99] op_sel_hi:[1,0]
	v_mul_f32_e32 v102, 0xbfb8aa3b, v94
	v_mul_f32_e32 v103, 0xbfb8aa3b, v95
	v_exp_f32_e32 v102, v102
	v_exp_f32_e32 v103, v103
	v_rcp_f32_e32 v100, v100
	s_nop 0
	v_pk_mul_f32 v[92:93], v[92:93], v[100:101]
	v_pk_add_f32 v[102:103], v[102:103], 1.0 op_sel_hi:[1,0]
	v_pk_mul_f32 v[88:89], v[88:89], v[92:93]
	s_nop 0
	v_pk_mul_f32 v[90:91], v[90:91], v[98:99] op_sel_hi:[1,0]
	v_rcp_f32_e32 v93, v103
	v_pk_mul_f32 v[84:85], v[84:85], v[98:99] op_sel_hi:[1,0]
	v_mul_f32_e32 v97, 0xbfb8aa3b, v84
	v_exp_f32_e32 v100, v97
	v_mul_f32_e32 v97, 0xbfb8aa3b, v85
	v_exp_f32_e32 v101, v97
	v_rcp_f32_e32 v92, v102
	s_nop 0
	v_pk_mul_f32 v[92:93], v[94:95], v[92:93]
	v_pk_add_f32 v[100:101], v[100:101], 1.0 op_sel_hi:[1,0]
	v_pk_mul_f32 v[90:91], v[90:91], v[92:93]
	s_nop 0
	v_pk_mul_f32 v[80:81], v[80:81], v[98:99] op_sel_hi:[1,0]
	v_rcp_f32_e32 v93, v101
	v_pk_mul_f32 v[86:87], v[86:87], v[98:99] op_sel_hi:[1,0]
	v_mul_f32_e32 v94, 0xbfb8aa3b, v86
	v_mul_f32_e32 v95, 0xbfb8aa3b, v87
	v_exp_f32_e32 v94, v94
	v_exp_f32_e32 v95, v95
	v_rcp_f32_e32 v92, v100
	s_nop 0
	v_pk_mul_f32 v[84:85], v[84:85], v[92:93]
	v_pk_add_f32 v[94:95], v[94:95], 1.0 op_sel_hi:[1,0]
	v_pk_mul_f32 v[84:85], v[80:81], v[84:85]
	s_nop 0
	v_pk_mul_f32 v[80:81], v[82:83], v[98:99] op_sel_hi:[1,0]
	v_rcp_f32_e32 v83, v95
	v_rcp_f32_e32 v82, v94
	s_nop 0
	v_pk_mul_f32 v[82:83], v[86:87], v[82:83]
	s_nop 0
	v_pk_mul_f32 v[86:87], v[80:81], v[82:83]
	v_cvt_pk_bf16_f32 v82, v84, v85
	v_mad_i64_i32 v[84:85], s[0:1], v96, s44, v[112:113]
	v_cvt_pk_bf16_f32 v80, v88, v89
	v_cvt_pk_bf16_f32 v81, v90, v91
	v_cvt_pk_bf16_f32 v83, v86, v87
	v_lshl_add_u64 v[84:85], v[84:85], 0, v[114:115]
	global_store_dwordx4 v[84:85], v[80:83], off
	s_nop 1
	v_or_b32_e32 v80, 48, v144
	v_ashrrev_i32_e32 v81, 31, v80
	v_lshl_add_u64 v[82:83], v[80:81], 2, s[46:47]
	s_nop 0
	s_nop 0
	v_fmamk_f32 v81, v250, 0x3a800000, v158
	v_mul_f32_e32 v82, 0x4b800000, v81
	v_cmp_gt_f32_e32 vcc, s43, v81
	s_nop 1
	v_cndmask_b32_e32 v81, v81, v82, vcc
	v_rsq_f32_e32 v81, v81
	s_nop 0
	v_mul_f32_e32 v82, 0x45800000, v81
	v_cndmask_b32_e32 v82, v81, v82, vcc
	v_pk_mul_f32 v[76:77], v[76:77], v[82:83] op_sel_hi:[1,0]
	s_nop 0
	v_mul_f32_e32 v81, 0xbfb8aa3b, v76
	v_exp_f32_e32 v84, v81
	v_mul_f32_e32 v81, 0xbfb8aa3b, v77
	v_exp_f32_e32 v85, v81
	s_nop 0
	v_pk_add_f32 v[84:85], v[84:85], 1.0 op_sel_hi:[1,0]
	s_nop 0
	s_nop 0
	v_pk_mul_f32 v[72:73], v[72:73], v[82:83] op_sel_hi:[1,0]
	v_rcp_f32_e32 v85, v85
	v_pk_mul_f32 v[78:79], v[78:79], v[82:83] op_sel_hi:[1,0]
	v_mul_f32_e32 v86, 0xbfb8aa3b, v78
	v_mul_f32_e32 v87, 0xbfb8aa3b, v79
	v_exp_f32_e32 v86, v86
	v_exp_f32_e32 v87, v87
	v_rcp_f32_e32 v84, v84
	s_nop 0
	v_pk_mul_f32 v[76:77], v[76:77], v[84:85]
	v_pk_add_f32 v[86:87], v[86:87], 1.0 op_sel_hi:[1,0]
	v_pk_mul_f32 v[72:73], v[72:73], v[76:77]
	s_nop 0
	v_pk_mul_f32 v[74:75], v[74:75], v[82:83] op_sel_hi:[1,0]
	v_rcp_f32_e32 v77, v87
	v_pk_mul_f32 v[68:69], v[68:69], v[82:83] op_sel_hi:[1,0]
	v_mul_f32_e32 v81, 0xbfb8aa3b, v68
	v_exp_f32_e32 v84, v81
	v_mul_f32_e32 v81, 0xbfb8aa3b, v69
	v_exp_f32_e32 v85, v81
	v_rcp_f32_e32 v76, v86
	s_nop 0
	v_pk_mul_f32 v[76:77], v[78:79], v[76:77]
	v_pk_add_f32 v[84:85], v[84:85], 1.0 op_sel_hi:[1,0]
	v_pk_mul_f32 v[74:75], v[74:75], v[76:77]
	s_nop 0
	v_pk_mul_f32 v[64:65], v[64:65], v[82:83] op_sel_hi:[1,0]
	v_rcp_f32_e32 v77, v85
	v_pk_mul_f32 v[70:71], v[70:71], v[82:83] op_sel_hi:[1,0]
	v_mul_f32_e32 v78, 0xbfb8aa3b, v70
	v_mul_f32_e32 v79, 0xbfb8aa3b, v71
	v_exp_f32_e32 v78, v78
	v_exp_f32_e32 v79, v79
	v_rcp_f32_e32 v76, v84
	s_nop 0
	v_pk_mul_f32 v[68:69], v[68:69], v[76:77]
	v_pk_add_f32 v[78:79], v[78:79], 1.0 op_sel_hi:[1,0]
	v_pk_mul_f32 v[68:69], v[64:65], v[68:69]
	s_nop 0
	v_pk_mul_f32 v[64:65], v[66:67], v[82:83] op_sel_hi:[1,0]
	v_rcp_f32_e32 v67, v79
	v_rcp_f32_e32 v66, v78
	s_nop 0
	v_pk_mul_f32 v[66:67], v[70:71], v[66:67]
	s_nop 0
	v_pk_mul_f32 v[70:71], v[64:65], v[66:67]
	v_cvt_pk_bf16_f32 v66, v68, v69
	v_mad_i64_i32 v[68:69], s[0:1], v80, s44, v[112:113]
	v_cvt_pk_bf16_f32 v64, v72, v73
	v_cvt_pk_bf16_f32 v65, v74, v75
	v_cvt_pk_bf16_f32 v67, v70, v71
	v_lshl_add_u64 v[68:69], v[68:69], 0, v[114:115]
	global_store_dwordx4 v[68:69], v[64:67], off
	s_nop 0
	v_add_u32_e32 v70, 0x80, v144
	s_nop 0
	v_fmamk_f32 v64, v251, 0x3a800000, v158
	v_mul_f32_e32 v65, 0x4b800000, v64
	v_cmp_gt_f32_e32 vcc, s43, v64
	s_nop 1
	v_cndmask_b32_e32 v64, v64, v65, vcc
	v_rsq_f32_e32 v64, v64
	s_nop 0
	v_mul_f32_e32 v65, 0x45800000, v64
	v_cndmask_b32_e32 v64, v64, v65, vcc
	v_pk_mul_f32 v[60:61], v[60:61], v[64:65] op_sel_hi:[1,0]
	s_nop 0
	v_mul_f32_e32 v65, 0xbfb8aa3b, v60
	v_exp_f32_e32 v66, v65
; DI unsigned pk2(float lo, float hi) { f32x2_t v = {lo, hi}; bf16x2_t b = __builtin_convertvector(v, bf16x2_t); return __builtin_bit_cast(unsigned, b); }
; DI float sigmoidf_(float x) { return 1.0f / (1.0f + __expf(-x)); }
;     DI void operator()(AccRef acc, const Unit& u, int wr, int wc, int fr, int fq) const {
;     ...
;             for (int m = 0; m < 4; ++m) {
;                 const int row = row0 + ai * HALF + m * 16; const float rs = rsqrtf(SS1[row] * (1.0f / DM) + EPSN);
;                 float h[8];
; #pragma unroll
;                 for (int n = 0; n < 2; ++n)
; #pragma unroll
;                     for (int e = 0; e < 4; ++e) { const float g = acc[ai][0][m][n][e] * rs, up = acc[ai][1][m][n][e] * rs; h[4 * n + e] = g * sigmoidf_(g) * up; }
;                 u32x4 w; w.x = pk2(h[0], h[1]); w.y = pk2(h[2], h[3]); w.z = pk2(h[4], h[5]); w.w = pk2(h[6], h[7]);
;                 *(u32x4*)(H + (size_t)row * DFF + col0) = w;
	v_mul_f32_e32 v65, 0xbfb8aa3b, v61
	v_exp_f32_e32 v67, v65
	s_nop 0
	v_pk_add_f32 v[66:67], v[66:67], 1.0 op_sel_hi:[1,0]
	s_nop 0
	v_pk_mul_f32 v[56:57], v[56:57], v[64:65] op_sel_hi:[1,0]
	v_rcp_f32_e32 v67, v67
	v_pk_mul_f32 v[62:63], v[62:63], v[64:65] op_sel_hi:[1,0]
	v_mul_f32_e32 v68, 0xbfb8aa3b, v62
	v_mul_f32_e32 v69, 0xbfb8aa3b, v63
	v_exp_f32_e32 v68, v68
	v_exp_f32_e32 v69, v69
	v_rcp_f32_e32 v66, v66
	s_nop 0
	v_pk_mul_f32 v[60:61], v[60:61], v[66:67]
	v_pk_add_f32 v[68:69], v[68:69], 1.0 op_sel_hi:[1,0]
	s_nop 0
	v_pk_mul_f32 v[56:57], v[56:57], v[60:61]
	v_pk_mul_f32 v[58:59], v[58:59], v[64:65] op_sel_hi:[1,0]
	v_rcp_f32_e32 v61, v69
	v_pk_mul_f32 v[52:53], v[52:53], v[64:65] op_sel_hi:[1,0]
	v_mul_f32_e32 v65, 0xbfb8aa3b, v52
	v_exp_f32_e32 v66, v65
	v_mul_f32_e32 v65, 0xbfb8aa3b, v53
	v_exp_f32_e32 v67, v65
	v_rcp_f32_e32 v60, v68
	s_nop 0
	v_pk_mul_f32 v[60:61], v[62:63], v[60:61]
	v_pk_add_f32 v[66:67], v[66:67], 1.0 op_sel_hi:[1,0]
	v_pk_mul_f32 v[58:59], v[58:59], v[60:61]
	v_pk_mul_f32 v[48:49], v[48:49], v[64:65] op_sel_hi:[1,0]
	v_rcp_f32_e32 v61, v67
	v_pk_mul_f32 v[54:55], v[54:55], v[64:65] op_sel_hi:[1,0]
	v_mul_f32_e32 v62, 0xbfb8aa3b, v54
	v_mul_f32_e32 v63, 0xbfb8aa3b, v55
	v_exp_f32_e32 v62, v62
	v_exp_f32_e32 v63, v63
	v_rcp_f32_e32 v60, v66
	s_nop 0
	v_pk_mul_f32 v[52:53], v[52:53], v[60:61]
	v_pk_add_f32 v[62:63], v[62:63], 1.0 op_sel_hi:[1,0]
	v_pk_mul_f32 v[52:53], v[48:49], v[52:53]
	v_pk_mul_f32 v[48:49], v[50:51], v[64:65] op_sel_hi:[1,0]
	v_rcp_f32_e32 v51, v63
	v_rcp_f32_e32 v50, v62
	s_nop 0
	v_pk_mul_f32 v[50:51], v[54:55], v[50:51]
	s_nop 0
	v_pk_mul_f32 v[54:55], v[48:49], v[50:51]
	v_cvt_pk_bf16_f32 v50, v52, v53
	v_mad_i64_i32 v[52:53], s[0:1], v70, s44, v[112:113]
	v_cvt_pk_bf16_f32 v48, v56, v57
	v_cvt_pk_bf16_f32 v49, v58, v59
	v_cvt_pk_bf16_f32 v51, v54, v55
	v_lshl_add_u64 v[52:53], v[52:53], 0, v[114:115]
	global_store_dwordx4 v[52:53], v[48:51], off
	s_nop 0
	v_add_u32_e32 v54, 0x90, v144
	s_nop 0
	v_fmamk_f32 v48, v252, 0x3a800000, v158
	v_mul_f32_e32 v49, 0x4b800000, v48
	v_cmp_gt_f32_e32 vcc, s43, v48
	s_nop 1
	v_cndmask_b32_e32 v48, v48, v49, vcc
	v_rsq_f32_e32 v48, v48
	s_nop 0
	v_mul_f32_e32 v49, 0x45800000, v48
	v_cndmask_b32_e32 v48, v48, v49, vcc
	v_pk_mul_f32 v[44:45], v[44:45], v[48:49] op_sel_hi:[1,0]
	s_nop 0
	v_mul_f32_e32 v49, 0xbfb8aa3b, v44
	v_exp_f32_e32 v50, v49
	v_mul_f32_e32 v49, 0xbfb8aa3b, v45
	v_exp_f32_e32 v51, v49
	s_nop 0
	v_pk_add_f32 v[50:51], v[50:51], 1.0 op_sel_hi:[1,0]
	s_nop 0
	v_pk_mul_f32 v[40:41], v[40:41], v[48:49] op_sel_hi:[1,0]
	v_rcp_f32_e32 v51, v51
	v_pk_mul_f32 v[46:47], v[46:47], v[48:49] op_sel_hi:[1,0]
	v_mul_f32_e32 v52, 0xbfb8aa3b, v46
	v_mul_f32_e32 v53, 0xbfb8aa3b, v47
	v_exp_f32_e32 v52, v52
	v_exp_f32_e32 v53, v53
	v_rcp_f32_e32 v50, v50
	s_nop 0
	v_pk_mul_f32 v[44:45], v[44:45], v[50:51]
	v_pk_add_f32 v[52:53], v[52:53], 1.0 op_sel_hi:[1,0]
	s_nop 0
	v_pk_mul_f32 v[40:41], v[40:41], v[44:45]
	v_pk_mul_f32 v[42:43], v[42:43], v[48:49] op_sel_hi:[1,0]
	v_rcp_f32_e32 v45, v53
	v_pk_mul_f32 v[36:37], v[36:37], v[48:49] op_sel_hi:[1,0]
	v_mul_f32_e32 v49, 0xbfb8aa3b, v36
	v_exp_f32_e32 v50, v49
	v_mul_f32_e32 v49, 0xbfb8aa3b, v37
	v_exp_f32_e32 v51, v49
	v_rcp_f32_e32 v44, v52
	s_nop 0
	v_pk_mul_f32 v[44:45], v[46:47], v[44:45]
	v_pk_add_f32 v[50:51], v[50:51], 1.0 op_sel_hi:[1,0]
	v_pk_mul_f32 v[42:43], v[42:43], v[44:45]
	v_pk_mul_f32 v[32:33], v[32:33], v[48:49] op_sel_hi:[1,0]
	v_rcp_f32_e32 v45, v51
	v_pk_mul_f32 v[38:39], v[38:39], v[48:49] op_sel_hi:[1,0]
	v_mul_f32_e32 v46, 0xbfb8aa3b, v38
	v_mul_f32_e32 v47, 0xbfb8aa3b, v39
	v_exp_f32_e32 v46, v46
	v_exp_f32_e32 v47, v47
	v_rcp_f32_e32 v44, v50
	s_nop 0
	v_pk_mul_f32 v[36:37], v[36:37], v[44:45]
	v_pk_add_f32 v[46:47], v[46:47], 1.0 op_sel_hi:[1,0]
	v_pk_mul_f32 v[36:37], v[32:33], v[36:37]
	v_pk_mul_f32 v[32:33], v[34:35], v[48:49] op_sel_hi:[1,0]
	v_rcp_f32_e32 v35, v47
	v_rcp_f32_e32 v34, v46
	s_nop 0
	v_pk_mul_f32 v[34:35], v[38:39], v[34:35]
	s_nop 0
	v_pk_mul_f32 v[38:39], v[32:33], v[34:35]
	v_cvt_pk_bf16_f32 v34, v36, v37
	v_mad_i64_i32 v[36:37], s[0:1], v54, s44, v[112:113]
	v_cvt_pk_bf16_f32 v32, v40, v41
	v_cvt_pk_bf16_f32 v33, v42, v43
	v_cvt_pk_bf16_f32 v35, v38, v39
	v_lshl_add_u64 v[36:37], v[36:37], 0, v[114:115]
	global_store_dwordx4 v[36:37], v[32:35], off
	s_nop 0
	v_add_u32_e32 v38, 0xa0, v144
	s_nop 0
	v_fmamk_f32 v32, v253, 0x3a800000, v158
	v_mul_f32_e32 v33, 0x4b800000, v32
	v_cmp_gt_f32_e32 vcc, s43, v32
	s_nop 1
	v_cndmask_b32_e32 v32, v32, v33, vcc
	v_rsq_f32_e32 v32, v32
	s_nop 0
	v_mul_f32_e32 v33, 0x45800000, v32
; DI unsigned pk2(float lo, float hi) { f32x2_t v = {lo, hi}; bf16x2_t b = __builtin_convertvector(v, bf16x2_t); return __builtin_bit_cast(unsigned, b); }
; DI float sigmoidf_(float x) { return 1.0f / (1.0f + __expf(-x)); }
;     DI void operator()(AccRef acc, const Unit& u, int wr, int wc, int fr, int fq) const {
;     ...
;             for (int m = 0; m < 4; ++m) {
;                 const int row = row0 + ai * HALF + m * 16; const float rs = rsqrtf(SS1[row] * (1.0f / DM) + EPSN);
;                 float h[8];
; #pragma unroll
;                 for (int n = 0; n < 2; ++n)
; #pragma unroll
;                     for (int e = 0; e < 4; ++e) { const float g = acc[ai][0][m][n][e] * rs, up = acc[ai][1][m][n][e] * rs; h[4 * n + e] = g * sigmoidf_(g) * up; }
;                 u32x4 w; w.x = pk2(h[0], h[1]); w.y = pk2(h[2], h[3]); w.z = pk2(h[4], h[5]); w.w = pk2(h[6], h[7]);
;                 *(u32x4*)(H + (size_t)row * DFF + col0) = w;
	v_cndmask_b32_e32 v32, v32, v33, vcc
	v_pk_mul_f32 v[28:29], v[28:29], v[32:33] op_sel_hi:[1,0]
	s_nop 0
	v_mul_f32_e32 v33, 0xbfb8aa3b, v28
	v_exp_f32_e32 v34, v33
	v_mul_f32_e32 v33, 0xbfb8aa3b, v29
	v_exp_f32_e32 v35, v33
	s_nop 0
	v_pk_add_f32 v[34:35], v[34:35], 1.0 op_sel_hi:[1,0]
	s_nop 0
	v_pk_mul_f32 v[24:25], v[24:25], v[32:33] op_sel_hi:[1,0]
	v_rcp_f32_e32 v35, v35
	v_pk_mul_f32 v[30:31], v[30:31], v[32:33] op_sel_hi:[1,0]
	v_mul_f32_e32 v36, 0xbfb8aa3b, v30
	v_mul_f32_e32 v37, 0xbfb8aa3b, v31
	v_exp_f32_e32 v36, v36
	v_exp_f32_e32 v37, v37
	v_rcp_f32_e32 v34, v34
	s_nop 0
	v_pk_mul_f32 v[28:29], v[28:29], v[34:35]
	v_pk_add_f32 v[36:37], v[36:37], 1.0 op_sel_hi:[1,0]
	s_nop 0
	v_pk_mul_f32 v[24:25], v[24:25], v[28:29]
	v_pk_mul_f32 v[26:27], v[26:27], v[32:33] op_sel_hi:[1,0]
	v_rcp_f32_e32 v29, v37
	v_pk_mul_f32 v[20:21], v[20:21], v[32:33] op_sel_hi:[1,0]
	v_mul_f32_e32 v33, 0xbfb8aa3b, v20
	v_exp_f32_e32 v34, v33
	v_mul_f32_e32 v33, 0xbfb8aa3b, v21
	v_exp_f32_e32 v35, v33
	v_rcp_f32_e32 v28, v36
	s_nop 0
	v_pk_mul_f32 v[28:29], v[30:31], v[28:29]
	v_pk_add_f32 v[34:35], v[34:35], 1.0 op_sel_hi:[1,0]
	v_pk_mul_f32 v[26:27], v[26:27], v[28:29]
	v_pk_mul_f32 v[16:17], v[16:17], v[32:33] op_sel_hi:[1,0]
	v_rcp_f32_e32 v29, v35
	v_pk_mul_f32 v[22:23], v[22:23], v[32:33] op_sel_hi:[1,0]
	v_mul_f32_e32 v30, 0xbfb8aa3b, v22
	v_mul_f32_e32 v31, 0xbfb8aa3b, v23
	v_exp_f32_e32 v30, v30
	v_exp_f32_e32 v31, v31
	v_rcp_f32_e32 v28, v34
	s_nop 0
	v_pk_mul_f32 v[20:21], v[20:21], v[28:29]
	v_pk_add_f32 v[30:31], v[30:31], 1.0 op_sel_hi:[1,0]
	v_pk_mul_f32 v[20:21], v[16:17], v[20:21]
	v_pk_mul_f32 v[16:17], v[18:19], v[32:33] op_sel_hi:[1,0]
	v_rcp_f32_e32 v19, v31
	v_rcp_f32_e32 v18, v30
	s_nop 0
	v_pk_mul_f32 v[18:19], v[22:23], v[18:19]
	s_nop 0
	v_pk_mul_f32 v[22:23], v[16:17], v[18:19]
	v_cvt_pk_bf16_f32 v18, v20, v21
	v_mad_i64_i32 v[20:21], s[0:1], v38, s44, v[112:113]
	v_cvt_pk_bf16_f32 v16, v24, v25
	v_cvt_pk_bf16_f32 v17, v26, v27
	v_cvt_pk_bf16_f32 v19, v22, v23
	v_lshl_add_u64 v[20:21], v[20:21], 0, v[114:115]
	global_store_dwordx4 v[20:21], v[16:19], off
	s_nop 0
	v_add_u32_e32 v22, 0xb0, v144
	s_nop 0
	v_fmamk_f32 v16, v254, 0x3a800000, v158
	v_mul_f32_e32 v17, 0x4b800000, v16
	v_cmp_gt_f32_e32 vcc, s43, v16
	s_nop 1
	v_cndmask_b32_e32 v16, v16, v17, vcc
	v_rsq_f32_e32 v16, v16
	s_nop 0
	v_mul_f32_e32 v17, 0x45800000, v16
	v_cndmask_b32_e32 v16, v16, v17, vcc
	v_pk_mul_f32 v[12:13], v[12:13], v[16:17] op_sel_hi:[1,0]
	s_nop 0
	v_mul_f32_e32 v17, 0xbfb8aa3b, v12
	v_exp_f32_e32 v18, v17
	v_mul_f32_e32 v17, 0xbfb8aa3b, v13
	v_exp_f32_e32 v19, v17
	s_nop 0
	v_pk_add_f32 v[18:19], v[18:19], 1.0 op_sel_hi:[1,0]
	s_nop 0
	v_pk_mul_f32 v[8:9], v[8:9], v[16:17] op_sel_hi:[1,0]
	v_rcp_f32_e32 v19, v19
	v_pk_mul_f32 v[14:15], v[14:15], v[16:17] op_sel_hi:[1,0]
	v_mul_f32_e32 v20, 0xbfb8aa3b, v14
	v_mul_f32_e32 v21, 0xbfb8aa3b, v15
	v_exp_f32_e32 v20, v20
	v_exp_f32_e32 v21, v21
	v_rcp_f32_e32 v18, v18
	s_nop 0
	v_pk_mul_f32 v[12:13], v[12:13], v[18:19]
	v_pk_add_f32 v[20:21], v[20:21], 1.0 op_sel_hi:[1,0]
	s_nop 0
	v_pk_mul_f32 v[8:9], v[8:9], v[12:13]
	v_pk_mul_f32 v[10:11], v[10:11], v[16:17] op_sel_hi:[1,0]
	v_rcp_f32_e32 v13, v21
	v_pk_mul_f32 v[4:5], v[4:5], v[16:17] op_sel_hi:[1,0]
	v_mul_f32_e32 v17, 0xbfb8aa3b, v4
	v_exp_f32_e32 v18, v17
	v_mul_f32_e32 v17, 0xbfb8aa3b, v5
	v_exp_f32_e32 v19, v17
	v_rcp_f32_e32 v12, v20
	s_nop 0
	v_pk_mul_f32 v[12:13], v[14:15], v[12:13]
	v_pk_add_f32 v[18:19], v[18:19], 1.0 op_sel_hi:[1,0]
	v_pk_mul_f32 v[10:11], v[10:11], v[12:13]
	v_pk_mul_f32 v[0:1], v[0:1], v[16:17] op_sel_hi:[1,0]
	v_rcp_f32_e32 v13, v19
	v_pk_mul_f32 v[6:7], v[6:7], v[16:17] op_sel_hi:[1,0]
	v_mul_f32_e32 v14, 0xbfb8aa3b, v6
	v_mul_f32_e32 v15, 0xbfb8aa3b, v7
	v_exp_f32_e32 v14, v14
	v_exp_f32_e32 v15, v15
	v_rcp_f32_e32 v12, v18
	s_nop 0
	v_pk_mul_f32 v[4:5], v[4:5], v[12:13]
	v_pk_add_f32 v[14:15], v[14:15], 1.0 op_sel_hi:[1,0]
	v_pk_mul_f32 v[4:5], v[0:1], v[4:5]
	v_pk_mul_f32 v[0:1], v[2:3], v[16:17] op_sel_hi:[1,0]
	v_rcp_f32_e32 v3, v15
	v_rcp_f32_e32 v2, v14
	s_nop 0
	v_pk_mul_f32 v[2:3], v[6:7], v[2:3]
	s_andn2_b64 vcc, exec, s[2:3]
	v_pk_mul_f32 v[6:7], v[0:1], v[2:3]
	v_cvt_pk_bf16_f32 v2, v4, v5
	v_mad_i64_i32 v[4:5], s[0:1], v22, s44, v[112:113]
	v_cvt_pk_bf16_f32 v0, v8, v9
	v_cvt_pk_bf16_f32 v1, v10, v11
	v_cvt_pk_bf16_f32 v3, v6, v7
	v_lshl_add_u64 v[4:5], v[4:5], 0, v[114:115]
	s_mov_b64 s[0:1], -1
	global_store_dwordx4 v[4:5], v[0:3], off
	s_cbranch_vccnz .LBB0_1483
	s_andn2_b64 vcc, exec, s[14:15]
	s_cbranch_vccnz .LBB0_1482
	s_barrier
	s_branch .LBB0_1482

; DI unsigned pk2(float lo, float hi) { f32x2_t v = {lo, hi}; bf16x2_t b = __builtin_convertvector(v, bf16x2_t); return __builtin_bit_cast(unsigned, b); }
; DI float sigmoidf_(float x) { return 1.0f / (1.0f + __expf(-x)); }
;     DI void operator()(AccRef acc, const Unit& u, int wr, int wc, int fr, int fq) const {
;     ...
;             for (int m = 0; m < 4; ++m) {
;                 const int row = row0 + ai * HALF + m * 16; const float rs = rsqrtf(SS1[row] * (1.0f / DM) + EPSN);
;                 float h[8];
; #pragma unroll
;                 for (int n = 0; n < 2; ++n)
; #pragma unroll
;                     for (int e = 0; e < 4; ++e) { const float g = acc[ai][0][m][n][e] * rs, up = acc[ai][1][m][n][e] * rs; h[4 * n + e] = g * sigmoidf_(g) * up; }
;                 u32x4 w; w.x = pk2(h[0], h[1]); w.y = pk2(h[2], h[3]); w.z = pk2(h[4], h[5]); w.w = pk2(h[6], h[7]);
;                 *(u32x4*)(H + (size_t)row * DFF + col0) = w;
.LBB0_1669:
	v_lshl_add_u32 v144, s0, 8, v149
	v_ashrrev_i32_e32 v145, 31, v144
	v_lshl_add_u64 v[146:147], v[144:145], 2, s[18:19]
	global_load_dword v145, v[146:147], off
	global_load_dword v248, v[146:147], off offset:64
	global_load_dword v249, v[146:147], off offset:128
	global_load_dword v250, v[146:147], off offset:192
	global_load_dword v251, v[146:147], off offset:512
	global_load_dword v252, v[146:147], off offset:576
	global_load_dword v253, v[146:147], off offset:640
	global_load_dword v254, v[146:147], off offset:704
	s_waitcnt vmcnt(0)
	v_fmamk_f32 v145, v145, 0x3a800000, v158
	v_mul_f32_e32 v152, 0x4b800000, v145
	v_cmp_gt_f32_e32 vcc, s51, v145
	s_nop 1
	v_cndmask_b32_e32 v145, v145, v152, vcc
	v_rsq_f32_e32 v145, v145
	v_lshl_or_b32 v152, s1, 7, v154
	v_ashrrev_i32_e32 v153, 31, v152
	v_mul_f32_e32 v159, 0x45800000, v145
	v_cndmask_b32_e32 v160, v145, v159, vcc
	v_pk_mul_f32 v[124:125], v[124:125], v[160:161] op_sel_hi:[1,0]
	v_pk_mul_f32 v[126:127], v[126:127], v[160:161] op_sel_hi:[1,0]
	v_mul_f32_e32 v145, 0xbfb8aa3b, v124
	v_mul_f32_e32 v159, 0xbfb8aa3b, v125
	v_exp_f32_e32 v162, v145
	v_exp_f32_e32 v163, v159
	v_pk_mul_f32 v[120:121], v[120:121], v[160:161] op_sel_hi:[1,0]
	v_pk_mul_f32 v[122:123], v[122:123], v[160:161] op_sel_hi:[1,0]
	v_pk_mul_f32 v[116:117], v[116:117], v[160:161] op_sel_hi:[1,0]
	v_mul_f32_e32 v161, 0xbfb8aa3b, v126
	v_mul_f32_e32 v165, 0xbfb8aa3b, v127
	v_exp_f32_e32 v164, v161
	v_exp_f32_e32 v165, v165
	v_pk_add_f32 v[162:163], v[162:163], 1.0 op_sel_hi:[1,0]
	v_pk_mul_f32 v[112:113], v[112:113], v[160:161] op_sel_hi:[1,0]
	v_pk_add_f32 v[164:165], v[164:165], 1.0 op_sel_hi:[1,0]
	v_mul_f32_e32 v166, 0xbfb8aa3b, v116
	v_mul_f32_e32 v167, 0xbfb8aa3b, v117
	v_exp_f32_e32 v166, v166
	v_exp_f32_e32 v167, v167
	s_nop 0
	v_pk_add_f32 v[166:167], v[166:167], 1.0 op_sel_hi:[1,0]
	v_rcp_f32_e32 v163, v163
	v_rcp_f32_e32 v162, v162
	s_nop 0
	v_pk_mul_f32 v[124:125], v[124:125], v[162:163]
	v_rcp_f32_e32 v163, v165
	v_rcp_f32_e32 v162, v164
	v_pk_mul_f32 v[120:121], v[120:121], v[124:125]
	v_pk_mul_f32 v[124:125], v[126:127], v[162:163]
	v_pk_mul_f32 v[118:119], v[118:119], v[160:161] op_sel_hi:[1,0]
	v_pk_mul_f32 v[122:123], v[122:123], v[124:125]
	v_mul_f32_e32 v124, 0xbfb8aa3b, v118
	v_mul_f32_e32 v125, 0xbfb8aa3b, v119
	v_exp_f32_e32 v124, v124
	v_exp_f32_e32 v125, v125
	s_nop 0
	v_pk_add_f32 v[124:125], v[124:125], 1.0 op_sel_hi:[1,0]
	v_rcp_f32_e32 v127, v167
	v_rcp_f32_e32 v126, v166
	s_nop 0
	v_pk_mul_f32 v[116:117], v[116:117], v[126:127]
	v_pk_mul_f32 v[114:115], v[114:115], v[160:161] op_sel_hi:[1,0]
	v_pk_mul_f32 v[112:113], v[112:113], v[116:117]
	v_rcp_f32_e32 v117, v125
	v_rcp_f32_e32 v116, v124
	s_nop 0
	v_pk_mul_f32 v[116:117], v[118:119], v[116:117]
	v_cvt_pk_bf16_f32 v118, v112, v113
	v_pk_mul_f32 v[114:115], v[114:115], v[116:117]
	v_mov_b64_e32 v[112:113], s[48:49]
	v_cvt_pk_bf16_f32 v116, v120, v121
	v_cvt_pk_bf16_f32 v119, v114, v115
	v_mad_i64_i32 v[120:121], s[0:1], v144, s52, v[112:113]
	v_lshlrev_b64 v[114:115], 1, v[152:153]
	v_cvt_pk_bf16_f32 v117, v122, v123
	v_lshl_add_u64 v[120:121], v[120:121], 0, v[114:115]
	global_store_dwordx4 v[120:121], v[116:119], off
	s_nop 1
	v_or_b32_e32 v116, 16, v144
	v_ashrrev_i32_e32 v117, 31, v116
	v_lshl_add_u64 v[118:119], v[116:117], 2, s[18:19]
	s_nop 0
	s_nop 0
	v_fmamk_f32 v117, v248, 0x3a800000, v158
	v_mul_f32_e32 v118, 0x4b800000, v117
	v_cmp_gt_f32_e32 vcc, s51, v117
	s_nop 1
	v_cndmask_b32_e32 v117, v117, v118, vcc
	v_rsq_f32_e32 v117, v117
	s_nop 0
	v_mul_f32_e32 v118, 0x45800000, v117
	v_cndmask_b32_e32 v118, v117, v118, vcc
	v_pk_mul_f32 v[108:109], v[108:109], v[118:119] op_sel_hi:[1,0]
	v_pk_mul_f32 v[110:111], v[110:111], v[118:119] op_sel_hi:[1,0]
	v_mul_f32_e32 v117, 0xbfb8aa3b, v108
	v_mul_f32_e32 v119, 0xbfb8aa3b, v109
	v_exp_f32_e32 v120, v117
	v_exp_f32_e32 v121, v119
	v_mul_f32_e32 v122, 0xbfb8aa3b, v110
	v_mul_f32_e32 v123, 0xbfb8aa3b, v111
	v_exp_f32_e32 v122, v122
	v_pk_add_f32 v[120:121], v[120:121], 1.0 op_sel_hi:[1,0]
	v_exp_f32_e32 v123, v123
	s_nop 0
	v_pk_add_f32 v[122:123], v[122:123], 1.0 op_sel_hi:[1,0]
	v_pk_mul_f32 v[104:105], v[104:105], v[118:119] op_sel_hi:[1,0]
	v_pk_mul_f32 v[106:107], v[106:107], v[118:119] op_sel_hi:[1,0]
	v_rcp_f32_e32 v121, v121
	v_rcp_f32_e32 v120, v120
	s_nop 0
	v_pk_mul_f32 v[108:109], v[108:109], v[120:121]
	v_pk_mul_f32 v[104:105], v[104:105], v[108:109]
	v_rcp_f32_e32 v109, v123
	v_pk_mul_f32 v[100:101], v[100:101], v[118:119] op_sel_hi:[1,0]
	v_mul_f32_e32 v117, 0xbfb8aa3b, v100
	v_exp_f32_e32 v120, v117
	v_mul_f32_e32 v117, 0xbfb8aa3b, v101
	v_exp_f32_e32 v121, v117
	v_rcp_f32_e32 v108, v122
	s_nop 0
	v_pk_mul_f32 v[108:109], v[110:111], v[108:109]
	v_pk_add_f32 v[120:121], v[120:121], 1.0 op_sel_hi:[1,0]
	v_pk_mul_f32 v[106:107], v[106:107], v[108:109]
	s_nop 0
	v_pk_mul_f32 v[96:97], v[96:97], v[118:119] op_sel_hi:[1,0]
	v_rcp_f32_e32 v109, v121
	v_pk_mul_f32 v[102:103], v[102:103], v[118:119] op_sel_hi:[1,0]
	v_mul_f32_e32 v110, 0xbfb8aa3b, v102
	v_mul_f32_e32 v111, 0xbfb8aa3b, v103
	v_exp_f32_e32 v110, v110
	v_exp_f32_e32 v111, v111
	v_rcp_f32_e32 v108, v120
	s_nop 0
	v_pk_mul_f32 v[100:101], v[100:101], v[108:109]
	v_pk_add_f32 v[110:111], v[110:111], 1.0 op_sel_hi:[1,0]
	v_pk_mul_f32 v[100:101], v[96:97], v[100:101]
	s_nop 0
	v_pk_mul_f32 v[96:97], v[98:99], v[118:119] op_sel_hi:[1,0]
	v_rcp_f32_e32 v99, v111
	v_rcp_f32_e32 v98, v110
	s_nop 0
	v_pk_mul_f32 v[98:99], v[102:103], v[98:99]
	s_nop 0
	v_pk_mul_f32 v[102:103], v[96:97], v[98:99]
	v_cvt_pk_bf16_f32 v98, v100, v101
	v_mad_i64_i32 v[100:101], s[0:1], v116, s52, v[112:113]
	v_cvt_pk_bf16_f32 v96, v104, v105
; DI unsigned pk2(float lo, float hi) { f32x2_t v = {lo, hi}; bf16x2_t b = __builtin_convertvector(v, bf16x2_t); return __builtin_bit_cast(unsigned, b); }
; DI float sigmoidf_(float x) { return 1.0f / (1.0f + __expf(-x)); }
;     DI void operator()(AccRef acc, const Unit& u, int wr, int wc, int fr, int fq) const {
;     ...
;             for (int m = 0; m < 4; ++m) {
;                 const int row = row0 + ai * HALF + m * 16; const float rs = rsqrtf(SS1[row] * (1.0f / DM) + EPSN);
;                 float h[8];
; #pragma unroll
;                 for (int n = 0; n < 2; ++n)
; #pragma unroll
;                     for (int e = 0; e < 4; ++e) { const float g = acc[ai][0][m][n][e] * rs, up = acc[ai][1][m][n][e] * rs; h[4 * n + e] = g * sigmoidf_(g) * up; }
;                 u32x4 w; w.x = pk2(h[0], h[1]); w.y = pk2(h[2], h[3]); w.z = pk2(h[4], h[5]); w.w = pk2(h[6], h[7]);
;                 *(u32x4*)(H + (size_t)row * DFF + col0) = w;
	v_cvt_pk_bf16_f32 v97, v106, v107
	v_cvt_pk_bf16_f32 v99, v102, v103
	v_lshl_add_u64 v[100:101], v[100:101], 0, v[114:115]
	global_store_dwordx4 v[100:101], v[96:99], off
	s_nop 1
	v_or_b32_e32 v96, 32, v144
	v_ashrrev_i32_e32 v97, 31, v96
	v_lshl_add_u64 v[98:99], v[96:97], 2, s[18:19]
	s_nop 0
	s_nop 0
	v_fmamk_f32 v97, v249, 0x3a800000, v158
	v_mul_f32_e32 v98, 0x4b800000, v97
	v_cmp_gt_f32_e32 vcc, s51, v97
	s_nop 1
	v_cndmask_b32_e32 v97, v97, v98, vcc
	v_rsq_f32_e32 v97, v97
	s_nop 0
	v_mul_f32_e32 v98, 0x45800000, v97
	v_cndmask_b32_e32 v98, v97, v98, vcc
	v_pk_mul_f32 v[92:93], v[92:93], v[98:99] op_sel_hi:[1,0]
	s_nop 0
	v_mul_f32_e32 v97, 0xbfb8aa3b, v92
	v_exp_f32_e32 v100, v97
	v_mul_f32_e32 v97, 0xbfb8aa3b, v93
	v_exp_f32_e32 v101, v97
	s_nop 0
	v_pk_add_f32 v[100:101], v[100:101], 1.0 op_sel_hi:[1,0]
	s_nop 0
	s_nop 0
	v_pk_mul_f32 v[88:89], v[88:89], v[98:99] op_sel_hi:[1,0]
	v_rcp_f32_e32 v101, v101
	v_pk_mul_f32 v[94:95], v[94:95], v[98:99] op_sel_hi:[1,0]
	v_mul_f32_e32 v102, 0xbfb8aa3b, v94
	v_mul_f32_e32 v103, 0xbfb8aa3b, v95
	v_exp_f32_e32 v102, v102
	v_exp_f32_e32 v103, v103
	v_rcp_f32_e32 v100, v100
	s_nop 0
	v_pk_mul_f32 v[92:93], v[92:93], v[100:101]
	v_pk_add_f32 v[102:103], v[102:103], 1.0 op_sel_hi:[1,0]
	v_pk_mul_f32 v[88:89], v[88:89], v[92:93]
	s_nop 0
	v_pk_mul_f32 v[90:91], v[90:91], v[98:99] op_sel_hi:[1,0]
	v_rcp_f32_e32 v93, v103
	v_pk_mul_f32 v[84:85], v[84:85], v[98:99] op_sel_hi:[1,0]
	v_mul_f32_e32 v97, 0xbfb8aa3b, v84
	v_exp_f32_e32 v100, v97
	v_mul_f32_e32 v97, 0xbfb8aa3b, v85
	v_exp_f32_e32 v101, v97
	v_rcp_f32_e32 v92, v102
	s_nop 0
	v_pk_mul_f32 v[92:93], v[94:95], v[92:93]
	v_pk_add_f32 v[100:101], v[100:101], 1.0 op_sel_hi:[1,0]
	v_pk_mul_f32 v[90:91], v[90:91], v[92:93]
	s_nop 0
	v_pk_mul_f32 v[80:81], v[80:81], v[98:99] op_sel_hi:[1,0]
	v_rcp_f32_e32 v93, v101
	v_pk_mul_f32 v[86:87], v[86:87], v[98:99] op_sel_hi:[1,0]
	v_mul_f32_e32 v94, 0xbfb8aa3b, v86
	v_mul_f32_e32 v95, 0xbfb8aa3b, v87
	v_exp_f32_e32 v94, v94
	v_exp_f32_e32 v95, v95
	v_rcp_f32_e32 v92, v100
	s_nop 0
	v_pk_mul_f32 v[84:85], v[84:85], v[92:93]
	v_pk_add_f32 v[94:95], v[94:95], 1.0 op_sel_hi:[1,0]
	v_pk_mul_f32 v[84:85], v[80:81], v[84:85]
	s_nop 0
	v_pk_mul_f32 v[80:81], v[82:83], v[98:99] op_sel_hi:[1,0]
	v_rcp_f32_e32 v83, v95
	v_rcp_f32_e32 v82, v94
	s_nop 0
	v_pk_mul_f32 v[82:83], v[86:87], v[82:83]
	s_nop 0
	v_pk_mul_f32 v[86:87], v[80:81], v[82:83]
	v_cvt_pk_bf16_f32 v82, v84, v85
	v_mad_i64_i32 v[84:85], s[0:1], v96, s52, v[112:113]
	v_cvt_pk_bf16_f32 v80, v88, v89
	v_cvt_pk_bf16_f32 v81, v90, v91
	v_cvt_pk_bf16_f32 v83, v86, v87
	v_lshl_add_u64 v[84:85], v[84:85], 0, v[114:115]
	global_store_dwordx4 v[84:85], v[80:83], off
	s_nop 1
	v_or_b32_e32 v80, 48, v144
	v_ashrrev_i32_e32 v81, 31, v80
	v_lshl_add_u64 v[82:83], v[80:81], 2, s[18:19]
	s_nop 0
	s_nop 0
	v_fmamk_f32 v81, v250, 0x3a800000, v158
	v_mul_f32_e32 v82, 0x4b800000, v81
	v_cmp_gt_f32_e32 vcc, s51, v81
	s_nop 1
	v_cndmask_b32_e32 v81, v81, v82, vcc
	v_rsq_f32_e32 v81, v81
	s_nop 0
	v_mul_f32_e32 v82, 0x45800000, v81
	v_cndmask_b32_e32 v82, v81, v82, vcc
	v_pk_mul_f32 v[76:77], v[76:77], v[82:83] op_sel_hi:[1,0]
	s_nop 0
	v_mul_f32_e32 v81, 0xbfb8aa3b, v76
	v_exp_f32_e32 v84, v81
	v_mul_f32_e32 v81, 0xbfb8aa3b, v77
	v_exp_f32_e32 v85, v81
	s_nop 0
	v_pk_add_f32 v[84:85], v[84:85], 1.0 op_sel_hi:[1,0]
	s_nop 0
	s_nop 0
	v_pk_mul_f32 v[72:73], v[72:73], v[82:83] op_sel_hi:[1,0]
	v_rcp_f32_e32 v85, v85
	v_pk_mul_f32 v[78:79], v[78:79], v[82:83] op_sel_hi:[1,0]
	v_mul_f32_e32 v86, 0xbfb8aa3b, v78
	v_mul_f32_e32 v87, 0xbfb8aa3b, v79
	v_exp_f32_e32 v86, v86
	v_exp_f32_e32 v87, v87
	v_rcp_f32_e32 v84, v84
	s_nop 0
	v_pk_mul_f32 v[76:77], v[76:77], v[84:85]
	v_pk_add_f32 v[86:87], v[86:87], 1.0 op_sel_hi:[1,0]
	v_pk_mul_f32 v[72:73], v[72:73], v[76:77]
	s_nop 0
	v_pk_mul_f32 v[74:75], v[74:75], v[82:83] op_sel_hi:[1,0]
	v_rcp_f32_e32 v77, v87
	v_pk_mul_f32 v[68:69], v[68:69], v[82:83] op_sel_hi:[1,0]
	v_mul_f32_e32 v81, 0xbfb8aa3b, v68
	v_exp_f32_e32 v84, v81
	v_mul_f32_e32 v81, 0xbfb8aa3b, v69
	v_exp_f32_e32 v85, v81
	v_rcp_f32_e32 v76, v86
	s_nop 0
	v_pk_mul_f32 v[76:77], v[78:79], v[76:77]
	v_pk_add_f32 v[84:85], v[84:85], 1.0 op_sel_hi:[1,0]
	v_pk_mul_f32 v[74:75], v[74:75], v[76:77]
	s_nop 0
	v_pk_mul_f32 v[64:65], v[64:65], v[82:83] op_sel_hi:[1,0]
	v_rcp_f32_e32 v77, v85
	v_pk_mul_f32 v[70:71], v[70:71], v[82:83] op_sel_hi:[1,0]
	v_mul_f32_e32 v78, 0xbfb8aa3b, v70
	v_mul_f32_e32 v79, 0xbfb8aa3b, v71
	v_exp_f32_e32 v78, v78
	v_exp_f32_e32 v79, v79
	v_rcp_f32_e32 v76, v84
	s_nop 0
	v_pk_mul_f32 v[68:69], v[68:69], v[76:77]
	v_pk_add_f32 v[78:79], v[78:79], 1.0 op_sel_hi:[1,0]
	v_pk_mul_f32 v[68:69], v[64:65], v[68:69]
	s_nop 0
	v_pk_mul_f32 v[64:65], v[66:67], v[82:83] op_sel_hi:[1,0]
	v_rcp_f32_e32 v67, v79
	v_rcp_f32_e32 v66, v78
	s_nop 0
	v_pk_mul_f32 v[66:67], v[70:71], v[66:67]
	s_nop 0
	v_pk_mul_f32 v[70:71], v[64:65], v[66:67]
	v_cvt_pk_bf16_f32 v66, v68, v69
	v_mad_i64_i32 v[68:69], s[0:1], v80, s52, v[112:113]
	v_cvt_pk_bf16_f32 v64, v72, v73
	v_cvt_pk_bf16_f32 v65, v74, v75
	v_cvt_pk_bf16_f32 v67, v70, v71
	v_lshl_add_u64 v[68:69], v[68:69], 0, v[114:115]
	global_store_dwordx4 v[68:69], v[64:67], off
	s_nop 0
	v_add_u32_e32 v70, 0x80, v144
	s_nop 0
	v_fmamk_f32 v64, v251, 0x3a800000, v158
	v_mul_f32_e32 v65, 0x4b800000, v64
	v_cmp_gt_f32_e32 vcc, s51, v64
	s_nop 1
	v_cndmask_b32_e32 v64, v64, v65, vcc
	v_rsq_f32_e32 v64, v64
	s_nop 0
	v_mul_f32_e32 v65, 0x45800000, v64
	v_cndmask_b32_e32 v64, v64, v65, vcc
	v_pk_mul_f32 v[60:61], v[60:61], v[64:65] op_sel_hi:[1,0]
	s_nop 0
	v_mul_f32_e32 v65, 0xbfb8aa3b, v60
	v_exp_f32_e32 v66, v65
; DI unsigned pk2(float lo, float hi) { f32x2_t v = {lo, hi}; bf16x2_t b = __builtin_convertvector(v, bf16x2_t); return __builtin_bit_cast(unsigned, b); }
; DI float sigmoidf_(float x) { return 1.0f / (1.0f + __expf(-x)); }
;     DI void operator()(AccRef acc, const Unit& u, int wr, int wc, int fr, int fq) const {
;     ...
;             for (int m = 0; m < 4; ++m) {
;                 const int row = row0 + ai * HALF + m * 16; const float rs = rsqrtf(SS1[row] * (1.0f / DM) + EPSN);
;                 float h[8];
; #pragma unroll
;                 for (int n = 0; n < 2; ++n)
; #pragma unroll
;                     for (int e = 0; e < 4; ++e) { const float g = acc[ai][0][m][n][e] * rs, up = acc[ai][1][m][n][e] * rs; h[4 * n + e] = g * sigmoidf_(g) * up; }
;                 u32x4 w; w.x = pk2(h[0], h[1]); w.y = pk2(h[2], h[3]); w.z = pk2(h[4], h[5]); w.w = pk2(h[6], h[7]);
;                 *(u32x4*)(H + (size_t)row * DFF + col0) = w;
	v_mul_f32_e32 v65, 0xbfb8aa3b, v61
	v_exp_f32_e32 v67, v65
	s_nop 0
	v_pk_add_f32 v[66:67], v[66:67], 1.0 op_sel_hi:[1,0]
	s_nop 0
	v_pk_mul_f32 v[56:57], v[56:57], v[64:65] op_sel_hi:[1,0]
	v_rcp_f32_e32 v67, v67
	v_pk_mul_f32 v[62:63], v[62:63], v[64:65] op_sel_hi:[1,0]
	v_mul_f32_e32 v68, 0xbfb8aa3b, v62
	v_mul_f32_e32 v69, 0xbfb8aa3b, v63
	v_exp_f32_e32 v68, v68
	v_exp_f32_e32 v69, v69
	v_rcp_f32_e32 v66, v66
	s_nop 0
	v_pk_mul_f32 v[60:61], v[60:61], v[66:67]
	v_pk_add_f32 v[68:69], v[68:69], 1.0 op_sel_hi:[1,0]
	s_nop 0
	v_pk_mul_f32 v[56:57], v[56:57], v[60:61]
	v_pk_mul_f32 v[58:59], v[58:59], v[64:65] op_sel_hi:[1,0]
	v_rcp_f32_e32 v61, v69
	v_pk_mul_f32 v[52:53], v[52:53], v[64:65] op_sel_hi:[1,0]
	v_mul_f32_e32 v65, 0xbfb8aa3b, v52
	v_exp_f32_e32 v66, v65
	v_mul_f32_e32 v65, 0xbfb8aa3b, v53
	v_exp_f32_e32 v67, v65
	v_rcp_f32_e32 v60, v68
	s_nop 0
	v_pk_mul_f32 v[60:61], v[62:63], v[60:61]
	v_pk_add_f32 v[66:67], v[66:67], 1.0 op_sel_hi:[1,0]
	v_pk_mul_f32 v[58:59], v[58:59], v[60:61]
	v_pk_mul_f32 v[48:49], v[48:49], v[64:65] op_sel_hi:[1,0]
	v_rcp_f32_e32 v61, v67
	v_pk_mul_f32 v[54:55], v[54:55], v[64:65] op_sel_hi:[1,0]
	v_mul_f32_e32 v62, 0xbfb8aa3b, v54
	v_mul_f32_e32 v63, 0xbfb8aa3b, v55
	v_exp_f32_e32 v62, v62
	v_exp_f32_e32 v63, v63
	v_rcp_f32_e32 v60, v66
	s_nop 0
	v_pk_mul_f32 v[52:53], v[52:53], v[60:61]
	v_pk_add_f32 v[62:63], v[62:63], 1.0 op_sel_hi:[1,0]
	v_pk_mul_f32 v[52:53], v[48:49], v[52:53]
	v_pk_mul_f32 v[48:49], v[50:51], v[64:65] op_sel_hi:[1,0]
	v_rcp_f32_e32 v51, v63
	v_rcp_f32_e32 v50, v62
	s_nop 0
	v_pk_mul_f32 v[50:51], v[54:55], v[50:51]
	s_nop 0
	v_pk_mul_f32 v[54:55], v[48:49], v[50:51]
	v_cvt_pk_bf16_f32 v50, v52, v53
	v_mad_i64_i32 v[52:53], s[0:1], v70, s52, v[112:113]
	v_cvt_pk_bf16_f32 v48, v56, v57
	v_cvt_pk_bf16_f32 v49, v58, v59
	v_cvt_pk_bf16_f32 v51, v54, v55
	v_lshl_add_u64 v[52:53], v[52:53], 0, v[114:115]
	global_store_dwordx4 v[52:53], v[48:51], off
	s_nop 0
	v_add_u32_e32 v54, 0x90, v144
	s_nop 0
	v_fmamk_f32 v48, v252, 0x3a800000, v158
	v_mul_f32_e32 v49, 0x4b800000, v48
	v_cmp_gt_f32_e32 vcc, s51, v48
	s_nop 1
	v_cndmask_b32_e32 v48, v48, v49, vcc
	v_rsq_f32_e32 v48, v48
	s_nop 0
	v_mul_f32_e32 v49, 0x45800000, v48
	v_cndmask_b32_e32 v48, v48, v49, vcc
	v_pk_mul_f32 v[44:45], v[44:45], v[48:49] op_sel_hi:[1,0]
	s_nop 0
	v_mul_f32_e32 v49, 0xbfb8aa3b, v44
	v_exp_f32_e32 v50, v49
	v_mul_f32_e32 v49, 0xbfb8aa3b, v45
	v_exp_f32_e32 v51, v49
	s_nop 0
	v_pk_add_f32 v[50:51], v[50:51], 1.0 op_sel_hi:[1,0]
	s_nop 0
	v_pk_mul_f32 v[40:41], v[40:41], v[48:49] op_sel_hi:[1,0]
	v_rcp_f32_e32 v51, v51
	v_pk_mul_f32 v[46:47], v[46:47], v[48:49] op_sel_hi:[1,0]
	v_mul_f32_e32 v52, 0xbfb8aa3b, v46
	v_mul_f32_e32 v53, 0xbfb8aa3b, v47
	v_exp_f32_e32 v52, v52
	v_exp_f32_e32 v53, v53
	v_rcp_f32_e32 v50, v50
	s_nop 0
	v_pk_mul_f32 v[44:45], v[44:45], v[50:51]
	v_pk_add_f32 v[52:53], v[52:53], 1.0 op_sel_hi:[1,0]
	s_nop 0
	v_pk_mul_f32 v[40:41], v[40:41], v[44:45]
	v_pk_mul_f32 v[42:43], v[42:43], v[48:49] op_sel_hi:[1,0]
	v_rcp_f32_e32 v45, v53
	v_pk_mul_f32 v[36:37], v[36:37], v[48:49] op_sel_hi:[1,0]
	v_mul_f32_e32 v49, 0xbfb8aa3b, v36
	v_exp_f32_e32 v50, v49
	v_mul_f32_e32 v49, 0xbfb8aa3b, v37
	v_exp_f32_e32 v51, v49
	v_rcp_f32_e32 v44, v52
	s_nop 0
	v_pk_mul_f32 v[44:45], v[46:47], v[44:45]
	v_pk_add_f32 v[50:51], v[50:51], 1.0 op_sel_hi:[1,0]
	v_pk_mul_f32 v[42:43], v[42:43], v[44:45]
	v_pk_mul_f32 v[32:33], v[32:33], v[48:49] op_sel_hi:[1,0]
	v_rcp_f32_e32 v45, v51
	v_pk_mul_f32 v[38:39], v[38:39], v[48:49] op_sel_hi:[1,0]
	v_mul_f32_e32 v46, 0xbfb8aa3b, v38
	v_mul_f32_e32 v47, 0xbfb8aa3b, v39
	v_exp_f32_e32 v46, v46
	v_exp_f32_e32 v47, v47
	v_rcp_f32_e32 v44, v50
	s_nop 0
	v_pk_mul_f32 v[36:37], v[36:37], v[44:45]
	v_pk_add_f32 v[46:47], v[46:47], 1.0 op_sel_hi:[1,0]
	v_pk_mul_f32 v[36:37], v[32:33], v[36:37]
	v_pk_mul_f32 v[32:33], v[34:35], v[48:49] op_sel_hi:[1,0]
	v_rcp_f32_e32 v35, v47
	v_rcp_f32_e32 v34, v46
	s_nop 0
	v_pk_mul_f32 v[34:35], v[38:39], v[34:35]
	s_nop 0
	v_pk_mul_f32 v[38:39], v[32:33], v[34:35]
	v_cvt_pk_bf16_f32 v34, v36, v37
	v_mad_i64_i32 v[36:37], s[0:1], v54, s52, v[112:113]
	v_cvt_pk_bf16_f32 v32, v40, v41
	v_cvt_pk_bf16_f32 v33, v42, v43
	v_cvt_pk_bf16_f32 v35, v38, v39
	v_lshl_add_u64 v[36:37], v[36:37], 0, v[114:115]
	global_store_dwordx4 v[36:37], v[32:35], off
	s_nop 0
	v_add_u32_e32 v38, 0xa0, v144
	s_nop 0
	v_fmamk_f32 v32, v253, 0x3a800000, v158
	v_mul_f32_e32 v33, 0x4b800000, v32
	v_cmp_gt_f32_e32 vcc, s51, v32
	s_nop 1
	v_cndmask_b32_e32 v32, v32, v33, vcc
	v_rsq_f32_e32 v32, v32
	s_nop 0
	v_mul_f32_e32 v33, 0x45800000, v32
; DI unsigned pk2(float lo, float hi) { f32x2_t v = {lo, hi}; bf16x2_t b = __builtin_convertvector(v, bf16x2_t); return __builtin_bit_cast(unsigned, b); }
; DI float sigmoidf_(float x) { return 1.0f / (1.0f + __expf(-x)); }
;     DI void operator()(AccRef acc, const Unit& u, int wr, int wc, int fr, int fq) const {
;     ...
;             for (int m = 0; m < 4; ++m) {
;                 const int row = row0 + ai * HALF + m * 16; const float rs = rsqrtf(SS1[row] * (1.0f / DM) + EPSN);
;                 float h[8];
; #pragma unroll
;                 for (int n = 0; n < 2; ++n)
; #pragma unroll
;                     for (int e = 0; e < 4; ++e) { const float g = acc[ai][0][m][n][e] * rs, up = acc[ai][1][m][n][e] * rs; h[4 * n + e] = g * sigmoidf_(g) * up; }
;                 u32x4 w; w.x = pk2(h[0], h[1]); w.y = pk2(h[2], h[3]); w.z = pk2(h[4], h[5]); w.w = pk2(h[6], h[7]);
;                 *(u32x4*)(H + (size_t)row * DFF + col0) = w;
	v_cndmask_b32_e32 v32, v32, v33, vcc
	v_pk_mul_f32 v[28:29], v[28:29], v[32:33] op_sel_hi:[1,0]
	s_nop 0
	v_mul_f32_e32 v33, 0xbfb8aa3b, v28
	v_exp_f32_e32 v34, v33
	v_mul_f32_e32 v33, 0xbfb8aa3b, v29
	v_exp_f32_e32 v35, v33
	s_nop 0
	v_pk_add_f32 v[34:35], v[34:35], 1.0 op_sel_hi:[1,0]
	s_nop 0
	v_pk_mul_f32 v[24:25], v[24:25], v[32:33] op_sel_hi:[1,0]
	v_rcp_f32_e32 v35, v35
	v_pk_mul_f32 v[30:31], v[30:31], v[32:33] op_sel_hi:[1,0]
	v_mul_f32_e32 v36, 0xbfb8aa3b, v30
	v_mul_f32_e32 v37, 0xbfb8aa3b, v31
	v_exp_f32_e32 v36, v36
	v_exp_f32_e32 v37, v37
	v_rcp_f32_e32 v34, v34
	s_nop 0
	v_pk_mul_f32 v[28:29], v[28:29], v[34:35]
	v_pk_add_f32 v[36:37], v[36:37], 1.0 op_sel_hi:[1,0]
	s_nop 0
	v_pk_mul_f32 v[24:25], v[24:25], v[28:29]
	v_pk_mul_f32 v[26:27], v[26:27], v[32:33] op_sel_hi:[1,0]
	v_rcp_f32_e32 v29, v37
	v_pk_mul_f32 v[20:21], v[20:21], v[32:33] op_sel_hi:[1,0]
	v_mul_f32_e32 v33, 0xbfb8aa3b, v20
	v_exp_f32_e32 v34, v33
	v_mul_f32_e32 v33, 0xbfb8aa3b, v21
	v_exp_f32_e32 v35, v33
	v_rcp_f32_e32 v28, v36
	s_nop 0
	v_pk_mul_f32 v[28:29], v[30:31], v[28:29]
	v_pk_add_f32 v[34:35], v[34:35], 1.0 op_sel_hi:[1,0]
	v_pk_mul_f32 v[26:27], v[26:27], v[28:29]
	v_pk_mul_f32 v[16:17], v[16:17], v[32:33] op_sel_hi:[1,0]
	v_rcp_f32_e32 v29, v35
	v_pk_mul_f32 v[22:23], v[22:23], v[32:33] op_sel_hi:[1,0]
	v_mul_f32_e32 v30, 0xbfb8aa3b, v22
	v_mul_f32_e32 v31, 0xbfb8aa3b, v23
	v_exp_f32_e32 v30, v30
	v_exp_f32_e32 v31, v31
	v_rcp_f32_e32 v28, v34
	s_nop 0
	v_pk_mul_f32 v[20:21], v[20:21], v[28:29]
	v_pk_add_f32 v[30:31], v[30:31], 1.0 op_sel_hi:[1,0]
	v_pk_mul_f32 v[20:21], v[16:17], v[20:21]
	v_pk_mul_f32 v[16:17], v[18:19], v[32:33] op_sel_hi:[1,0]
	v_rcp_f32_e32 v19, v31
	v_rcp_f32_e32 v18, v30
	s_nop 0
	v_pk_mul_f32 v[18:19], v[22:23], v[18:19]
	s_nop 0
	v_pk_mul_f32 v[22:23], v[16:17], v[18:19]
	v_cvt_pk_bf16_f32 v18, v20, v21
	v_mad_i64_i32 v[20:21], s[0:1], v38, s52, v[112:113]
	v_cvt_pk_bf16_f32 v16, v24, v25
	v_cvt_pk_bf16_f32 v17, v26, v27
	v_cvt_pk_bf16_f32 v19, v22, v23
	v_lshl_add_u64 v[20:21], v[20:21], 0, v[114:115]
	global_store_dwordx4 v[20:21], v[16:19], off
	s_nop 0
	v_add_u32_e32 v22, 0xb0, v144
	s_nop 0
	v_fmamk_f32 v16, v254, 0x3a800000, v158
	v_mul_f32_e32 v17, 0x4b800000, v16
	v_cmp_gt_f32_e32 vcc, s51, v16
	s_nop 1
	v_cndmask_b32_e32 v16, v16, v17, vcc
	v_rsq_f32_e32 v16, v16
	s_nop 0
	v_mul_f32_e32 v17, 0x45800000, v16
	v_cndmask_b32_e32 v16, v16, v17, vcc
	v_pk_mul_f32 v[12:13], v[12:13], v[16:17] op_sel_hi:[1,0]
	s_nop 0
	v_mul_f32_e32 v17, 0xbfb8aa3b, v12
	v_exp_f32_e32 v18, v17
	v_mul_f32_e32 v17, 0xbfb8aa3b, v13
	v_exp_f32_e32 v19, v17
	s_nop 0
	v_pk_add_f32 v[18:19], v[18:19], 1.0 op_sel_hi:[1,0]
	s_nop 0
	v_pk_mul_f32 v[8:9], v[8:9], v[16:17] op_sel_hi:[1,0]
	v_rcp_f32_e32 v19, v19
	v_pk_mul_f32 v[14:15], v[14:15], v[16:17] op_sel_hi:[1,0]
	v_mul_f32_e32 v20, 0xbfb8aa3b, v14
	v_mul_f32_e32 v21, 0xbfb8aa3b, v15
	v_exp_f32_e32 v20, v20
	v_exp_f32_e32 v21, v21
	v_rcp_f32_e32 v18, v18
	s_nop 0
	v_pk_mul_f32 v[12:13], v[12:13], v[18:19]
	v_pk_add_f32 v[20:21], v[20:21], 1.0 op_sel_hi:[1,0]
	s_nop 0
	v_pk_mul_f32 v[8:9], v[8:9], v[12:13]
	v_pk_mul_f32 v[10:11], v[10:11], v[16:17] op_sel_hi:[1,0]
	v_rcp_f32_e32 v13, v21
	v_pk_mul_f32 v[4:5], v[4:5], v[16:17] op_sel_hi:[1,0]
	v_mul_f32_e32 v17, 0xbfb8aa3b, v4
	v_exp_f32_e32 v18, v17
	v_mul_f32_e32 v17, 0xbfb8aa3b, v5
	v_exp_f32_e32 v19, v17
	v_rcp_f32_e32 v12, v20
	s_nop 0
	v_pk_mul_f32 v[12:13], v[14:15], v[12:13]
	v_pk_add_f32 v[18:19], v[18:19], 1.0 op_sel_hi:[1,0]
	v_pk_mul_f32 v[10:11], v[10:11], v[12:13]
	v_pk_mul_f32 v[0:1], v[0:1], v[16:17] op_sel_hi:[1,0]
	v_rcp_f32_e32 v13, v19
	v_pk_mul_f32 v[6:7], v[6:7], v[16:17] op_sel_hi:[1,0]
	v_mul_f32_e32 v14, 0xbfb8aa3b, v6
	v_mul_f32_e32 v15, 0xbfb8aa3b, v7
	v_exp_f32_e32 v14, v14
	v_exp_f32_e32 v15, v15
	v_rcp_f32_e32 v12, v18
	s_nop 0
	v_pk_mul_f32 v[4:5], v[4:5], v[12:13]
	v_pk_add_f32 v[14:15], v[14:15], 1.0 op_sel_hi:[1,0]
	v_pk_mul_f32 v[4:5], v[0:1], v[4:5]
	v_pk_mul_f32 v[0:1], v[2:3], v[16:17] op_sel_hi:[1,0]
	v_rcp_f32_e32 v3, v15
	v_rcp_f32_e32 v2, v14
	s_nop 0
	v_pk_mul_f32 v[2:3], v[6:7], v[2:3]
	s_andn2_b64 vcc, exec, s[2:3]
	v_pk_mul_f32 v[6:7], v[0:1], v[2:3]
	v_cvt_pk_bf16_f32 v2, v4, v5
	v_mad_i64_i32 v[4:5], s[0:1], v22, s52, v[112:113]
	v_cvt_pk_bf16_f32 v0, v8, v9
	v_cvt_pk_bf16_f32 v1, v10, v11
	v_cvt_pk_bf16_f32 v3, v6, v7
	v_lshl_add_u64 v[4:5], v[4:5], 0, v[114:115]
	s_mov_b64 s[0:1], -1
	global_store_dwordx4 v[4:5], v[0:3], off
	s_cbranch_vccnz .LBB0_1662
	s_andn2_b64 vcc, exec, s[16:17]
	s_cbranch_vccnz .LBB0_1661
	s_barrier
	s_branch .LBB0_1661

; __global__ void __launch_bounds__(512, 2) hybrid_fwd(Args args) {
	.amdhsa_kernel _Z10hybrid_fwd4Args
		.amdhsa_group_segment_fixed_size 0
		.amdhsa_private_segment_fixed_size 0
		.amdhsa_kernarg_size 472
		.amdhsa_user_sgpr_count 2
		.amdhsa_user_sgpr_dispatch_ptr 0
		.amdhsa_user_sgpr_queue_ptr 0
		.amdhsa_user_sgpr_kernarg_segment_ptr 1
		.amdhsa_user_sgpr_dispatch_id 0
		.amdhsa_user_sgpr_kernarg_preload_length 0
		.amdhsa_user_sgpr_kernarg_preload_offset 0
		.amdhsa_user_sgpr_private_segment_size 0
		.amdhsa_uses_dynamic_stack 0
		.amdhsa_enable_private_segment 0
		.amdhsa_system_sgpr_workgroup_id_x 1
		.amdhsa_system_sgpr_workgroup_id_y 0
		.amdhsa_system_sgpr_workgroup_id_z 0
		.amdhsa_system_sgpr_workgroup_info 0
		.amdhsa_system_vgpr_workitem_id 2
		.amdhsa_next_free_vgpr 256
		.amdhsa_next_free_sgpr 102
		.amdhsa_accum_offset 256
		.amdhsa_reserve_vcc 1
		.amdhsa_float_round_mode_32 0
		.amdhsa_float_round_mode_16_64 0
		.amdhsa_float_denorm_mode_32 3
		.amdhsa_float_denorm_mode_16_64 3
		.amdhsa_dx10_clamp 1
		.amdhsa_ieee_mode 1
		.amdhsa_fp16_overflow 0
		.amdhsa_tg_split 0
		.amdhsa_exception_fp_ieee_invalid_op 0
		.amdhsa_exception_fp_denorm_src 0
		.amdhsa_exception_fp_ieee_div_zero 0
		.amdhsa_exception_fp_ieee_overflow 0
		.amdhsa_exception_fp_ieee_underflow 0
		.amdhsa_exception_fp_ieee_inexact 0
		.amdhsa_exception_int_div_zero 0
	.end_amdhsa_kernel

; __global__ void __launch_bounds__(512, 2) hybrid_fwd(Args args) {
amdhsa.kernels:
  - .agpr_count:     0
    .args:
      - .offset:         0
        .size:           216
        .value_kind:     by_value
      - .offset:         216
        .size:           4
        .value_kind:     hidden_block_count_x
      - .offset:         220
        .size:           4
        .value_kind:     hidden_block_count_y
      - .offset:         224
        .size:           4
        .value_kind:     hidden_block_count_z
      - .offset:         228
        .size:           2
        .value_kind:     hidden_group_size_x
      - .offset:         230
        .size:           2
        .value_kind:     hidden_group_size_y
      - .offset:         232
        .size:           2
        .value_kind:     hidden_group_size_z
      - .offset:         234
        .size:           2
        .value_kind:     hidden_remainder_x
      - .offset:         236
        .size:           2
        .value_kind:     hidden_remainder_y
      - .offset:         238
        .size:           2
        .value_kind:     hidden_remainder_z
      - .offset:         256
        .size:           8
        .value_kind:     hidden_global_offset_x
      - .offset:         264
        .size:           8
        .value_kind:     hidden_global_offset_y
      - .offset:         272
        .size:           8
        .value_kind:     hidden_global_offset_z
      - .offset:         280
        .size:           2
        .value_kind:     hidden_grid_dims
      - .offset:         304
        .size:           8
        .value_kind:     hidden_multigrid_sync_arg
      - .offset:         336
        .size:           4
        .value_kind:     hidden_dynamic_lds_size
    .group_segment_fixed_size: 0
    .kernarg_segment_align: 8
    .kernarg_segment_size: 472
    .language:       OpenCL C
    .language_version:
      - 2
      - 0
    .max_flat_workgroup_size: 512
    .name:           _Z10hybrid_fwd4Args
    .private_segment_fixed_size: 0
    .sgpr_count:     108
    .sgpr_spill_count: 44
    .symbol:         _Z10hybrid_fwd4Args.kd
    .uniform_work_group_size: 1
    .uses_dynamic_stack: false
    .vgpr_count:     256
    .vgpr_spill_count: 0
    .wavefront_size: 64
